# GEMM k-loops: LDS fragment reads hoisted one sub-step ahead onto spare register quads with recomputed lgkmcnt waits
# speedup vs baseline: 1.0071x; 1.0009x over previous
.LBB0_198:
	s_setprio 1
	ds_read_b128 v[140:143], v103
	ds_read_b128 v[144:147], v104 offset:36864
	ds_read_b128 v[148:151], v103 offset:32
	ds_read_b128 v[192:195], v104 offset:36896
	ds_read_b128 v[196:199], v104 offset:41472
	ds_read_b128 v[200:203], v103 offset:4608
	s_waitcnt lgkmcnt(4)
	v_mfma_f32_32x32x16_bf16 v[48:63], v[140:143], v[144:147], v[48:63]
	ds_read_b128 v[204:207], v104 offset:41504
	global_load_dwordx4 v[108:111], v168, s[98:99] offset:3840
	global_load_dwordx4 v[112:115], v170, s[98:99] offset:3840
	s_waitcnt vmcnt(9)
	ds_write_b128 v105, v[68:71] offset:18432
	s_waitcnt lgkmcnt(3)
	v_mfma_f32_32x32x16_bf16 v[32:47], v[140:143], v[196:199], v[32:47]
	ds_read_b128 v[208:211], v103 offset:4640
	global_load_dwordx4 v[116:119], v172, s[98:99] offset:3840
	global_load_dwordx4 v[120:123], v174, s[98:99] offset:3840
	s_waitcnt lgkmcnt(3)
	v_mfma_f32_32x32x16_bf16 v[16:31], v[200:203], v[144:147], v[16:31]
	global_load_dwordx4 v[124:127], v176, s[98:99] offset:3840
	global_load_dwordx4 v[128:131], v178, s[98:99] offset:3840
	s_waitcnt vmcnt(11)
	ds_write_b128 v105, v[84:87] offset:23040
	v_mfma_f32_32x32x16_bf16 v[0:15], v[200:203], v[196:199], v[0:15]
	ds_read_b128 v[212:215], v103 offset:64
	ds_read_b128 v[216:219], v104 offset:36928
	global_load_dwordx4 v[132:135], v180, s[98:99] offset:3840
	global_load_dwordx4 v[136:139], v182, s[98:99] offset:3840
	v_mfma_f32_32x32x16_bf16 v[48:63], v[148:151], v[192:195], v[48:63]
	ds_read_b128 v[220:223], v104 offset:41536
	s_waitcnt vmcnt(12)
	ds_write_b128 v105, v[88:91] offset:27648
	s_waitcnt lgkmcnt(7)
	v_mfma_f32_32x32x16_bf16 v[32:47], v[148:151], v[204:207], v[32:47]
	ds_read_b128 v[224:227], v103 offset:4672
	s_waitcnt lgkmcnt(6)
	v_mfma_f32_32x32x16_bf16 v[16:31], v[208:211], v[192:195], v[16:31]
	s_waitcnt vmcnt(11)
	ds_write_b128 v105, v[92:95] offset:32256
	v_mfma_f32_32x32x16_bf16 v[0:15], v[208:211], v[204:207], v[0:15]
	ds_read_b128 v[228:231], v103 offset:96
	ds_read_b128 v[140:143], v104 offset:36960
	s_waitcnt lgkmcnt(6)
	v_mfma_f32_32x32x16_bf16 v[48:63], v[212:215], v[216:219], v[48:63]
	ds_read_b128 v[144:147], v104 offset:41568
	ds_write_b128 v105, v[64:67] offset:55296
	s_waitcnt lgkmcnt(7)
	v_mfma_f32_32x32x16_bf16 v[32:47], v[212:215], v[220:223], v[32:47]
	ds_read_b128 v[196:199], v103 offset:4704
	s_waitcnt lgkmcnt(6)
	v_mfma_f32_32x32x16_bf16 v[16:31], v[224:227], v[216:219], v[16:31]
	s_waitcnt vmcnt(10)
	ds_write_b128 v105, v[72:75] offset:59904
	v_mfma_f32_32x32x16_bf16 v[0:15], v[224:227], v[220:223], v[0:15]
	s_waitcnt lgkmcnt(4)
	v_mfma_f32_32x32x16_bf16 v[48:63], v[228:231], v[140:143], v[48:63]
	s_waitcnt vmcnt(9)
	ds_write_b128 v105, v[76:79] offset:64512
	s_waitcnt lgkmcnt(4)
	v_mfma_f32_32x32x16_bf16 v[32:47], v[228:231], v[144:147], v[32:47]
	s_waitcnt lgkmcnt(2)
	v_mfma_f32_32x32x16_bf16 v[16:31], v[196:199], v[140:143], v[16:31]
	s_waitcnt vmcnt(8)
	ds_write_b128 v106, v[80:83] offset:13824
	v_mfma_f32_32x32x16_bf16 v[0:15], v[196:199], v[144:147], v[0:15]
	s_setprio 0
	s_waitcnt lgkmcnt(0)
	s_barrier
	s_setprio 1
	ds_read_b128 v[140:143], v103 offset:18432
	ds_read_b128 v[144:147], v104 offset:55296
	ds_read_b128 v[148:151], v103 offset:18464
	ds_read_b128 v[192:195], v104 offset:55328
	ds_read_b128 v[196:199], v104 offset:59904
	ds_read_b128 v[200:203], v103 offset:23040
	s_waitcnt lgkmcnt(4)
	v_mfma_f32_32x32x16_bf16 v[48:63], v[140:143], v[144:147], v[48:63]
	ds_read_b128 v[204:207], v104 offset:59936
	global_load_dwordx4 v[68:71], v168, s[98:99] offset:3968
	global_load_dwordx4 v[84:87], v170, s[98:99] offset:3968
	s_waitcnt vmcnt(9)
	ds_write_b128 v105, v[108:111]
	s_waitcnt lgkmcnt(3)
	v_mfma_f32_32x32x16_bf16 v[32:47], v[140:143], v[196:199], v[32:47]
	ds_read_b128 v[208:211], v103 offset:23072
	global_load_dwordx4 v[88:91], v172, s[98:99] offset:3968
	global_load_dwordx4 v[92:95], v174, s[98:99] offset:3968
	s_waitcnt lgkmcnt(3)
	v_mfma_f32_32x32x16_bf16 v[16:31], v[200:203], v[144:147], v[16:31]
	global_load_dwordx4 v[64:67], v176, s[98:99] offset:3968
	global_load_dwordx4 v[72:75], v178, s[98:99] offset:3968
	s_waitcnt vmcnt(12)
	ds_write_b128 v105, v[112:115] offset:4608
	v_mfma_f32_32x32x16_bf16 v[0:15], v[200:203], v[196:199], v[0:15]
	ds_read_b128 v[212:215], v103 offset:18496
	ds_read_b128 v[216:219], v104 offset:55360
	global_load_dwordx4 v[76:79], v180, s[98:99] offset:3968
	global_load_dwordx4 v[80:83], v182, s[98:99] offset:3968
	v_mfma_f32_32x32x16_bf16 v[48:63], v[148:151], v[192:195], v[48:63]
	ds_read_b128 v[220:223], v104 offset:59968
	s_add_u32 s98, s98, 0x100
	s_addc_u32 s99, s99, 0
	s_add_i32 s6, s6, 2
	s_cmp_lt_u32 s6, 11
	s_waitcnt vmcnt(13)
	ds_write_b128 v105, v[116:119] offset:9216
	s_waitcnt lgkmcnt(7)
	v_mfma_f32_32x32x16_bf16 v[32:47], v[148:151], v[204:207], v[32:47]
	ds_read_b128 v[224:227], v103 offset:23104
	s_waitcnt lgkmcnt(6)
	v_mfma_f32_32x32x16_bf16 v[16:31], v[208:211], v[192:195], v[16:31]
	s_waitcnt vmcnt(12)
	ds_write_b128 v105, v[120:123] offset:13824
	v_mfma_f32_32x32x16_bf16 v[0:15], v[208:211], v[204:207], v[0:15]
	ds_read_b128 v[228:231], v103 offset:18528
	ds_read_b128 v[140:143], v104 offset:55392
	s_waitcnt lgkmcnt(6)
	v_mfma_f32_32x32x16_bf16 v[48:63], v[212:215], v[216:219], v[48:63]
	ds_read_b128 v[144:147], v104 offset:60000
	s_waitcnt vmcnt(11)
	ds_write_b128 v105, v[124:127] offset:36864
	s_waitcnt lgkmcnt(7)
	v_mfma_f32_32x32x16_bf16 v[32:47], v[212:215], v[220:223], v[32:47]
	ds_read_b128 v[196:199], v103 offset:23136
	s_waitcnt lgkmcnt(6)
	v_mfma_f32_32x32x16_bf16 v[16:31], v[224:227], v[216:219], v[16:31]
	s_waitcnt vmcnt(10)
	ds_write_b128 v105, v[128:131] offset:41472
	v_mfma_f32_32x32x16_bf16 v[0:15], v[224:227], v[220:223], v[0:15]
	s_waitcnt lgkmcnt(4)
	v_mfma_f32_32x32x16_bf16 v[48:63], v[228:231], v[140:143], v[48:63]
	s_waitcnt vmcnt(9)
	ds_write_b128 v105, v[132:135] offset:46080
	s_waitcnt lgkmcnt(4)
	v_mfma_f32_32x32x16_bf16 v[32:47], v[228:231], v[144:147], v[32:47]
	s_waitcnt lgkmcnt(2)
	v_mfma_f32_32x32x16_bf16 v[16:31], v[196:199], v[140:143], v[16:31]
	s_waitcnt vmcnt(8)
	ds_write_b128 v105, v[136:139] offset:50688
	v_mfma_f32_32x32x16_bf16 v[0:15], v[196:199], v[144:147], v[0:15]
	s_setprio 0
	s_waitcnt lgkmcnt(0)
	s_barrier
	s_cbranch_scc1 .LBB0_198
	s_setprio 1
	ds_read_b128 v[98:101], v103
	ds_read_b128 v[108:111], v104 offset:36864
	ds_read_b128 v[112:115], v103 offset:32
	ds_read_b128 v[192:195], v104 offset:36896
	ds_read_b128 v[196:199], v104 offset:41472
	ds_read_b128 v[200:203], v103 offset:4608
	s_waitcnt lgkmcnt(4)
	v_mfma_f32_32x32x16_bf16 v[48:63], v[98:101], v[108:111], v[48:63]
	ds_read_b128 v[204:207], v104 offset:41504
	s_waitcnt vmcnt(7)
	ds_write_b128 v105, v[68:71] offset:18432
	s_waitcnt lgkmcnt(3)
	v_mfma_f32_32x32x16_bf16 v[32:47], v[98:101], v[196:199], v[32:47]
	ds_read_b128 v[208:211], v103 offset:4640
	s_waitcnt lgkmcnt(3)
	v_mfma_f32_32x32x16_bf16 v[16:31], v[200:203], v[108:111], v[16:31]
	s_waitcnt vmcnt(6)
	ds_write_b128 v105, v[84:87] offset:23040
	v_mfma_f32_32x32x16_bf16 v[0:15], v[200:203], v[196:199], v[0:15]
	ds_read_b128 v[212:215], v103 offset:64
	ds_read_b128 v[216:219], v104 offset:36928
	v_mfma_f32_32x32x16_bf16 v[48:63], v[112:115], v[192:195], v[48:63]
	ds_read_b128 v[220:223], v104 offset:41536
	s_waitcnt vmcnt(5)
	ds_write_b128 v105, v[88:91] offset:27648
	s_waitcnt lgkmcnt(7)
	v_mfma_f32_32x32x16_bf16 v[32:47], v[112:115], v[204:207], v[32:47]
	ds_read_b128 v[224:227], v103 offset:4672
	s_waitcnt lgkmcnt(6)
	v_mfma_f32_32x32x16_bf16 v[16:31], v[208:211], v[192:195], v[16:31]
	s_waitcnt vmcnt(4)
	ds_write_b128 v105, v[92:95] offset:32256
	v_mfma_f32_32x32x16_bf16 v[0:15], v[208:211], v[204:207], v[0:15]
	ds_read_b128 v[228:231], v103 offset:96
	ds_read_b128 v[98:101], v104 offset:36960
	s_waitcnt lgkmcnt(6)
	v_mfma_f32_32x32x16_bf16 v[48:63], v[212:215], v[216:219], v[48:63]
	ds_read_b128 v[108:111], v104 offset:41568
	s_waitcnt vmcnt(3)
	ds_write_b128 v105, v[64:67] offset:55296
	s_waitcnt lgkmcnt(7)
	v_mfma_f32_32x32x16_bf16 v[32:47], v[212:215], v[220:223], v[32:47]
	ds_read_b128 v[196:199], v103 offset:4704
	s_waitcnt lgkmcnt(6)
	v_mfma_f32_32x32x16_bf16 v[16:31], v[224:227], v[216:219], v[16:31]
	s_waitcnt vmcnt(2)
	ds_write_b128 v105, v[72:75] offset:59904
	v_mfma_f32_32x32x16_bf16 v[0:15], v[224:227], v[220:223], v[0:15]
	s_waitcnt lgkmcnt(4)
	v_mfma_f32_32x32x16_bf16 v[48:63], v[228:231], v[98:101], v[48:63]
	s_waitcnt vmcnt(1)
	ds_write_b128 v105, v[76:79] offset:64512
	s_waitcnt lgkmcnt(4)
	v_mfma_f32_32x32x16_bf16 v[32:47], v[228:231], v[108:111], v[32:47]
	s_waitcnt lgkmcnt(2)
	v_mfma_f32_32x32x16_bf16 v[16:31], v[196:199], v[98:101], v[16:31]
	s_waitcnt vmcnt(0)
	ds_write_b128 v106, v[80:83] offset:13824
	v_mfma_f32_32x32x16_bf16 v[0:15], v[196:199], v[108:111], v[0:15]
	s_setprio 0
	s_waitcnt lgkmcnt(0)
	s_barrier
	s_setprio 1
	ds_read_b128 v[64:67], v103 offset:18432
	ds_read_b128 v[68:71], v104 offset:55296
	ds_read_b128 v[72:75], v103 offset:18464
	ds_read_b128 v[192:195], v104 offset:55328
	ds_read_b128 v[196:199], v104 offset:59904
	ds_read_b128 v[200:203], v103 offset:23040
	s_waitcnt lgkmcnt(4)
	v_mfma_f32_32x32x16_bf16 v[48:63], v[64:67], v[68:71], v[48:63]
	ds_read_b128 v[204:207], v104 offset:59936
	s_waitcnt lgkmcnt(2)
	v_mfma_f32_32x32x16_bf16 v[32:47], v[64:67], v[196:199], v[32:47]
	ds_read_b128 v[208:211], v103 offset:23072
	s_waitcnt lgkmcnt(2)
	v_mfma_f32_32x32x16_bf16 v[16:31], v[200:203], v[68:71], v[16:31]
	v_mfma_f32_32x32x16_bf16 v[0:15], v[200:203], v[196:199], v[0:15]
	ds_read_b128 v[212:215], v103 offset:18496
	ds_read_b128 v[216:219], v104 offset:55360
	v_mfma_f32_32x32x16_bf16 v[48:63], v[72:75], v[192:195], v[48:63]
	ds_read_b128 v[220:223], v104 offset:59968
	s_waitcnt lgkmcnt(4)
	v_mfma_f32_32x32x16_bf16 v[32:47], v[72:75], v[204:207], v[32:47]
	ds_read_b128 v[224:227], v103 offset:23104
	s_waitcnt lgkmcnt(4)
	v_mfma_f32_32x32x16_bf16 v[16:31], v[208:211], v[192:195], v[16:31]
	v_mfma_f32_32x32x16_bf16 v[0:15], v[208:211], v[204:207], v[0:15]
	ds_read_b128 v[228:231], v103 offset:18528
	ds_read_b128 v[64:67], v104 offset:55392
	s_waitcnt lgkmcnt(4)
	v_mfma_f32_32x32x16_bf16 v[48:63], v[212:215], v[216:219], v[48:63]
	ds_read_b128 v[68:71], v104 offset:60000
	s_waitcnt lgkmcnt(4)
	v_mfma_f32_32x32x16_bf16 v[32:47], v[212:215], v[220:223], v[32:47]
	ds_read_b128 v[196:199], v103 offset:23136
	s_waitcnt lgkmcnt(4)
	v_mfma_f32_32x32x16_bf16 v[16:31], v[224:227], v[216:219], v[16:31]
	v_mfma_f32_32x32x16_bf16 v[0:15], v[224:227], v[220:223], v[0:15]
	s_waitcnt lgkmcnt(2)
	v_mfma_f32_32x32x16_bf16 v[48:63], v[228:231], v[64:67], v[48:63]
	s_waitcnt lgkmcnt(1)
	v_mfma_f32_32x32x16_bf16 v[32:47], v[228:231], v[68:71], v[32:47]
	s_waitcnt lgkmcnt(0)
	v_mfma_f32_32x32x16_bf16 v[16:31], v[196:199], v[64:67], v[16:31]
	v_mfma_f32_32x32x16_bf16 v[0:15], v[196:199], v[68:71], v[0:15]
	s_setprio 0
	s_cmpk_gt_u32 s24, 0xfff
	s_cselect_b64 s[12:13], -1, 0
	s_cmpk_lt_u32 s24, 0x1000
	s_cselect_b64 s[48:49], -1, 0
	s_ashr_i32 s76, s2, 2
	s_cmp_lt_i32 s76, 7
	s_barrier
	s_cbranch_scc1 .LBB0_201
	s_cmp_lg_u32 s76, 7
	s_cselect_b64 s[6:7], -1, 0
	s_cbranch_execz .LBB0_202
	s_branch .LBB0_203

.LBB0_1745:
	s_setprio 1
	ds_read_b128 v[148:151], v144
	ds_read_b128 v[152:155], v145 offset:36864
	ds_read_b128 v[156:159], v145 offset:41472
	ds_read_b128 v[192:195], v144 offset:4608
	ds_read_b128 v[196:199], v144 offset:32
	ds_read_b128 v[200:203], v145 offset:36896
	s_waitcnt lgkmcnt(4)
	v_mfma_f32_32x32x16_bf16 v[48:63], v[148:151], v[152:155], v[48:63]
	ds_read_b128 v[204:207], v145 offset:41504
	global_load_dwordx4 v[96:99], v160, s[98:99] offset:256
	global_load_dwordx4 v[100:103], v164, s[98:99] offset:256
	s_waitcnt vmcnt(9)
	ds_write_b128 v146, v[64:67] offset:18432
	s_waitcnt lgkmcnt(5)
	v_mfma_f32_32x32x16_bf16 v[32:47], v[148:151], v[156:159], v[32:47]
	ds_read_b128 v[208:211], v144 offset:4640
	global_load_dwordx4 v[104:107], v166, s[98:99] offset:256
	global_load_dwordx4 v[108:111], v168, s[98:99] offset:256
	s_waitcnt lgkmcnt(5)
	v_mfma_f32_32x32x16_bf16 v[16:31], v[192:195], v[152:155], v[16:31]
	global_load_dwordx4 v[112:115], v162, s[98:99]
	global_load_dwordx4 v[116:119], v130, s[98:99]
	s_waitcnt vmcnt(12)
	ds_write_b128 v146, v[68:71] offset:23040
	v_mfma_f32_32x32x16_bf16 v[0:15], v[192:195], v[156:159], v[0:15]
	ds_read_b128 v[212:215], v144 offset:64
	ds_read_b128 v[216:219], v145 offset:36928
	global_load_dwordx4 v[120:123], v170, s[98:99]
	global_load_dwordx4 v[124:127], v172, s[98:99] offset:-128
	s_waitcnt lgkmcnt(6)
	v_mfma_f32_32x32x16_bf16 v[48:63], v[196:199], v[200:203], v[48:63]
	ds_read_b128 v[220:223], v145 offset:41536
	s_waitcnt vmcnt(13)
	ds_write_b128 v146, v[72:75] offset:27648
	s_waitcnt lgkmcnt(7)
	v_mfma_f32_32x32x16_bf16 v[32:47], v[196:199], v[204:207], v[32:47]
	ds_read_b128 v[224:227], v144 offset:4672
	s_waitcnt lgkmcnt(6)
	v_mfma_f32_32x32x16_bf16 v[16:31], v[208:211], v[200:203], v[16:31]
	s_waitcnt vmcnt(12)
	ds_write_b128 v146, v[76:79] offset:32256
	v_mfma_f32_32x32x16_bf16 v[0:15], v[208:211], v[204:207], v[0:15]
	ds_read_b128 v[228:231], v144 offset:96
	ds_read_b128 v[148:151], v145 offset:36960
	s_waitcnt lgkmcnt(6)
	v_mfma_f32_32x32x16_bf16 v[48:63], v[212:215], v[216:219], v[48:63]
	ds_read_b128 v[152:155], v145 offset:41568
	s_waitcnt vmcnt(11)
	ds_write_b128 v146, v[80:83] offset:55296
	s_waitcnt lgkmcnt(7)
	v_mfma_f32_32x32x16_bf16 v[32:47], v[212:215], v[220:223], v[32:47]
	ds_read_b128 v[156:159], v144 offset:4704
	s_waitcnt lgkmcnt(6)
	v_mfma_f32_32x32x16_bf16 v[16:31], v[224:227], v[216:219], v[16:31]
	s_waitcnt vmcnt(10)
	ds_write_b128 v146, v[84:87] offset:59904
	v_mfma_f32_32x32x16_bf16 v[0:15], v[224:227], v[220:223], v[0:15]
	s_waitcnt lgkmcnt(4)
	v_mfma_f32_32x32x16_bf16 v[48:63], v[228:231], v[148:151], v[48:63]
	s_waitcnt vmcnt(9)
	ds_write_b128 v146, v[88:91] offset:64512
	s_waitcnt lgkmcnt(4)
	v_mfma_f32_32x32x16_bf16 v[32:47], v[228:231], v[152:155], v[32:47]
	s_waitcnt lgkmcnt(2)
	v_mfma_f32_32x32x16_bf16 v[16:31], v[156:159], v[148:151], v[16:31]
	s_waitcnt vmcnt(8)
	ds_write_b128 v147, v[92:95] offset:13824
	v_mfma_f32_32x32x16_bf16 v[0:15], v[156:159], v[152:155], v[0:15]
	s_setprio 0
	s_waitcnt lgkmcnt(0)
	s_barrier
	s_setprio 1
	ds_read_b128 v[148:151], v144 offset:18432
	ds_read_b128 v[152:155], v145 offset:55296
	ds_read_b128 v[156:159], v145 offset:59904
	ds_read_b128 v[192:195], v144 offset:23040
	ds_read_b128 v[196:199], v144 offset:18464
	ds_read_b128 v[200:203], v145 offset:55328
	s_waitcnt lgkmcnt(4)
	v_mfma_f32_32x32x16_bf16 v[48:63], v[148:151], v[152:155], v[48:63]
	ds_read_b128 v[204:207], v145 offset:59936
	global_load_dwordx4 v[64:67], v160, s[98:99] offset:384
	global_load_dwordx4 v[68:71], v164, s[98:99] offset:384
	s_waitcnt vmcnt(9)
	ds_write_b128 v146, v[96:99]
	s_waitcnt lgkmcnt(5)
	v_mfma_f32_32x32x16_bf16 v[32:47], v[148:151], v[156:159], v[32:47]
	ds_read_b128 v[208:211], v144 offset:23072
	global_load_dwordx4 v[72:75], v166, s[98:99] offset:384
	global_load_dwordx4 v[76:79], v168, s[98:99] offset:384
	s_waitcnt lgkmcnt(5)
	v_mfma_f32_32x32x16_bf16 v[16:31], v[192:195], v[152:155], v[16:31]
	global_load_dwordx4 v[80:83], v162, s[98:99] offset:128
	global_load_dwordx4 v[84:87], v131, s[98:99]
	s_waitcnt vmcnt(12)
	ds_write_b128 v146, v[100:103] offset:4608
	v_mfma_f32_32x32x16_bf16 v[0:15], v[192:195], v[156:159], v[0:15]
	ds_read_b128 v[212:215], v144 offset:18496
	ds_read_b128 v[216:219], v145 offset:55360
	global_load_dwordx4 v[88:91], v170, s[98:99] offset:128
	global_load_dwordx4 v[92:95], v172, s[98:99]
	s_waitcnt lgkmcnt(6)
	v_mfma_f32_32x32x16_bf16 v[48:63], v[196:199], v[200:203], v[48:63]
	ds_read_b128 v[220:223], v145 offset:59968
	s_add_u32 s98, s98, 0x100
	s_addc_u32 s99, s99, 0
	s_add_i32 s0, s0, 2
	s_cmp_lt_u32 s0, 3
	s_waitcnt vmcnt(13)
	ds_write_b128 v146, v[104:107] offset:9216
	s_waitcnt lgkmcnt(7)
	v_mfma_f32_32x32x16_bf16 v[32:47], v[196:199], v[204:207], v[32:47]
	ds_read_b128 v[224:227], v144 offset:23104
	s_waitcnt lgkmcnt(6)
	v_mfma_f32_32x32x16_bf16 v[16:31], v[208:211], v[200:203], v[16:31]
	s_waitcnt vmcnt(12)
	ds_write_b128 v146, v[108:111] offset:13824
	v_mfma_f32_32x32x16_bf16 v[0:15], v[208:211], v[204:207], v[0:15]
	ds_read_b128 v[228:231], v144 offset:18528
	ds_read_b128 v[148:151], v145 offset:55392
	s_waitcnt lgkmcnt(6)
	v_mfma_f32_32x32x16_bf16 v[48:63], v[212:215], v[216:219], v[48:63]
	ds_read_b128 v[152:155], v145 offset:60000
	s_waitcnt vmcnt(11)
	ds_write_b128 v146, v[112:115] offset:36864
	s_waitcnt lgkmcnt(7)
	v_mfma_f32_32x32x16_bf16 v[32:47], v[212:215], v[220:223], v[32:47]
	ds_read_b128 v[156:159], v144 offset:23136
	s_waitcnt lgkmcnt(6)
	v_mfma_f32_32x32x16_bf16 v[16:31], v[224:227], v[216:219], v[16:31]
	s_waitcnt vmcnt(10)
	ds_write_b128 v146, v[116:119] offset:41472
	v_mfma_f32_32x32x16_bf16 v[0:15], v[224:227], v[220:223], v[0:15]
	s_waitcnt lgkmcnt(4)
	v_mfma_f32_32x32x16_bf16 v[48:63], v[228:231], v[148:151], v[48:63]
	s_waitcnt vmcnt(9)
	ds_write_b128 v146, v[120:123] offset:46080
	s_waitcnt lgkmcnt(4)
	v_mfma_f32_32x32x16_bf16 v[32:47], v[228:231], v[152:155], v[32:47]
	s_waitcnt lgkmcnt(2)
	v_mfma_f32_32x32x16_bf16 v[16:31], v[156:159], v[148:151], v[16:31]
	s_waitcnt vmcnt(8)
	ds_write_b128 v146, v[124:127] offset:50688
	v_mfma_f32_32x32x16_bf16 v[0:15], v[156:159], v[152:155], v[0:15]
	s_setprio 0
	s_waitcnt lgkmcnt(0)
	s_barrier
	s_cbranch_scc1 .LBB0_1745
	s_setprio 1
	ds_read_b128 v[96:99], v144
	ds_read_b128 v[100:103], v145 offset:36864
	ds_read_b128 v[104:107], v145 offset:41472
	ds_read_b128 v[192:195], v144 offset:4608
	ds_read_b128 v[196:199], v144 offset:32
	ds_read_b128 v[200:203], v145 offset:36896
	s_waitcnt lgkmcnt(4)
	v_mfma_f32_32x32x16_bf16 v[48:63], v[96:99], v[100:103], v[48:63]
	ds_read_b128 v[204:207], v145 offset:41504
	s_waitcnt vmcnt(7)
	ds_write_b128 v146, v[64:67] offset:18432
	s_waitcnt lgkmcnt(5)
	v_mfma_f32_32x32x16_bf16 v[32:47], v[96:99], v[104:107], v[32:47]
	ds_read_b128 v[208:211], v144 offset:4640
	s_waitcnt lgkmcnt(5)
	v_mfma_f32_32x32x16_bf16 v[16:31], v[192:195], v[100:103], v[16:31]
	s_waitcnt vmcnt(6)
	ds_write_b128 v146, v[68:71] offset:23040
	v_mfma_f32_32x32x16_bf16 v[0:15], v[192:195], v[104:107], v[0:15]
	ds_read_b128 v[212:215], v144 offset:64
	ds_read_b128 v[216:219], v145 offset:36928
	s_waitcnt lgkmcnt(6)
	v_mfma_f32_32x32x16_bf16 v[48:63], v[196:199], v[200:203], v[48:63]
	ds_read_b128 v[220:223], v145 offset:41536
	s_waitcnt vmcnt(5)
	ds_write_b128 v146, v[72:75] offset:27648
	s_waitcnt lgkmcnt(7)
	v_mfma_f32_32x32x16_bf16 v[32:47], v[196:199], v[204:207], v[32:47]
	ds_read_b128 v[224:227], v144 offset:4672
	s_waitcnt lgkmcnt(6)
	v_mfma_f32_32x32x16_bf16 v[16:31], v[208:211], v[200:203], v[16:31]
	s_waitcnt vmcnt(4)
	ds_write_b128 v146, v[76:79] offset:32256
	v_mfma_f32_32x32x16_bf16 v[0:15], v[208:211], v[204:207], v[0:15]
	ds_read_b128 v[228:231], v144 offset:96
	ds_read_b128 v[96:99], v145 offset:36960
	s_waitcnt lgkmcnt(6)
	v_mfma_f32_32x32x16_bf16 v[48:63], v[212:215], v[216:219], v[48:63]
	ds_read_b128 v[100:103], v145 offset:41568
	s_waitcnt vmcnt(3)
	ds_write_b128 v146, v[80:83] offset:55296
	s_waitcnt lgkmcnt(7)
	v_mfma_f32_32x32x16_bf16 v[32:47], v[212:215], v[220:223], v[32:47]
	ds_read_b128 v[104:107], v144 offset:4704
	s_waitcnt lgkmcnt(6)
	v_mfma_f32_32x32x16_bf16 v[16:31], v[224:227], v[216:219], v[16:31]
	s_waitcnt vmcnt(2)
	ds_write_b128 v146, v[84:87] offset:59904
	v_mfma_f32_32x32x16_bf16 v[0:15], v[224:227], v[220:223], v[0:15]
	s_waitcnt lgkmcnt(4)
	v_mfma_f32_32x32x16_bf16 v[48:63], v[228:231], v[96:99], v[48:63]
	s_waitcnt vmcnt(1)
	ds_write_b128 v146, v[88:91] offset:64512
	s_waitcnt lgkmcnt(4)
	v_mfma_f32_32x32x16_bf16 v[32:47], v[228:231], v[100:103], v[32:47]
	s_waitcnt lgkmcnt(2)
	v_mfma_f32_32x32x16_bf16 v[16:31], v[104:107], v[96:99], v[16:31]
	s_waitcnt vmcnt(0)
	ds_write_b128 v147, v[92:95] offset:13824
	v_mfma_f32_32x32x16_bf16 v[0:15], v[104:107], v[100:103], v[0:15]
	s_setprio 0
	s_waitcnt lgkmcnt(0)
	s_barrier
	s_setprio 1
	ds_read_b128 v[64:67], v144 offset:18432
	ds_read_b128 v[68:71], v145 offset:55296
	ds_read_b128 v[72:75], v145 offset:59904
	ds_read_b128 v[192:195], v144 offset:23040
	ds_read_b128 v[196:199], v144 offset:18464
	ds_read_b128 v[200:203], v145 offset:55328
	s_waitcnt lgkmcnt(4)
	v_mfma_f32_32x32x16_bf16 v[48:63], v[64:67], v[68:71], v[48:63]
	ds_read_b128 v[204:207], v145 offset:59936
	s_waitcnt lgkmcnt(4)
	v_mfma_f32_32x32x16_bf16 v[32:47], v[64:67], v[72:75], v[32:47]
	ds_read_b128 v[208:211], v144 offset:23072
	s_waitcnt lgkmcnt(4)
	v_mfma_f32_32x32x16_bf16 v[16:31], v[192:195], v[68:71], v[16:31]
	v_mfma_f32_32x32x16_bf16 v[0:15], v[192:195], v[72:75], v[0:15]
	ds_read_b128 v[212:215], v144 offset:18496
	ds_read_b128 v[216:219], v145 offset:55360
	s_waitcnt lgkmcnt(4)
	v_mfma_f32_32x32x16_bf16 v[48:63], v[196:199], v[200:203], v[48:63]
	ds_read_b128 v[220:223], v145 offset:59968
	s_waitcnt lgkmcnt(4)
	v_mfma_f32_32x32x16_bf16 v[32:47], v[196:199], v[204:207], v[32:47]
	ds_read_b128 v[224:227], v144 offset:23104
	s_waitcnt lgkmcnt(4)
	v_mfma_f32_32x32x16_bf16 v[16:31], v[208:211], v[200:203], v[16:31]
	v_mfma_f32_32x32x16_bf16 v[0:15], v[208:211], v[204:207], v[0:15]
	ds_read_b128 v[228:231], v144 offset:18528
	ds_read_b128 v[64:67], v145 offset:55392
	s_waitcnt lgkmcnt(4)
	v_mfma_f32_32x32x16_bf16 v[48:63], v[212:215], v[216:219], v[48:63]
	ds_read_b128 v[68:71], v145 offset:60000
	s_waitcnt lgkmcnt(4)
	v_mfma_f32_32x32x16_bf16 v[32:47], v[212:215], v[220:223], v[32:47]
	ds_read_b128 v[72:75], v144 offset:23136
	s_waitcnt lgkmcnt(4)
	v_mfma_f32_32x32x16_bf16 v[16:31], v[224:227], v[216:219], v[16:31]
	v_mfma_f32_32x32x16_bf16 v[0:15], v[224:227], v[220:223], v[0:15]
	s_waitcnt lgkmcnt(2)
	v_mfma_f32_32x32x16_bf16 v[48:63], v[228:231], v[64:67], v[48:63]
	s_waitcnt lgkmcnt(1)
	v_mfma_f32_32x32x16_bf16 v[32:47], v[228:231], v[68:71], v[32:47]
	s_waitcnt lgkmcnt(0)
	v_mfma_f32_32x32x16_bf16 v[16:31], v[72:75], v[64:67], v[16:31]
	v_mfma_f32_32x32x16_bf16 v[0:15], v[72:75], v[68:71], v[0:15]
	s_setprio 0
	s_nop 6
	v_cvt_pk_bf16_f32 v32, v32, s0
	s_nop 2
	v_cvt_pk_bf16_f32 v0, v0, s0
	s_barrier
	ds_write_b16 v143, v32 offset:64
	v_cvt_pk_bf16_f32 v32, v49, s0
	ds_write_b16 v143, v0 offset:8768
	v_cvt_pk_bf16_f32 v0, v17, s0
	ds_write_b16 v143, v32 offset:272
	v_cvt_pk_bf16_f32 v32, v33, s0
	ds_write_b16 v143, v0 offset:8976
	v_cvt_pk_bf16_f32 v0, v1, s0
	ds_write_b16 v143, v32 offset:336
	v_cvt_pk_bf16_f32 v32, v50, s0
	ds_write_b16 v143, v0 offset:9040
	v_cvt_pk_bf16_f32 v0, v18, s0
	ds_write_b16 v143, v32 offset:544
	v_cvt_pk_bf16_f32 v32, v34, s0
	ds_write_b16 v143, v0 offset:9248
	v_cvt_pk_bf16_f32 v0, v2, s0
	ds_write_b16 v143, v32 offset:608
	v_cvt_pk_bf16_f32 v32, v51, s0
	ds_write_b16 v143, v0 offset:9312
	v_cvt_pk_bf16_f32 v0, v19, s0
	ds_write_b16 v143, v32 offset:816
	v_cvt_pk_bf16_f32 v32, v35, s0
	ds_write_b16 v143, v0 offset:9520
	v_cvt_pk_bf16_f32 v0, v3, s0
	ds_write_b16 v143, v32 offset:880
	v_cvt_pk_bf16_f32 v32, v52, s0
	ds_write_b16 v143, v0 offset:9584
	v_cvt_pk_bf16_f32 v0, v20, s0
	ds_write_b16 v143, v32 offset:2176
	v_cvt_pk_bf16_f32 v32, v36, s0
	ds_write_b16 v143, v0 offset:10880
	v_cvt_pk_bf16_f32 v0, v4, s0
	ds_write_b16 v143, v32 offset:2240
	v_cvt_pk_bf16_f32 v32, v53, s0
	ds_write_b16 v143, v0 offset:10944
	v_cvt_pk_bf16_f32 v0, v21, s0
	ds_write_b16 v143, v32 offset:2448
	v_cvt_pk_bf16_f32 v32, v37, s0
	ds_write_b16 v143, v0 offset:11152
	v_cvt_pk_bf16_f32 v0, v5, s0
	ds_write_b16 v143, v32 offset:2512
	v_cvt_pk_bf16_f32 v32, v54, s0
	ds_write_b16 v143, v0 offset:11216
	v_cvt_pk_bf16_f32 v0, v22, s0
	ds_write_b16 v143, v32 offset:2720
	v_cvt_pk_bf16_f32 v32, v38, s0
	ds_write_b16 v143, v0 offset:11424
	v_cvt_pk_bf16_f32 v0, v6, s0
	ds_write_b16 v143, v32 offset:2784
	v_cvt_pk_bf16_f32 v32, v55, s0
	ds_write_b16 v143, v0 offset:11488
	v_cvt_pk_bf16_f32 v0, v23, s0
	ds_write_b16 v143, v32 offset:2992
	v_cvt_pk_bf16_f32 v32, v39, s0
	ds_write_b16 v143, v0 offset:11696
	v_cvt_pk_bf16_f32 v0, v7, s0
	ds_write_b16 v143, v32 offset:3056
	v_cvt_pk_bf16_f32 v32, v56, s0
	ds_write_b16 v143, v0 offset:11760
	v_cvt_pk_bf16_f32 v0, v24, s0
	ds_write_b16 v143, v32 offset:4352
	v_cvt_pk_bf16_f32 v32, v40, s0
	ds_write_b16 v143, v0 offset:13056
	v_cvt_pk_bf16_f32 v0, v8, s0
	ds_write_b16 v143, v32 offset:4416
	v_cvt_pk_bf16_f32 v32, v57, s0
	ds_write_b16 v143, v0 offset:13120
	v_cvt_pk_bf16_f32 v0, v25, s0
	ds_write_b16 v143, v32 offset:4624
	v_cvt_pk_bf16_f32 v32, v41, s0
	ds_write_b16 v143, v0 offset:13328
	v_cvt_pk_bf16_f32 v0, v9, s0
	ds_write_b16 v143, v32 offset:4688
	v_cvt_pk_bf16_f32 v32, v58, s0
	ds_write_b16 v143, v0 offset:13392
	v_cvt_pk_bf16_f32 v0, v26, s0
	ds_write_b16 v143, v32 offset:4896
	v_cvt_pk_bf16_f32 v32, v42, s0
	ds_write_b16 v143, v0 offset:13600
	v_cvt_pk_bf16_f32 v0, v10, s0
	ds_write_b16 v143, v32 offset:4960
	v_cvt_pk_bf16_f32 v32, v59, s0
	ds_write_b16 v143, v0 offset:13664
	v_cvt_pk_bf16_f32 v0, v27, s0
	ds_write_b16 v143, v32 offset:5168
	v_cvt_pk_bf16_f32 v32, v43, s0
	ds_write_b16 v143, v0 offset:13872
	v_cvt_pk_bf16_f32 v0, v11, s0
	ds_write_b16 v143, v32 offset:5232
	v_cvt_pk_bf16_f32 v32, v60, s0
	ds_write_b16 v143, v0 offset:13936
	v_cvt_pk_bf16_f32 v0, v28, s0
	ds_write_b16 v143, v32 offset:6528
	v_cvt_pk_bf16_f32 v32, v44, s0
	ds_write_b16 v143, v0 offset:15232
	v_cvt_pk_bf16_f32 v0, v12, s0
	ds_write_b16 v143, v32 offset:6592
	v_cvt_pk_bf16_f32 v32, v61, s0
	ds_write_b16 v143, v0 offset:15296
	v_cvt_pk_bf16_f32 v0, v29, s0
	ds_write_b16 v143, v32 offset:6800
	v_cvt_pk_bf16_f32 v32, v45, s0
	ds_write_b16 v143, v0 offset:15504
	v_cvt_pk_bf16_f32 v0, v13, s0
	ds_write_b16 v143, v32 offset:6864
	v_cvt_pk_bf16_f32 v32, v62, s0
	ds_write_b16 v143, v0 offset:15568
	v_cvt_pk_bf16_f32 v0, v30, s0
	ds_write_b16 v143, v32 offset:7072
	v_cvt_pk_bf16_f32 v32, v46, s0
	ds_write_b16 v143, v0 offset:15776
	v_cvt_pk_bf16_f32 v0, v14, s0
	ds_write_b16 v143, v32 offset:7136
	v_cvt_pk_bf16_f32 v32, v63, s0
	ds_write_b16 v143, v0 offset:15840
	v_cvt_pk_bf16_f32 v0, v31, s0
	v_cvt_pk_bf16_f32 v48, v48, s0
	ds_write_b16 v143, v32 offset:7344
	v_cvt_pk_bf16_f32 v32, v47, s0
	v_cvt_pk_bf16_f32 v16, v16, s0
	ds_write_b16 v143, v0 offset:16048
	v_cvt_pk_bf16_f32 v0, v15, s0
	v_mov_b32_e32 v15, v142
	ds_write_b16 v143, v48
	ds_write_b16 v143, v32 offset:7408
	ds_write_b16 v143, v16 offset:8704
	ds_write_b16 v143, v0 offset:16112
	s_waitcnt lgkmcnt(0)
	s_barrier
	v_mov_b64_e32 v[2:3], s[4:5]
	v_lshlrev_b32_e32 v0, 3, v15
	v_and_b32_e32 v0, 0x78, v0
	v_ashrrev_i32_e32 v1, 4, v15
	v_lshlrev_b32_e32 v128, 1, v0
	v_add_u32_e32 v0, s69, v1
	s_lshl_b32 s16, s26, 10
	v_mad_i64_i32 v[2:3], s[0:1], v0, s66, v[2:3]
	v_lshl_add_u64 v[2:3], s[16:17], 1, v[2:3]
	v_lshl_add_u64 v[2:3], s[22:23], 1, v[2:3]
	v_lshl_add_u64 v[2:3], v[2:3], 0, v[128:129]
	global_load_dwordx4 v[6:9], v[2:3], off
	v_add_co_u32_e32 v80, vcc, 0x18000, v2
	s_nop 1
	v_addc_co_u32_e32 v81, vcc, 0, v3, vcc
	global_load_dwordx4 v[24:27], v[80:81], off
	v_add_co_u32_e32 v80, vcc, 0x30000, v2
	s_nop 1
	v_addc_co_u32_e32 v81, vcc, 0, v3, vcc
	global_load_dwordx4 v[28:31], v[80:81], off
	v_add_co_u32_e32 v80, vcc, 0x48000, v2
	s_nop 1
	v_addc_co_u32_e32 v81, vcc, 0, v3, vcc
	global_load_dwordx4 v[32:35], v[80:81], off
	v_add_co_u32_e32 v80, vcc, 0x60000, v2
	s_nop 1
	v_addc_co_u32_e32 v81, vcc, 0, v3, vcc
	global_load_dwordx4 v[36:39], v[80:81], off
	v_add_co_u32_e32 v80, vcc, 0x78000, v2
	s_nop 1
	v_addc_co_u32_e32 v81, vcc, 0, v3, vcc
	global_load_dwordx4 v[40:43], v[80:81], off
	v_add_co_u32_e32 v80, vcc, 0x90000, v2
	s_nop 1
	v_addc_co_u32_e32 v81, vcc, 0, v3, vcc
	global_load_dwordx4 v[44:47], v[80:81], off
	v_add_co_u32_e32 v80, vcc, 0xa8000, v2
	s_nop 1
	v_addc_co_u32_e32 v81, vcc, 0, v3, vcc
	global_load_dwordx4 v[48:51], v[80:81], off
	v_add_u32_e32 v14, 32, v128
	v_mad_u64_u32 v[2:3], s[0:1], v1, s60, v[14:15]
	ds_read_b128 v[2:5], v2
	v_ashrrev_i32_e32 v1, 31, v0
	v_lshlrev_b64 v[0:1], 11, v[0:1]
	v_lshl_add_u64 v[0:1], s[24:25], 0, v[0:1]
	v_lshl_add_u64 v[16:17], v[0:1], 0, v[128:129]
	v_cndmask_b32_e64 v1, 0, 1, s[50:51]
	v_mov_b32_e32 v0, 0
	v_cmp_ne_u32_e64 s[0:1], 1, v1
	s_andn2_b64 vcc, exec, s[50:51]
	v_mov_b32_e32 v10, 0
	v_mov_b32_e32 v11, 0
	v_mov_b32_e32 v12, 0
	v_mov_b32_e32 v13, 0
	s_cbranch_vccnz .LBB0_1748
	global_load_dwordx4 v[10:13], v[16:17], off
	v_add_co_u32_e32 v80, vcc, 0x8000, v16
	s_nop 1
	v_addc_co_u32_e32 v81, vcc, 0, v17, vcc
	global_load_dwordx4 v[52:55], v[80:81], off
	v_add_co_u32_e32 v80, vcc, 0x10000, v16
	s_nop 1
	v_addc_co_u32_e32 v81, vcc, 0, v17, vcc
	global_load_dwordx4 v[56:59], v[80:81], off
	v_add_co_u32_e32 v80, vcc, 0x18000, v16
	s_nop 1
	v_addc_co_u32_e32 v81, vcc, 0, v17, vcc
	global_load_dwordx4 v[60:63], v[80:81], off
	v_add_co_u32_e32 v80, vcc, 0x20000, v16
	s_nop 1
	v_addc_co_u32_e32 v81, vcc, 0, v17, vcc
	global_load_dwordx4 v[64:67], v[80:81], off
	v_add_co_u32_e32 v80, vcc, 0x28000, v16
	s_nop 1
	v_addc_co_u32_e32 v81, vcc, 0, v17, vcc
	global_load_dwordx4 v[68:71], v[80:81], off
	v_add_co_u32_e32 v80, vcc, 0x30000, v16
	s_nop 1
	v_addc_co_u32_e32 v81, vcc, 0, v17, vcc
	global_load_dwordx4 v[72:75], v[80:81], off
	v_add_co_u32_e32 v80, vcc, 0x38000, v16
	s_nop 1
	v_addc_co_u32_e32 v81, vcc, 0, v17, vcc
	global_load_dwordx4 v[76:79], v[80:81], off

.LBB0_1817:
	s_setprio 1
	ds_read_b128 v[140:143], v103
	ds_read_b128 v[144:147], v104 offset:36864
	ds_read_b128 v[148:151], v103 offset:32
	ds_read_b128 v[192:195], v104 offset:36896
	ds_read_b128 v[196:199], v104 offset:41472
	ds_read_b128 v[200:203], v103 offset:4608
	s_waitcnt lgkmcnt(4)
	v_mfma_f32_32x32x16_bf16 v[48:63], v[140:143], v[144:147], v[48:63]
	ds_read_b128 v[204:207], v104 offset:41504
	global_load_dwordx4 v[108:111], v168, s[98:99] offset:3840
	global_load_dwordx4 v[112:115], v170, s[98:99] offset:3840
	s_waitcnt vmcnt(9)
	ds_write_b128 v105, v[68:71] offset:18432
	s_waitcnt lgkmcnt(3)
	v_mfma_f32_32x32x16_bf16 v[32:47], v[140:143], v[196:199], v[32:47]
	ds_read_b128 v[208:211], v103 offset:4640
	global_load_dwordx4 v[116:119], v172, s[98:99] offset:3840
	global_load_dwordx4 v[120:123], v174, s[98:99] offset:3840
	s_waitcnt lgkmcnt(3)
	v_mfma_f32_32x32x16_bf16 v[16:31], v[200:203], v[144:147], v[16:31]
	global_load_dwordx4 v[124:127], v176, s[98:99] offset:3840
	global_load_dwordx4 v[128:131], v178, s[98:99] offset:3840
	s_waitcnt vmcnt(11)
	ds_write_b128 v105, v[84:87] offset:23040
	v_mfma_f32_32x32x16_bf16 v[0:15], v[200:203], v[196:199], v[0:15]
	ds_read_b128 v[212:215], v103 offset:64
	ds_read_b128 v[216:219], v104 offset:36928
	global_load_dwordx4 v[132:135], v180, s[98:99] offset:3840
	global_load_dwordx4 v[136:139], v182, s[98:99] offset:3840
	v_mfma_f32_32x32x16_bf16 v[48:63], v[148:151], v[192:195], v[48:63]
	ds_read_b128 v[220:223], v104 offset:41536
	s_waitcnt vmcnt(12)
	ds_write_b128 v105, v[88:91] offset:27648
	s_waitcnt lgkmcnt(7)
	v_mfma_f32_32x32x16_bf16 v[32:47], v[148:151], v[204:207], v[32:47]
	ds_read_b128 v[224:227], v103 offset:4672
	s_waitcnt lgkmcnt(6)
	v_mfma_f32_32x32x16_bf16 v[16:31], v[208:211], v[192:195], v[16:31]
	s_waitcnt vmcnt(11)
	ds_write_b128 v105, v[92:95] offset:32256
	v_mfma_f32_32x32x16_bf16 v[0:15], v[208:211], v[204:207], v[0:15]
	ds_read_b128 v[228:231], v103 offset:96
	ds_read_b128 v[140:143], v104 offset:36960
	s_waitcnt lgkmcnt(6)
	v_mfma_f32_32x32x16_bf16 v[48:63], v[212:215], v[216:219], v[48:63]
	ds_read_b128 v[144:147], v104 offset:41568
	ds_write_b128 v105, v[64:67] offset:55296
	s_waitcnt lgkmcnt(7)
	v_mfma_f32_32x32x16_bf16 v[32:47], v[212:215], v[220:223], v[32:47]
	ds_read_b128 v[196:199], v103 offset:4704
	s_waitcnt lgkmcnt(6)
	v_mfma_f32_32x32x16_bf16 v[16:31], v[224:227], v[216:219], v[16:31]
	s_waitcnt vmcnt(10)
	ds_write_b128 v105, v[72:75] offset:59904
	v_mfma_f32_32x32x16_bf16 v[0:15], v[224:227], v[220:223], v[0:15]
	s_waitcnt lgkmcnt(4)
	v_mfma_f32_32x32x16_bf16 v[48:63], v[228:231], v[140:143], v[48:63]
	s_waitcnt vmcnt(9)
	ds_write_b128 v105, v[76:79] offset:64512
	s_waitcnt lgkmcnt(4)
	v_mfma_f32_32x32x16_bf16 v[32:47], v[228:231], v[144:147], v[32:47]
	s_waitcnt lgkmcnt(2)
	v_mfma_f32_32x32x16_bf16 v[16:31], v[196:199], v[140:143], v[16:31]
	s_waitcnt vmcnt(8)
	ds_write_b128 v106, v[80:83] offset:13824
	v_mfma_f32_32x32x16_bf16 v[0:15], v[196:199], v[144:147], v[0:15]
	s_setprio 0
	s_waitcnt lgkmcnt(0)
	s_barrier
	s_setprio 1
	ds_read_b128 v[140:143], v103 offset:18432
	ds_read_b128 v[144:147], v104 offset:55296
	ds_read_b128 v[148:151], v103 offset:18464
	ds_read_b128 v[192:195], v104 offset:55328
	ds_read_b128 v[196:199], v104 offset:59904
	ds_read_b128 v[200:203], v103 offset:23040
	s_waitcnt lgkmcnt(4)
	v_mfma_f32_32x32x16_bf16 v[48:63], v[140:143], v[144:147], v[48:63]
	ds_read_b128 v[204:207], v104 offset:59936
	global_load_dwordx4 v[68:71], v168, s[98:99] offset:3968
	global_load_dwordx4 v[84:87], v170, s[98:99] offset:3968
	s_waitcnt vmcnt(9)
	ds_write_b128 v105, v[108:111]
	s_waitcnt lgkmcnt(3)
	v_mfma_f32_32x32x16_bf16 v[32:47], v[140:143], v[196:199], v[32:47]
	ds_read_b128 v[208:211], v103 offset:23072
	global_load_dwordx4 v[88:91], v172, s[98:99] offset:3968
	global_load_dwordx4 v[92:95], v174, s[98:99] offset:3968
	s_waitcnt lgkmcnt(3)
	v_mfma_f32_32x32x16_bf16 v[16:31], v[200:203], v[144:147], v[16:31]
	global_load_dwordx4 v[64:67], v176, s[98:99] offset:3968
	global_load_dwordx4 v[72:75], v178, s[98:99] offset:3968
	s_waitcnt vmcnt(12)
	ds_write_b128 v105, v[112:115] offset:4608
	v_mfma_f32_32x32x16_bf16 v[0:15], v[200:203], v[196:199], v[0:15]
	ds_read_b128 v[212:215], v103 offset:18496
	ds_read_b128 v[216:219], v104 offset:55360
	global_load_dwordx4 v[76:79], v180, s[98:99] offset:3968
	global_load_dwordx4 v[80:83], v182, s[98:99] offset:3968
	v_mfma_f32_32x32x16_bf16 v[48:63], v[148:151], v[192:195], v[48:63]
	ds_read_b128 v[220:223], v104 offset:59968
	s_add_u32 s98, s98, 0x100
	s_addc_u32 s99, s99, 0
	s_add_i32 s10, s10, 2
	s_cmp_lt_u32 s10, 11
	s_waitcnt vmcnt(13)
	ds_write_b128 v105, v[116:119] offset:9216
	s_waitcnt lgkmcnt(7)
	v_mfma_f32_32x32x16_bf16 v[32:47], v[148:151], v[204:207], v[32:47]
	ds_read_b128 v[224:227], v103 offset:23104
	s_waitcnt lgkmcnt(6)
	v_mfma_f32_32x32x16_bf16 v[16:31], v[208:211], v[192:195], v[16:31]
	s_waitcnt vmcnt(12)
	ds_write_b128 v105, v[120:123] offset:13824
	v_mfma_f32_32x32x16_bf16 v[0:15], v[208:211], v[204:207], v[0:15]
	ds_read_b128 v[228:231], v103 offset:18528
	ds_read_b128 v[140:143], v104 offset:55392
	s_waitcnt lgkmcnt(6)
	v_mfma_f32_32x32x16_bf16 v[48:63], v[212:215], v[216:219], v[48:63]
	ds_read_b128 v[144:147], v104 offset:60000
	s_waitcnt vmcnt(11)
	ds_write_b128 v105, v[124:127] offset:36864
	s_waitcnt lgkmcnt(7)
	v_mfma_f32_32x32x16_bf16 v[32:47], v[212:215], v[220:223], v[32:47]
	ds_read_b128 v[196:199], v103 offset:23136
	s_waitcnt lgkmcnt(6)
	v_mfma_f32_32x32x16_bf16 v[16:31], v[224:227], v[216:219], v[16:31]
	s_waitcnt vmcnt(10)
	ds_write_b128 v105, v[128:131] offset:41472
	v_mfma_f32_32x32x16_bf16 v[0:15], v[224:227], v[220:223], v[0:15]
	s_waitcnt lgkmcnt(4)
	v_mfma_f32_32x32x16_bf16 v[48:63], v[228:231], v[140:143], v[48:63]
	s_waitcnt vmcnt(9)
	ds_write_b128 v105, v[132:135] offset:46080
	s_waitcnt lgkmcnt(4)
	v_mfma_f32_32x32x16_bf16 v[32:47], v[228:231], v[144:147], v[32:47]
	s_waitcnt lgkmcnt(2)
	v_mfma_f32_32x32x16_bf16 v[16:31], v[196:199], v[140:143], v[16:31]
	s_waitcnt vmcnt(8)
	ds_write_b128 v105, v[136:139] offset:50688
	v_mfma_f32_32x32x16_bf16 v[0:15], v[196:199], v[144:147], v[0:15]
	s_setprio 0
	s_waitcnt lgkmcnt(0)
	s_barrier
	s_cbranch_scc1 .LBB0_1817
	s_setprio 1
	ds_read_b128 v[98:101], v103
	ds_read_b128 v[108:111], v104 offset:36864
	ds_read_b128 v[112:115], v103 offset:32
	ds_read_b128 v[192:195], v104 offset:36896
	ds_read_b128 v[196:199], v104 offset:41472
	ds_read_b128 v[200:203], v103 offset:4608
	s_waitcnt lgkmcnt(4)
	v_mfma_f32_32x32x16_bf16 v[48:63], v[98:101], v[108:111], v[48:63]
	ds_read_b128 v[204:207], v104 offset:41504
	s_waitcnt vmcnt(7)
	ds_write_b128 v105, v[68:71] offset:18432
	s_waitcnt lgkmcnt(3)
	v_mfma_f32_32x32x16_bf16 v[32:47], v[98:101], v[196:199], v[32:47]
	ds_read_b128 v[208:211], v103 offset:4640
	s_waitcnt lgkmcnt(3)
	v_mfma_f32_32x32x16_bf16 v[16:31], v[200:203], v[108:111], v[16:31]
	s_waitcnt vmcnt(6)
	ds_write_b128 v105, v[84:87] offset:23040
	v_mfma_f32_32x32x16_bf16 v[0:15], v[200:203], v[196:199], v[0:15]
	ds_read_b128 v[212:215], v103 offset:64
	ds_read_b128 v[216:219], v104 offset:36928
	v_mfma_f32_32x32x16_bf16 v[48:63], v[112:115], v[192:195], v[48:63]
	ds_read_b128 v[220:223], v104 offset:41536
	s_waitcnt vmcnt(5)
	ds_write_b128 v105, v[88:91] offset:27648
	s_waitcnt lgkmcnt(7)
	v_mfma_f32_32x32x16_bf16 v[32:47], v[112:115], v[204:207], v[32:47]
	ds_read_b128 v[224:227], v103 offset:4672
	s_waitcnt lgkmcnt(6)
	v_mfma_f32_32x32x16_bf16 v[16:31], v[208:211], v[192:195], v[16:31]
	s_waitcnt vmcnt(4)
	ds_write_b128 v105, v[92:95] offset:32256
	v_mfma_f32_32x32x16_bf16 v[0:15], v[208:211], v[204:207], v[0:15]
	ds_read_b128 v[228:231], v104 offset:36960
	ds_read_b128 v[98:101], v103 offset:4704
	s_waitcnt lgkmcnt(6)
	v_mfma_f32_32x32x16_bf16 v[48:63], v[212:215], v[216:219], v[48:63]
	ds_read_b128 v[108:111], v104 offset:41568
	s_waitcnt vmcnt(3)
	ds_write_b128 v105, v[64:67] offset:55296
	s_waitcnt lgkmcnt(7)
	v_mfma_f32_32x32x16_bf16 v[32:47], v[212:215], v[220:223], v[32:47]
	ds_read_b128 v[196:199], v103 offset:96
	s_waitcnt lgkmcnt(6)
	v_mfma_f32_32x32x16_bf16 v[16:31], v[224:227], v[216:219], v[16:31]
	s_waitcnt vmcnt(2)
	ds_write_b128 v105, v[72:75] offset:59904
	v_mfma_f32_32x32x16_bf16 v[0:15], v[224:227], v[220:223], v[0:15]
	s_waitcnt lgkmcnt(4)
	v_mfma_f32_32x32x16_bf16 v[16:31], v[98:101], v[228:231], v[16:31]
	s_waitcnt vmcnt(1)
	ds_write_b128 v105, v[76:79] offset:64512
	s_waitcnt lgkmcnt(4)
	v_mfma_f32_32x32x16_bf16 v[0:15], v[98:101], v[108:111], v[0:15]
	s_waitcnt lgkmcnt(2)
	v_mfma_f32_32x32x16_bf16 v[48:63], v[196:199], v[228:231], v[48:63]
	s_waitcnt vmcnt(0)
	ds_write_b128 v106, v[80:83] offset:13824
	v_mfma_f32_32x32x16_bf16 v[32:47], v[196:199], v[108:111], v[32:47]
	s_setprio 0
	s_waitcnt lgkmcnt(0)
	s_barrier
	s_setprio 1
	ds_read_b128 v[64:67], v103 offset:18432
	ds_read_b128 v[68:71], v104 offset:55296
	ds_read_b128 v[72:75], v103 offset:18464
	ds_read_b128 v[192:195], v104 offset:55328
	ds_read_b128 v[196:199], v104 offset:59904
	ds_read_b128 v[200:203], v103 offset:23040
	s_waitcnt lgkmcnt(4)
	v_mfma_f32_32x32x16_bf16 v[48:63], v[64:67], v[68:71], v[48:63]
	ds_read_b128 v[204:207], v104 offset:59936
	s_waitcnt lgkmcnt(2)
	v_mfma_f32_32x32x16_bf16 v[32:47], v[64:67], v[196:199], v[32:47]
	ds_read_b128 v[208:211], v103 offset:23072
	s_waitcnt lgkmcnt(2)
	v_mfma_f32_32x32x16_bf16 v[16:31], v[200:203], v[68:71], v[16:31]
	v_mfma_f32_32x32x16_bf16 v[0:15], v[200:203], v[196:199], v[0:15]
	ds_read_b128 v[212:215], v103 offset:18496
	ds_read_b128 v[216:219], v104 offset:55360
	v_mfma_f32_32x32x16_bf16 v[48:63], v[72:75], v[192:195], v[48:63]
	ds_read_b128 v[220:223], v104 offset:59968
	s_waitcnt lgkmcnt(4)
	v_mfma_f32_32x32x16_bf16 v[32:47], v[72:75], v[204:207], v[32:47]
	ds_read_b128 v[224:227], v103 offset:23104
	s_waitcnt lgkmcnt(4)
	v_mfma_f32_32x32x16_bf16 v[16:31], v[208:211], v[192:195], v[16:31]
	v_mfma_f32_32x32x16_bf16 v[0:15], v[208:211], v[204:207], v[0:15]
	ds_read_b128 v[228:231], v104 offset:55392
	ds_read_b128 v[64:67], v103 offset:23136
	s_waitcnt lgkmcnt(4)
	v_mfma_f32_32x32x16_bf16 v[48:63], v[212:215], v[216:219], v[48:63]
	ds_read_b128 v[68:71], v104 offset:60000
	s_waitcnt lgkmcnt(4)
	v_mfma_f32_32x32x16_bf16 v[32:47], v[212:215], v[220:223], v[32:47]
	ds_read_b128 v[196:199], v103 offset:18528
	s_waitcnt lgkmcnt(4)
	v_mfma_f32_32x32x16_bf16 v[16:31], v[224:227], v[216:219], v[16:31]
	v_mfma_f32_32x32x16_bf16 v[0:15], v[224:227], v[220:223], v[0:15]
	s_waitcnt lgkmcnt(2)
	v_mfma_f32_32x32x16_bf16 v[16:31], v[64:67], v[228:231], v[16:31]
	s_waitcnt lgkmcnt(1)
	v_mfma_f32_32x32x16_bf16 v[0:15], v[64:67], v[68:71], v[0:15]
	s_waitcnt lgkmcnt(0)
	v_mfma_f32_32x32x16_bf16 v[48:63], v[196:199], v[228:231], v[48:63]
	v_mfma_f32_32x32x16_bf16 v[32:47], v[196:199], v[68:71], v[32:47]
	s_setprio 0
	s_addk_i32 s0, 0xf000
	s_lshr_b32 s10, s0, 10
	s_mulk_i32 s10, 0x1800
	s_addk_i32 s10, 0x1800
	s_and_b64 s[22:23], s[8:9], exec
	s_cselect_b32 s10, 0, s10
	v_mov_b32_e32 v68, v234
	s_barrier
	s_lshl_b64 s[22:23], s[10:11], 2
	s_add_u32 s22, s30, s22
	v_and_b32_e32 v69, 0x5f, v68
	v_or_b32_e32 v64, s21, v69
	s_addc_u32 s23, s31, s23
	v_ashrrev_i32_e32 v65, 31, v64
	v_lshl_add_u64 v[64:65], v[64:65], 2, s[22:23]
	v_lshl_add_u64 v[66:67], v[64:65], 0, s[14:15]
	v_add_co_u32_e32 v64, vcc, s54, v64
	v_lshlrev_b32_e32 v69, 2, v69
	s_nop 0
	v_addc_co_u32_e32 v65, vcc, 0, v65, vcc
	global_load_dword v64, v[64:65], off
	s_nop 0
	global_load_dword v65, v[66:67], off offset:128
	v_lshrrev_b32_e32 v67, 3, v68
	v_lshrrev_b32_e32 v66, 1, v68
	v_and_b32_e32 v67, 4, v67
	v_and_or_b32 v66, v66, s45, v67
	v_mul_lo_u32 v66, v66, s55
	v_add3_u32 v66, 32, v69, v66
	v_add_u32_e32 v67, 0x400, v66
	v_add_u32_e32 v69, 0x1000, v66
	v_add_u32_e32 v70, 0x1400, v66
	v_add_u32_e32 v71, 0x2000, v66
	v_add_u32_e32 v72, 0x2400, v66
	v_add_u32_e32 v73, 0x3000, v66
	v_add_u32_e32 v74, 0x3200, v66
	v_add_u32_e32 v75, 0x3400, v66
	v_add_u32_e32 v76, 0x3600, v66
	v_add_u32_e32 v77, 0x4000, v66
	v_readlane_b32 s80, v251, 39
	v_readlane_b32 s81, v251, 40
	s_lshl_b32 s1, s1, 19
	v_readlane_b32 s82, v251, 41
	v_readlane_b32 s83, v251, 42
	s_mov_b64 s[36:37], s[80:81]
	s_add_u32 s10, s36, s1
	s_mov_b32 s1, s11
	s_mov_b64 s[38:39], s[82:83]
	s_addc_u32 s21, s37, 0
	s_lshl_b64 s[0:1], s[0:1], 12
	s_add_u32 s22, s38, s0
	s_addc_u32 s23, s39, s1
	s_and_b64 s[0:1], s[8:9], exec
	s_cselect_b32 s23, s21, s23
	s_cselect_b32 s22, s10, s22
	s_add_i32 s10, s20, s27
	v_readlane_b32 s84, v251, 43
	v_readlane_b32 s85, v251, 44
	v_readlane_b32 s86, v251, 45
	v_readlane_b32 s87, v251, 46
	v_readlane_b32 s88, v251, 47
	v_readlane_b32 s89, v251, 48
	v_readlane_b32 s90, v251, 49
	v_readlane_b32 s91, v251, 50
	v_readlane_b32 s92, v251, 51
	v_readlane_b32 s93, v251, 52
	v_readlane_b32 s94, v251, 53
	v_readlane_b32 s95, v251, 54
	s_waitcnt vmcnt(1)
	v_mul_f32_e32 v48, v48, v64
	s_waitcnt vmcnt(0)
	v_mul_f32_e32 v32, v32, v65
	v_mul_f32_e32 v16, v16, v64
	v_mul_f32_e32 v0, v0, v65
	v_mul_f32_e32 v49, v49, v64
	v_mul_f32_e32 v33, v33, v65
	v_mul_f32_e32 v50, v50, v64
	v_mul_f32_e32 v34, v34, v65
	v_mul_f32_e32 v51, v51, v64
	v_mul_f32_e32 v35, v35, v65
	v_mul_f32_e32 v52, v52, v64
	v_mul_f32_e32 v36, v36, v65
	v_mul_f32_e32 v53, v53, v64
	v_mul_f32_e32 v37, v37, v65
	v_mul_f32_e32 v54, v54, v64
	v_mul_f32_e32 v38, v38, v65
	v_mul_f32_e32 v55, v55, v64
	v_mul_f32_e32 v39, v39, v65
	v_mul_f32_e32 v56, v56, v64
	v_mul_f32_e32 v40, v40, v65
	v_mul_f32_e32 v57, v57, v64
	v_mul_f32_e32 v41, v41, v65
	v_mul_f32_e32 v58, v58, v64
	v_mul_f32_e32 v42, v42, v65
	v_mul_f32_e32 v59, v59, v64
	v_mul_f32_e32 v43, v43, v65
	v_mul_f32_e32 v60, v60, v64
	v_mul_f32_e32 v44, v44, v65
	v_mul_f32_e32 v61, v61, v64
	v_mul_f32_e32 v45, v45, v65
	v_mul_f32_e32 v62, v62, v64
	v_mul_f32_e32 v46, v46, v65
	v_mul_f32_e32 v63, v63, v64
	v_mul_f32_e32 v47, v47, v65
	ds_write2_b32 v66, v48, v32 offset1:32
	ds_write2_b32 v66, v49, v33 offset0:132 offset1:164
	ds_write2_b32 v67, v50, v34 offset0:8 offset1:40
	ds_write2_b32 v67, v51, v35 offset0:140 offset1:172
	ds_write2_b32 v69, v52, v36 offset0:32 offset1:64
	ds_write2_b32 v69, v53, v37 offset0:164 offset1:196
	ds_write2_b32 v70, v54, v38 offset0:40 offset1:72
	ds_write2_b32 v70, v55, v39 offset0:172 offset1:204
	ds_write2_b32 v71, v56, v40 offset0:64 offset1:96
	ds_write2_b32 v71, v57, v41 offset0:196 offset1:228
	ds_write2_b32 v72, v58, v42 offset0:72 offset1:104
	ds_write2_b32 v72, v59, v43 offset0:204 offset1:236
	ds_write2_b32 v73, v60, v44 offset0:96 offset1:128
	ds_write2_b32 v74, v61, v45 offset0:100 offset1:132
	ds_write2_b32 v75, v62, v46 offset0:104 offset1:136
	ds_write2_b32 v76, v63, v47 offset0:108 offset1:140
	ds_write2_b32 v77, v16, v0 offset0:128 offset1:160
	v_mul_f32_e32 v0, v17, v64
	v_mul_f32_e32 v1, v1, v65
	v_add_u32_e32 v16, 0x4400, v66
	ds_write2_b32 v16, v0, v1 offset0:4 offset1:36
	v_mul_f32_e32 v0, v18, v64
	v_mul_f32_e32 v1, v2, v65
	ds_write2_b32 v16, v0, v1 offset0:136 offset1:168
	v_mul_f32_e32 v0, v19, v64
	v_mul_f32_e32 v1, v3, v65
	v_add_u32_e32 v2, 0x4800, v66
	ds_write2_b32 v2, v0, v1 offset0:12 offset1:44
	v_mul_f32_e32 v0, v20, v64
	v_mul_f32_e32 v1, v4, v65
	v_add_u32_e32 v2, 0x5000, v66
	ds_write2_b32 v2, v0, v1 offset0:160 offset1:192
	v_mul_f32_e32 v0, v21, v64
	v_mul_f32_e32 v1, v5, v65
	v_add_u32_e32 v2, 0x5400, v66
	ds_write2_b32 v2, v0, v1 offset0:36 offset1:68
	v_mul_f32_e32 v0, v22, v64
	v_mul_f32_e32 v1, v6, v65
	ds_write2_b32 v2, v0, v1 offset0:168 offset1:200
	v_mul_f32_e32 v0, v23, v64
	v_mul_f32_e32 v1, v7, v65
	v_add_u32_e32 v2, 0x5800, v66
	ds_write2_b32 v2, v0, v1 offset0:44 offset1:76
	v_mul_f32_e32 v0, v24, v64
	v_mul_f32_e32 v1, v8, v65
	v_add_u32_e32 v2, 0x6000, v66
	ds_write2_b32 v2, v0, v1 offset0:192 offset1:224
	v_mul_f32_e32 v0, v25, v64
	v_mul_f32_e32 v1, v9, v65
	v_add_u32_e32 v2, 0x6400, v66
	ds_write2_b32 v2, v0, v1 offset0:68 offset1:100
	v_mul_f32_e32 v0, v26, v64
	v_mul_f32_e32 v1, v10, v65
	ds_write2_b32 v2, v0, v1 offset0:200 offset1:232
	v_mul_f32_e32 v0, v27, v64
	v_mul_f32_e32 v1, v11, v65
	v_add_u32_e32 v2, 0x6800, v66
	ds_write2_b32 v2, v0, v1 offset0:76 offset1:108
	v_mul_f32_e32 v0, v28, v64
	v_mul_f32_e32 v1, v12, v65
	v_add_u32_e32 v2, 0x7200, v66
	ds_write2_b32 v2, v0, v1 offset0:96 offset1:128
	v_mul_f32_e32 v0, v29, v64
	v_mul_f32_e32 v1, v13, v65
	v_add_u32_e32 v2, 0x7400, v66
	ds_write2_b32 v2, v0, v1 offset0:100 offset1:132
	v_mul_f32_e32 v0, v30, v64
	v_mul_f32_e32 v1, v14, v65
	v_add_u32_e32 v2, 0x7600, v66
	ds_write2_b32 v2, v0, v1 offset0:104 offset1:136
	v_mul_f32_e32 v0, v31, v64
	v_mul_f32_e32 v1, v15, v65
	v_add_u32_e32 v2, 0x7800, v66
	ds_write2_b32 v2, v0, v1 offset0:108 offset1:140
	v_and_b32_e32 v0, 64, v102
	v_add_u32_e32 v0, 64, v0
	v_xor_b32_e32 v1, 1, v102
	v_cmp_lt_i32_e32 vcc, v1, v0
	v_and_b32_e32 v4, 31, v68
	v_lshl_add_u32 v2, v4, 2, s18
	v_cndmask_b32_e32 v1, v102, v1, vcc
	v_lshlrev_b32_e32 v20, 2, v1
	v_xor_b32_e32 v1, 2, v102
	v_cmp_lt_i32_e32 vcc, v1, v0
	v_ashrrev_i32_e32 v14, 5, v68
	v_ashrrev_i32_e32 v3, 31, v2
	v_cndmask_b32_e32 v1, v102, v1, vcc
	v_lshlrev_b32_e32 v21, 2, v1
	v_xor_b32_e32 v1, 4, v102
	v_cmp_lt_i32_e32 vcc, v1, v0
	v_cmp_eq_u32_e64 s[0:1], 0, v4
	v_lshlrev_b64 v[16:17], 2, v[2:3]
	v_cndmask_b32_e32 v1, v102, v1, vcc
	v_lshlrev_b32_e32 v22, 2, v1
	v_xor_b32_e32 v1, 8, v102
	v_cmp_lt_i32_e32 vcc, v1, v0
	v_lshlrev_b32_e32 v3, 4, v4
	v_add_u32_e32 v4, s10, v14
	v_cndmask_b32_e32 v1, v102, v1, vcc
	v_lshlrev_b32_e32 v23, 2, v1
	v_xor_b32_e32 v1, 16, v102
	s_add_i32 s10, s20, s33
	s_add_i32 s20, s20, s34
	v_cmp_lt_i32_e32 vcc, v1, v0
	v_add_u32_e32 v8, s10, v14
	v_add_u32_e32 v12, s20, v14
	v_add_u32_e32 v18, s19, v14
	v_cndmask_b32_e32 v0, v102, v1, vcc
	v_ashrrev_i32_e32 v15, 31, v14
	v_mul_lo_u32 v2, v14, s55
	v_ashrrev_i32_e32 v5, 31, v4
	v_ashrrev_i32_e32 v9, 31, v8
	v_ashrrev_i32_e32 v13, 31, v12
	v_ashrrev_i32_e32 v19, 31, v18
	v_lshlrev_b32_e32 v24, 2, v0
	v_lshlrev_b64 v[0:1], 12, v[14:15]
	v_add3_u32 v25, v2, v3, 32
	v_lshlrev_b32_e32 v2, 1, v4
	v_lshlrev_b64 v[4:5], 12, v[4:5]
	v_lshlrev_b32_e32 v6, 1, v8
	v_lshlrev_b64 v[8:9], 12, v[8:9]
	v_lshlrev_b32_e32 v10, 1, v12
	v_lshlrev_b64 v[12:13], 12, v[12:13]
	v_lshlrev_b64 v[14:15], 12, v[18:19]
	v_lshl_add_u64 v[0:1], v[0:1], 0, v[16:17]
	v_lshl_add_u64 v[4:5], v[4:5], 0, v[16:17]
	v_lshl_add_u64 v[8:9], v[8:9], 0, v[16:17]
	v_lshl_add_u64 v[12:13], v[12:13], 0, v[16:17]
	v_lshl_add_u64 v[14:15], v[14:15], 0, v[16:17]
	v_lshlrev_b32_e32 v16, 1, v18
	v_ashrrev_i32_e32 v3, 31, v2
	v_ashrrev_i32_e32 v7, 31, v6
	v_ashrrev_i32_e32 v11, 31, v10
	v_ashrrev_i32_e32 v17, 31, v16
	v_lshl_add_u64 v[0:1], s[22:23], 0, v[0:1]
	v_lshlrev_b64 v[2:3], 2, v[2:3]
	v_lshl_add_u64 v[4:5], s[30:31], 0, v[4:5]
	v_lshlrev_b64 v[6:7], 2, v[6:7]
	v_lshl_add_u64 v[8:9], s[30:31], 0, v[8:9]
	v_lshlrev_b64 v[10:11], 2, v[10:11]
	v_lshl_add_u64 v[12:13], s[30:31], 0, v[12:13]
	v_lshl_add_u64 v[14:15], s[30:31], 0, v[14:15]
	v_lshlrev_b64 v[16:17], 2, v[16:17]
	s_mov_b64 s[18:19], 0
	s_mov_b64 s[20:21], s[30:31]
	s_waitcnt lgkmcnt(0)
	s_barrier
	s_branch .LBB0_1820

.LBB0_1940:
	s_setprio 1
	ds_read_b128 v[140:143], v103
	ds_read_b128 v[144:147], v104 offset:36864
	ds_read_b128 v[148:151], v103 offset:32
	ds_read_b128 v[192:195], v104 offset:36896
	ds_read_b128 v[196:199], v104 offset:41472
	ds_read_b128 v[200:203], v103 offset:4608
	s_waitcnt lgkmcnt(4)
	v_mfma_f32_32x32x16_bf16 v[48:63], v[140:143], v[144:147], v[48:63]
	ds_read_b128 v[204:207], v104 offset:41504
	global_load_dwordx4 v[108:111], v168, s[98:99] offset:3840
	global_load_dwordx4 v[112:115], v170, s[98:99] offset:3840
	s_waitcnt vmcnt(9)
	ds_write_b128 v105, v[68:71] offset:18432
	s_waitcnt lgkmcnt(3)
	v_mfma_f32_32x32x16_bf16 v[32:47], v[140:143], v[196:199], v[32:47]
	ds_read_b128 v[208:211], v103 offset:4640
	global_load_dwordx4 v[116:119], v172, s[98:99] offset:3840
	global_load_dwordx4 v[120:123], v174, s[98:99] offset:3840
	s_waitcnt lgkmcnt(3)
	v_mfma_f32_32x32x16_bf16 v[16:31], v[200:203], v[144:147], v[16:31]
	global_load_dwordx4 v[124:127], v176, s[98:99] offset:3840
	global_load_dwordx4 v[128:131], v178, s[98:99] offset:3840
	s_waitcnt vmcnt(11)
	ds_write_b128 v105, v[84:87] offset:23040
	v_mfma_f32_32x32x16_bf16 v[0:15], v[200:203], v[196:199], v[0:15]
	ds_read_b128 v[212:215], v103 offset:64
	ds_read_b128 v[216:219], v104 offset:36928
	global_load_dwordx4 v[132:135], v180, s[98:99] offset:3840
	global_load_dwordx4 v[136:139], v182, s[98:99] offset:3840
	v_mfma_f32_32x32x16_bf16 v[48:63], v[148:151], v[192:195], v[48:63]
	ds_read_b128 v[220:223], v104 offset:41536
	s_waitcnt vmcnt(12)
	ds_write_b128 v105, v[88:91] offset:27648
	s_waitcnt lgkmcnt(7)
	v_mfma_f32_32x32x16_bf16 v[32:47], v[148:151], v[204:207], v[32:47]
	ds_read_b128 v[224:227], v103 offset:4672
	s_waitcnt lgkmcnt(6)
	v_mfma_f32_32x32x16_bf16 v[16:31], v[208:211], v[192:195], v[16:31]
	s_waitcnt vmcnt(11)
	ds_write_b128 v105, v[92:95] offset:32256
	v_mfma_f32_32x32x16_bf16 v[0:15], v[208:211], v[204:207], v[0:15]
	ds_read_b128 v[228:231], v103 offset:96
	ds_read_b128 v[140:143], v104 offset:36960
	s_waitcnt lgkmcnt(6)
	v_mfma_f32_32x32x16_bf16 v[48:63], v[212:215], v[216:219], v[48:63]
	ds_read_b128 v[144:147], v104 offset:41568
	ds_write_b128 v105, v[64:67] offset:55296
	s_waitcnt lgkmcnt(7)
	v_mfma_f32_32x32x16_bf16 v[32:47], v[212:215], v[220:223], v[32:47]
	ds_read_b128 v[196:199], v103 offset:4704
	s_waitcnt lgkmcnt(6)
	v_mfma_f32_32x32x16_bf16 v[16:31], v[224:227], v[216:219], v[16:31]
	s_waitcnt vmcnt(10)
	ds_write_b128 v105, v[72:75] offset:59904
	v_mfma_f32_32x32x16_bf16 v[0:15], v[224:227], v[220:223], v[0:15]
	s_waitcnt lgkmcnt(4)
	v_mfma_f32_32x32x16_bf16 v[48:63], v[228:231], v[140:143], v[48:63]
	s_waitcnt vmcnt(9)
	ds_write_b128 v105, v[76:79] offset:64512
	s_waitcnt lgkmcnt(4)
	v_mfma_f32_32x32x16_bf16 v[32:47], v[228:231], v[144:147], v[32:47]
	s_waitcnt lgkmcnt(2)
	v_mfma_f32_32x32x16_bf16 v[16:31], v[196:199], v[140:143], v[16:31]
	s_waitcnt vmcnt(8)
	ds_write_b128 v106, v[80:83] offset:13824
	v_mfma_f32_32x32x16_bf16 v[0:15], v[196:199], v[144:147], v[0:15]
	s_setprio 0
	s_waitcnt lgkmcnt(0)
	s_barrier
	s_setprio 1
	ds_read_b128 v[140:143], v103 offset:18432
	ds_read_b128 v[144:147], v104 offset:55296
	ds_read_b128 v[148:151], v103 offset:18464
	ds_read_b128 v[192:195], v104 offset:55328
	ds_read_b128 v[196:199], v104 offset:59904
	ds_read_b128 v[200:203], v103 offset:23040
	s_waitcnt lgkmcnt(4)
	v_mfma_f32_32x32x16_bf16 v[48:63], v[140:143], v[144:147], v[48:63]
	ds_read_b128 v[204:207], v104 offset:59936
	global_load_dwordx4 v[68:71], v168, s[98:99] offset:3968
	global_load_dwordx4 v[84:87], v170, s[98:99] offset:3968
	s_waitcnt vmcnt(9)
	ds_write_b128 v105, v[108:111]
	s_waitcnt lgkmcnt(3)
	v_mfma_f32_32x32x16_bf16 v[32:47], v[140:143], v[196:199], v[32:47]
	ds_read_b128 v[208:211], v103 offset:23072
	global_load_dwordx4 v[88:91], v172, s[98:99] offset:3968
	global_load_dwordx4 v[92:95], v174, s[98:99] offset:3968
	s_waitcnt lgkmcnt(3)
	v_mfma_f32_32x32x16_bf16 v[16:31], v[200:203], v[144:147], v[16:31]
	global_load_dwordx4 v[64:67], v176, s[98:99] offset:3968
	global_load_dwordx4 v[72:75], v178, s[98:99] offset:3968
	s_waitcnt vmcnt(12)
	ds_write_b128 v105, v[112:115] offset:4608
	v_mfma_f32_32x32x16_bf16 v[0:15], v[200:203], v[196:199], v[0:15]
	ds_read_b128 v[212:215], v103 offset:18496
	ds_read_b128 v[216:219], v104 offset:55360
	global_load_dwordx4 v[76:79], v180, s[98:99] offset:3968
	global_load_dwordx4 v[80:83], v182, s[98:99] offset:3968
	v_mfma_f32_32x32x16_bf16 v[48:63], v[148:151], v[192:195], v[48:63]
	ds_read_b128 v[220:223], v104 offset:59968
	s_add_u32 s98, s98, 0x100
	s_addc_u32 s99, s99, 0
	s_add_i32 s41, s41, 2
	s_cmp_lt_u32 s41, 11
	s_waitcnt vmcnt(13)
	ds_write_b128 v105, v[116:119] offset:9216
	s_waitcnt lgkmcnt(7)
	v_mfma_f32_32x32x16_bf16 v[32:47], v[148:151], v[204:207], v[32:47]
	ds_read_b128 v[224:227], v103 offset:23104
	s_waitcnt lgkmcnt(6)
	v_mfma_f32_32x32x16_bf16 v[16:31], v[208:211], v[192:195], v[16:31]
	s_waitcnt vmcnt(12)
	ds_write_b128 v105, v[120:123] offset:13824
	v_mfma_f32_32x32x16_bf16 v[0:15], v[208:211], v[204:207], v[0:15]
	ds_read_b128 v[228:231], v103 offset:18528
	ds_read_b128 v[140:143], v104 offset:55392
	s_waitcnt lgkmcnt(6)
	v_mfma_f32_32x32x16_bf16 v[48:63], v[212:215], v[216:219], v[48:63]
	ds_read_b128 v[144:147], v104 offset:60000
	s_waitcnt vmcnt(11)
	ds_write_b128 v105, v[124:127] offset:36864
	s_waitcnt lgkmcnt(7)
	v_mfma_f32_32x32x16_bf16 v[32:47], v[212:215], v[220:223], v[32:47]
	ds_read_b128 v[196:199], v103 offset:23136
	s_waitcnt lgkmcnt(6)
	v_mfma_f32_32x32x16_bf16 v[16:31], v[224:227], v[216:219], v[16:31]
	s_waitcnt vmcnt(10)
	ds_write_b128 v105, v[128:131] offset:41472
	v_mfma_f32_32x32x16_bf16 v[0:15], v[224:227], v[220:223], v[0:15]
	s_waitcnt lgkmcnt(4)
	v_mfma_f32_32x32x16_bf16 v[48:63], v[228:231], v[140:143], v[48:63]
	s_waitcnt vmcnt(9)
	ds_write_b128 v105, v[132:135] offset:46080
	s_waitcnt lgkmcnt(4)
	v_mfma_f32_32x32x16_bf16 v[32:47], v[228:231], v[144:147], v[32:47]
	s_waitcnt lgkmcnt(2)
	v_mfma_f32_32x32x16_bf16 v[16:31], v[196:199], v[140:143], v[16:31]
	s_waitcnt vmcnt(8)
	ds_write_b128 v105, v[136:139] offset:50688
	v_mfma_f32_32x32x16_bf16 v[0:15], v[196:199], v[144:147], v[0:15]
	s_setprio 0
	s_waitcnt lgkmcnt(0)
	s_barrier
	s_cbranch_scc1 .LBB0_1940
	s_setprio 1
	ds_read_b128 v[98:101], v103
	ds_read_b128 v[108:111], v104 offset:36864
	ds_read_b128 v[112:115], v103 offset:32
	ds_read_b128 v[192:195], v104 offset:36896
	ds_read_b128 v[196:199], v104 offset:41472
	ds_read_b128 v[200:203], v103 offset:4608
	s_waitcnt lgkmcnt(4)
	v_mfma_f32_32x32x16_bf16 v[48:63], v[98:101], v[108:111], v[48:63]
	ds_read_b128 v[204:207], v104 offset:41504
	s_waitcnt vmcnt(7)
	ds_write_b128 v105, v[68:71] offset:18432
	s_waitcnt lgkmcnt(3)
	v_mfma_f32_32x32x16_bf16 v[32:47], v[98:101], v[196:199], v[32:47]
	ds_read_b128 v[208:211], v103 offset:4640
	s_waitcnt lgkmcnt(3)
	v_mfma_f32_32x32x16_bf16 v[16:31], v[200:203], v[108:111], v[16:31]
	s_waitcnt vmcnt(6)
	ds_write_b128 v105, v[84:87] offset:23040
	v_mfma_f32_32x32x16_bf16 v[0:15], v[200:203], v[196:199], v[0:15]
	ds_read_b128 v[212:215], v103 offset:64
	ds_read_b128 v[216:219], v104 offset:36928
	v_mfma_f32_32x32x16_bf16 v[48:63], v[112:115], v[192:195], v[48:63]
	ds_read_b128 v[220:223], v104 offset:41536
	s_waitcnt vmcnt(5)
	ds_write_b128 v105, v[88:91] offset:27648
	s_waitcnt lgkmcnt(7)
	v_mfma_f32_32x32x16_bf16 v[32:47], v[112:115], v[204:207], v[32:47]
	ds_read_b128 v[224:227], v103 offset:4672
	s_waitcnt lgkmcnt(6)
	v_mfma_f32_32x32x16_bf16 v[16:31], v[208:211], v[192:195], v[16:31]
	s_waitcnt vmcnt(4)
	ds_write_b128 v105, v[92:95] offset:32256
	v_mfma_f32_32x32x16_bf16 v[0:15], v[208:211], v[204:207], v[0:15]
	ds_read_b128 v[228:231], v103 offset:96
	ds_read_b128 v[98:101], v104 offset:36960
	s_waitcnt lgkmcnt(6)
	v_mfma_f32_32x32x16_bf16 v[48:63], v[212:215], v[216:219], v[48:63]
	ds_read_b128 v[108:111], v104 offset:41568
	s_waitcnt vmcnt(3)
	ds_write_b128 v105, v[64:67] offset:55296
	s_waitcnt lgkmcnt(7)
	v_mfma_f32_32x32x16_bf16 v[32:47], v[212:215], v[220:223], v[32:47]
	ds_read_b128 v[196:199], v103 offset:4704
	s_waitcnt lgkmcnt(6)
	v_mfma_f32_32x32x16_bf16 v[16:31], v[224:227], v[216:219], v[16:31]
	s_waitcnt vmcnt(2)
	ds_write_b128 v105, v[72:75] offset:59904
	v_mfma_f32_32x32x16_bf16 v[0:15], v[224:227], v[220:223], v[0:15]
	s_waitcnt lgkmcnt(4)
	v_mfma_f32_32x32x16_bf16 v[48:63], v[228:231], v[98:101], v[48:63]
	s_waitcnt vmcnt(1)
	ds_write_b128 v105, v[76:79] offset:64512
	s_waitcnt lgkmcnt(4)
	v_mfma_f32_32x32x16_bf16 v[32:47], v[228:231], v[108:111], v[32:47]
	s_waitcnt lgkmcnt(2)
	v_mfma_f32_32x32x16_bf16 v[16:31], v[196:199], v[98:101], v[16:31]
	s_waitcnt vmcnt(0)
	ds_write_b128 v106, v[80:83] offset:13824
	v_mfma_f32_32x32x16_bf16 v[0:15], v[196:199], v[108:111], v[0:15]
	s_setprio 0
	s_waitcnt lgkmcnt(0)
	s_barrier
	s_setprio 1
	ds_read_b128 v[64:67], v103 offset:18432
	ds_read_b128 v[68:71], v104 offset:55296
	ds_read_b128 v[72:75], v103 offset:18464
	ds_read_b128 v[192:195], v104 offset:55328
	ds_read_b128 v[196:199], v104 offset:59904
	ds_read_b128 v[200:203], v103 offset:23040
	s_waitcnt lgkmcnt(4)
	v_mfma_f32_32x32x16_bf16 v[48:63], v[64:67], v[68:71], v[48:63]
	ds_read_b128 v[204:207], v104 offset:59936
	s_waitcnt lgkmcnt(2)
	v_mfma_f32_32x32x16_bf16 v[32:47], v[64:67], v[196:199], v[32:47]
	ds_read_b128 v[208:211], v103 offset:23072
	s_waitcnt lgkmcnt(2)
	v_mfma_f32_32x32x16_bf16 v[16:31], v[200:203], v[68:71], v[16:31]
	v_mfma_f32_32x32x16_bf16 v[0:15], v[200:203], v[196:199], v[0:15]
	ds_read_b128 v[212:215], v103 offset:18496
	ds_read_b128 v[216:219], v104 offset:55360
	v_mfma_f32_32x32x16_bf16 v[48:63], v[72:75], v[192:195], v[48:63]
	ds_read_b128 v[220:223], v104 offset:59968
	s_waitcnt lgkmcnt(4)
	v_mfma_f32_32x32x16_bf16 v[32:47], v[72:75], v[204:207], v[32:47]
	ds_read_b128 v[224:227], v103 offset:23104
	s_waitcnt lgkmcnt(4)
	v_mfma_f32_32x32x16_bf16 v[16:31], v[208:211], v[192:195], v[16:31]
	v_mfma_f32_32x32x16_bf16 v[0:15], v[208:211], v[204:207], v[0:15]
	ds_read_b128 v[228:231], v103 offset:18528
	ds_read_b128 v[64:67], v104 offset:55392
	s_waitcnt lgkmcnt(4)
	v_mfma_f32_32x32x16_bf16 v[48:63], v[212:215], v[216:219], v[48:63]
	ds_read_b128 v[68:71], v104 offset:60000
	s_waitcnt lgkmcnt(4)
	v_mfma_f32_32x32x16_bf16 v[32:47], v[212:215], v[220:223], v[32:47]
	ds_read_b128 v[196:199], v103 offset:23136
	s_waitcnt lgkmcnt(4)
	v_mfma_f32_32x32x16_bf16 v[16:31], v[224:227], v[216:219], v[16:31]
	v_mfma_f32_32x32x16_bf16 v[0:15], v[224:227], v[220:223], v[0:15]
	s_waitcnt lgkmcnt(2)
	v_mfma_f32_32x32x16_bf16 v[48:63], v[228:231], v[64:67], v[48:63]
	s_waitcnt lgkmcnt(1)
	v_mfma_f32_32x32x16_bf16 v[32:47], v[228:231], v[68:71], v[32:47]
	s_waitcnt lgkmcnt(0)
	v_mfma_f32_32x32x16_bf16 v[16:31], v[196:199], v[64:67], v[16:31]
	v_mfma_f32_32x32x16_bf16 v[0:15], v[196:199], v[68:71], v[0:15]
	s_setprio 0
	v_lshrrev_b32_e32 v65, 3, v102
	v_lshrrev_b32_e32 v64, 1, v102
	v_and_b32_e32 v65, 4, v65
	v_and_or_b32 v64, v64, s22, v65
	v_and_b32_e32 v65, 0x5f, v102
	v_lshlrev_b32_e32 v65, 1, v65
	v_mul_lo_u32 v64, v64, s36
	v_add3_u32 v64, 32, v65, v64
	s_nop 2
	v_cvt_pk_bf16_f32 v0, v0, s0
	s_barrier
	ds_write_b16 v64, v0 offset:8768
	v_cvt_pk_bf16_f32 v0, v17, s0
	ds_write_b16 v64, v0 offset:8976
	v_cvt_pk_bf16_f32 v0, v1, s0
	ds_write_b16 v64, v0 offset:9040
	v_cvt_pk_bf16_f32 v0, v18, s0
	v_cvt_pk_bf16_f32 v32, v32, s0
	ds_write_b16 v64, v0 offset:9248
	v_cvt_pk_bf16_f32 v0, v2, s0
	ds_write_b16 v64, v32 offset:64
	v_cvt_pk_bf16_f32 v32, v49, s0
	ds_write_b16 v64, v0 offset:9312
	v_cvt_pk_bf16_f32 v0, v19, s0
	ds_write_b16 v64, v32 offset:272
	v_cvt_pk_bf16_f32 v32, v33, s0
	ds_write_b16 v64, v0 offset:9520
	v_cvt_pk_bf16_f32 v0, v3, s0
	ds_write_b16 v64, v32 offset:336
	v_cvt_pk_bf16_f32 v32, v50, s0
	ds_write_b16 v64, v0 offset:9584
	v_cvt_pk_bf16_f32 v0, v20, s0
	ds_write_b16 v64, v32 offset:544
	v_cvt_pk_bf16_f32 v32, v34, s0
	ds_write_b16 v64, v0 offset:10880
	v_cvt_pk_bf16_f32 v0, v4, s0
	ds_write_b16 v64, v32 offset:608
	v_cvt_pk_bf16_f32 v32, v51, s0
	ds_write_b16 v64, v0 offset:10944
	v_cvt_pk_bf16_f32 v0, v21, s0
	ds_write_b16 v64, v32 offset:816
	v_cvt_pk_bf16_f32 v32, v35, s0
	ds_write_b16 v64, v0 offset:11152
	v_cvt_pk_bf16_f32 v0, v5, s0
	ds_write_b16 v64, v32 offset:880
	v_cvt_pk_bf16_f32 v32, v52, s0
	ds_write_b16 v64, v0 offset:11216
	v_cvt_pk_bf16_f32 v0, v22, s0
	ds_write_b16 v64, v32 offset:2176
	v_cvt_pk_bf16_f32 v32, v36, s0
	ds_write_b16 v64, v0 offset:11424
	v_cvt_pk_bf16_f32 v0, v6, s0
	ds_write_b16 v64, v32 offset:2240
	v_cvt_pk_bf16_f32 v32, v53, s0
	ds_write_b16 v64, v0 offset:11488
	v_cvt_pk_bf16_f32 v0, v23, s0
	ds_write_b16 v64, v32 offset:2448
	v_cvt_pk_bf16_f32 v32, v37, s0
	ds_write_b16 v64, v0 offset:11696
	v_cvt_pk_bf16_f32 v0, v7, s0
	ds_write_b16 v64, v32 offset:2512
	v_cvt_pk_bf16_f32 v32, v54, s0
	ds_write_b16 v64, v0 offset:11760
	v_cvt_pk_bf16_f32 v0, v24, s0
	ds_write_b16 v64, v32 offset:2720
	v_cvt_pk_bf16_f32 v32, v38, s0
	ds_write_b16 v64, v0 offset:13056
	v_cvt_pk_bf16_f32 v0, v8, s0
	ds_write_b16 v64, v32 offset:2784
	v_cvt_pk_bf16_f32 v32, v55, s0
	ds_write_b16 v64, v0 offset:13120
	v_cvt_pk_bf16_f32 v0, v25, s0
	ds_write_b16 v64, v32 offset:2992
	v_cvt_pk_bf16_f32 v32, v39, s0
	ds_write_b16 v64, v0 offset:13328
	v_cvt_pk_bf16_f32 v0, v9, s0
	ds_write_b16 v64, v32 offset:3056
	v_cvt_pk_bf16_f32 v32, v56, s0
	ds_write_b16 v64, v0 offset:13392
	v_cvt_pk_bf16_f32 v0, v26, s0
	ds_write_b16 v64, v32 offset:4352
	v_cvt_pk_bf16_f32 v32, v40, s0
	ds_write_b16 v64, v0 offset:13600
	v_cvt_pk_bf16_f32 v0, v10, s0
	ds_write_b16 v64, v32 offset:4416
	v_cvt_pk_bf16_f32 v32, v57, s0
	ds_write_b16 v64, v0 offset:13664
	v_cvt_pk_bf16_f32 v0, v27, s0
	ds_write_b16 v64, v32 offset:4624
	v_cvt_pk_bf16_f32 v32, v41, s0
	ds_write_b16 v64, v0 offset:13872
	v_cvt_pk_bf16_f32 v0, v11, s0
	ds_write_b16 v64, v32 offset:4688
	v_cvt_pk_bf16_f32 v32, v58, s0
	ds_write_b16 v64, v0 offset:13936
	v_cvt_pk_bf16_f32 v0, v28, s0
	ds_write_b16 v64, v32 offset:4896
	v_cvt_pk_bf16_f32 v32, v42, s0
	ds_write_b16 v64, v0 offset:15232
	v_cvt_pk_bf16_f32 v0, v12, s0
	ds_write_b16 v64, v32 offset:4960
	v_cvt_pk_bf16_f32 v32, v59, s0
	ds_write_b16 v64, v0 offset:15296
	v_cvt_pk_bf16_f32 v0, v29, s0
	ds_write_b16 v64, v32 offset:5168
	v_cvt_pk_bf16_f32 v32, v43, s0
	ds_write_b16 v64, v0 offset:15504
	v_cvt_pk_bf16_f32 v0, v13, s0
	ds_write_b16 v64, v32 offset:5232
	v_cvt_pk_bf16_f32 v32, v60, s0
	ds_write_b16 v64, v0 offset:15568
	v_cvt_pk_bf16_f32 v0, v30, s0
	ds_write_b16 v64, v32 offset:6528
	v_cvt_pk_bf16_f32 v32, v44, s0
	ds_write_b16 v64, v0 offset:15776
	v_cvt_pk_bf16_f32 v0, v14, s0
	s_mul_i32 s11, s11, 0x160000
	ds_write_b16 v64, v32 offset:6592
	v_cvt_pk_bf16_f32 v32, v61, s0
	ds_write_b16 v64, v0 offset:15840
	v_cvt_pk_bf16_f32 v0, v31, s0
	s_add_u32 s41, s13, s11
	ds_write_b16 v64, v32 offset:6800
	v_cvt_pk_bf16_f32 v32, v45, s0
	ds_write_b16 v64, v0 offset:16048
	v_cvt_pk_bf16_f32 v0, v15, s0
	s_addc_u32 s44, s14, 0
	s_ashr_i32 s11, s10, 31
	ds_write_b16 v64, v32 offset:6864
	v_cvt_pk_bf16_f32 v32, v62, s0
	ds_write_b16 v64, v0 offset:16112
	s_lshl_b64 s[10:11], s[10:11], 1
	v_lshlrev_b32_e32 v0, 4, v102
	ds_write_b16 v64, v32 offset:7072
	v_cvt_pk_bf16_f32 v32, v46, s0
	s_add_u32 s10, s41, s10
	v_and_b32_e32 v96, 0xf0, v0
	ds_write_b16 v64, v32 offset:7136
	v_cvt_pk_bf16_f32 v32, v63, s0
	s_addc_u32 s11, s44, s11
	v_add_u32_e32 v8, 32, v96
	v_ashrrev_i32_e32 v9, 4, v102
	v_add_u32_e32 v4, 0x100, v102
	v_cvt_pk_bf16_f32 v48, v48, s0
	ds_write_b16 v64, v32 offset:7344
	v_cvt_pk_bf16_f32 v32, v47, s0
	v_cvt_pk_bf16_f32 v16, v16, s0
	v_lshl_add_u64 v[10:11], s[10:11], 0, v[96:97]
	v_mad_u64_u32 v[0:1], s[10:11], v9, s36, v[8:9]
	v_ashrrev_i32_e32 v14, 4, v4
	ds_write_b16 v64, v48
	ds_write_b16 v64, v32 offset:7408
	ds_write_b16 v64, v16 offset:8704
	s_waitcnt lgkmcnt(0)
	s_barrier
	ds_read_b128 v[0:3], v0
	v_mad_u64_u32 v[4:5], s[10:11], v14, s36, v[8:9]
	ds_read_b128 v[4:7], v4
	v_mad_i64_i32 v[12:13], s[10:11], v9, s37, v[10:11]
	s_waitcnt lgkmcnt(1)
	global_store_dwordx4 v[12:13], v[0:3], off
	s_nop 1
	v_mad_i64_i32 v[0:1], s[10:11], v14, s37, v[10:11]
	s_waitcnt lgkmcnt(0)
	global_store_dwordx4 v[0:1], v[4:7], off
	v_add_u32_e32 v0, 0x200, v102
	v_ashrrev_i32_e32 v9, 4, v0
	v_add_u32_e32 v4, 0x300, v102
	v_mad_u64_u32 v[0:1], s[10:11], v9, s36, v[8:9]
	v_ashrrev_i32_e32 v14, 4, v4
	ds_read_b128 v[0:3], v0
	v_mad_u64_u32 v[4:5], s[10:11], v14, s36, v[8:9]
	ds_read_b128 v[4:7], v4
	v_mad_i64_i32 v[12:13], s[10:11], v9, s37, v[10:11]
	s_waitcnt lgkmcnt(1)
	global_store_dwordx4 v[12:13], v[0:3], off
	s_nop 1
	v_mad_i64_i32 v[0:1], s[10:11], v14, s37, v[10:11]
	s_waitcnt lgkmcnt(0)
	global_store_dwordx4 v[0:1], v[4:7], off
	v_add_u32_e32 v0, 0x400, v102
	v_ashrrev_i32_e32 v9, 4, v0
	v_add_u32_e32 v4, 0x500, v102
	v_mad_u64_u32 v[0:1], s[10:11], v9, s36, v[8:9]
	v_ashrrev_i32_e32 v14, 4, v4
	ds_read_b128 v[0:3], v0
	v_mad_u64_u32 v[4:5], s[10:11], v14, s36, v[8:9]
	ds_read_b128 v[4:7], v4
	v_mad_i64_i32 v[12:13], s[10:11], v9, s37, v[10:11]
	s_waitcnt lgkmcnt(1)
	global_store_dwordx4 v[12:13], v[0:3], off
	s_nop 1
	v_mad_i64_i32 v[0:1], s[10:11], v14, s37, v[10:11]
	s_waitcnt lgkmcnt(0)
	global_store_dwordx4 v[0:1], v[4:7], off
	v_add_u32_e32 v0, 0x600, v102
	v_ashrrev_i32_e32 v9, 4, v0
	v_add_u32_e32 v4, 0x700, v102
	v_mad_u64_u32 v[0:1], s[10:11], v9, s36, v[8:9]
	v_ashrrev_i32_e32 v12, 4, v4
	ds_read_b128 v[0:3], v0
	v_mad_u64_u32 v[4:5], s[10:11], v12, s36, v[8:9]
	ds_read_b128 v[4:7], v4
	v_mad_i64_i32 v[8:9], s[10:11], v9, s37, v[10:11]
	s_waitcnt lgkmcnt(1)
	global_store_dwordx4 v[8:9], v[0:3], off
	s_nop 1
	v_mad_i64_i32 v[0:1], s[10:11], v12, s37, v[10:11]
	s_waitcnt lgkmcnt(0)
	global_store_dwordx4 v[0:1], v[4:7], off
	s_branch .LBB0_1937

.LBB0_2062:
	s_setprio 1
	ds_read_b128 v[146:149], v109
	ds_read_b128 v[150:153], v110 offset:36864
	ds_read_b128 v[154:157], v109 offset:32
	ds_read_b128 v[192:195], v110 offset:36896
	ds_read_b128 v[196:199], v110 offset:41472
	ds_read_b128 v[200:203], v109 offset:4608
	s_waitcnt lgkmcnt(4)
	v_mfma_f32_32x32x16_bf16 v[32:47], v[146:149], v[150:153], v[32:47]
	ds_read_b128 v[204:207], v110 offset:41504
	global_load_dwordx4 v[114:117], v174, s[98:99] offset:3840
	global_load_dwordx4 v[118:121], v176, s[98:99] offset:3840
	s_waitcnt vmcnt(9)
	ds_write_b128 v111, v[68:71] offset:18432
	s_waitcnt lgkmcnt(3)
	v_mfma_f32_32x32x16_bf16 v[48:63], v[146:149], v[196:199], v[48:63]
	ds_read_b128 v[208:211], v109 offset:4640
	global_load_dwordx4 v[122:125], v178, s[98:99] offset:3840
	global_load_dwordx4 v[126:129], v180, s[98:99] offset:3840
	s_waitcnt lgkmcnt(3)
	v_mfma_f32_32x32x16_bf16 v[16:31], v[200:203], v[150:153], v[16:31]
	global_load_dwordx4 v[130:133], v182, s[98:99] offset:3840
	global_load_dwordx4 v[134:137], v184, s[98:99] offset:3840
	s_waitcnt vmcnt(11)
	ds_write_b128 v111, v[84:87] offset:23040
	v_mfma_f32_32x32x16_bf16 v[0:15], v[200:203], v[196:199], v[0:15]
	ds_read_b128 v[212:215], v109 offset:64
	ds_read_b128 v[216:219], v110 offset:36928
	global_load_dwordx4 v[138:141], v186, s[98:99] offset:3840
	global_load_dwordx4 v[142:145], v188, s[98:99] offset:3840
	v_mfma_f32_32x32x16_bf16 v[32:47], v[154:157], v[192:195], v[32:47]
	ds_read_b128 v[220:223], v110 offset:41536
	s_waitcnt vmcnt(12)
	ds_write_b128 v111, v[88:91] offset:27648
	s_waitcnt lgkmcnt(7)
	v_mfma_f32_32x32x16_bf16 v[48:63], v[154:157], v[204:207], v[48:63]
	ds_read_b128 v[224:227], v109 offset:4672
	s_waitcnt lgkmcnt(6)
	v_mfma_f32_32x32x16_bf16 v[16:31], v[208:211], v[192:195], v[16:31]
	s_waitcnt vmcnt(11)
	ds_write_b128 v111, v[92:95] offset:32256
	v_mfma_f32_32x32x16_bf16 v[0:15], v[208:211], v[204:207], v[0:15]
	ds_read_b128 v[228:231], v109 offset:96
	ds_read_b128 v[146:149], v110 offset:36960
	s_waitcnt lgkmcnt(6)
	v_mfma_f32_32x32x16_bf16 v[32:47], v[212:215], v[216:219], v[32:47]
	ds_read_b128 v[150:153], v110 offset:41568
	ds_write_b128 v111, v[64:67] offset:55296
	s_waitcnt lgkmcnt(7)
	v_mfma_f32_32x32x16_bf16 v[48:63], v[212:215], v[220:223], v[48:63]
	ds_read_b128 v[196:199], v109 offset:4704
	s_waitcnt lgkmcnt(6)
	v_mfma_f32_32x32x16_bf16 v[16:31], v[224:227], v[216:219], v[16:31]
	s_waitcnt vmcnt(10)
	ds_write_b128 v111, v[72:75] offset:59904
	v_mfma_f32_32x32x16_bf16 v[0:15], v[224:227], v[220:223], v[0:15]
	s_waitcnt lgkmcnt(4)
	v_mfma_f32_32x32x16_bf16 v[32:47], v[228:231], v[146:149], v[32:47]
	s_waitcnt vmcnt(9)
	ds_write_b128 v111, v[76:79] offset:64512
	s_waitcnt lgkmcnt(4)
	v_mfma_f32_32x32x16_bf16 v[48:63], v[228:231], v[150:153], v[48:63]
	s_waitcnt lgkmcnt(2)
	v_mfma_f32_32x32x16_bf16 v[16:31], v[196:199], v[146:149], v[16:31]
	s_waitcnt vmcnt(8)
	ds_write_b128 v112, v[80:83] offset:13824
	v_mfma_f32_32x32x16_bf16 v[0:15], v[196:199], v[150:153], v[0:15]
	s_setprio 0
	s_waitcnt lgkmcnt(0)
	s_barrier
	s_setprio 1
	ds_read_b128 v[146:149], v109 offset:18432
	ds_read_b128 v[150:153], v110 offset:55296
	ds_read_b128 v[154:157], v109 offset:18464
	ds_read_b128 v[192:195], v110 offset:55328
	ds_read_b128 v[196:199], v110 offset:59904
	ds_read_b128 v[200:203], v109 offset:23040
	s_waitcnt lgkmcnt(4)
	v_mfma_f32_32x32x16_bf16 v[32:47], v[146:149], v[150:153], v[32:47]
	ds_read_b128 v[204:207], v110 offset:59936
	global_load_dwordx4 v[68:71], v174, s[98:99] offset:3968
	global_load_dwordx4 v[84:87], v176, s[98:99] offset:3968
	s_waitcnt vmcnt(9)
	ds_write_b128 v111, v[114:117]
	s_waitcnt lgkmcnt(3)
	v_mfma_f32_32x32x16_bf16 v[48:63], v[146:149], v[196:199], v[48:63]
	ds_read_b128 v[208:211], v109 offset:23072
	global_load_dwordx4 v[88:91], v178, s[98:99] offset:3968
	global_load_dwordx4 v[92:95], v180, s[98:99] offset:3968
	s_waitcnt lgkmcnt(3)
	v_mfma_f32_32x32x16_bf16 v[16:31], v[200:203], v[150:153], v[16:31]
	global_load_dwordx4 v[64:67], v182, s[98:99] offset:3968
	global_load_dwordx4 v[72:75], v184, s[98:99] offset:3968
	s_waitcnt vmcnt(12)
	ds_write_b128 v111, v[118:121] offset:4608
	v_mfma_f32_32x32x16_bf16 v[0:15], v[200:203], v[196:199], v[0:15]
	ds_read_b128 v[212:215], v109 offset:18496
	ds_read_b128 v[216:219], v110 offset:55360
	global_load_dwordx4 v[76:79], v186, s[98:99] offset:3968
	global_load_dwordx4 v[80:83], v188, s[98:99] offset:3968
	v_mfma_f32_32x32x16_bf16 v[32:47], v[154:157], v[192:195], v[32:47]
	ds_read_b128 v[220:223], v110 offset:59968
	s_add_u32 s98, s98, 0x100
	s_addc_u32 s99, s99, 0
	s_add_i32 s8, s8, 2
	s_cmp_lt_u32 s8, 39
	s_waitcnt vmcnt(13)
	ds_write_b128 v111, v[122:125] offset:9216
	s_waitcnt lgkmcnt(7)
	v_mfma_f32_32x32x16_bf16 v[48:63], v[154:157], v[204:207], v[48:63]
	ds_read_b128 v[224:227], v109 offset:23104
	s_waitcnt lgkmcnt(6)
	v_mfma_f32_32x32x16_bf16 v[16:31], v[208:211], v[192:195], v[16:31]
	s_waitcnt vmcnt(12)
	ds_write_b128 v111, v[126:129] offset:13824
	v_mfma_f32_32x32x16_bf16 v[0:15], v[208:211], v[204:207], v[0:15]
	ds_read_b128 v[228:231], v109 offset:18528
	ds_read_b128 v[146:149], v110 offset:55392
	s_waitcnt lgkmcnt(6)
	v_mfma_f32_32x32x16_bf16 v[32:47], v[212:215], v[216:219], v[32:47]
	ds_read_b128 v[150:153], v110 offset:60000
	s_waitcnt vmcnt(11)
	ds_write_b128 v111, v[130:133] offset:36864
	s_waitcnt lgkmcnt(7)
	v_mfma_f32_32x32x16_bf16 v[48:63], v[212:215], v[220:223], v[48:63]
	ds_read_b128 v[196:199], v109 offset:23136
	s_waitcnt lgkmcnt(6)
	v_mfma_f32_32x32x16_bf16 v[16:31], v[224:227], v[216:219], v[16:31]
	s_waitcnt vmcnt(10)
	ds_write_b128 v111, v[134:137] offset:41472
	v_mfma_f32_32x32x16_bf16 v[0:15], v[224:227], v[220:223], v[0:15]
	s_waitcnt lgkmcnt(4)
	v_mfma_f32_32x32x16_bf16 v[32:47], v[228:231], v[146:149], v[32:47]
	s_waitcnt vmcnt(9)
	ds_write_b128 v111, v[138:141] offset:46080
	s_waitcnt lgkmcnt(4)
	v_mfma_f32_32x32x16_bf16 v[48:63], v[228:231], v[150:153], v[48:63]
	s_waitcnt lgkmcnt(2)
	v_mfma_f32_32x32x16_bf16 v[16:31], v[196:199], v[146:149], v[16:31]
	s_waitcnt vmcnt(8)
	ds_write_b128 v111, v[142:145] offset:50688
	v_mfma_f32_32x32x16_bf16 v[0:15], v[196:199], v[150:153], v[0:15]
	s_setprio 0
	s_waitcnt lgkmcnt(0)
	s_barrier
	s_cbranch_scc1 .LBB0_2062
	s_setprio 1
	ds_read_b128 v[104:107], v109
	ds_read_b128 v[114:117], v110 offset:36864
	ds_read_b128 v[118:121], v109 offset:32
	ds_read_b128 v[192:195], v110 offset:36896
	ds_read_b128 v[196:199], v110 offset:41472
	ds_read_b128 v[200:203], v109 offset:4608
	s_waitcnt lgkmcnt(4)
	v_mfma_f32_32x32x16_bf16 v[32:47], v[104:107], v[114:117], v[32:47]
	ds_read_b128 v[204:207], v110 offset:41504
	s_waitcnt vmcnt(7)
	ds_write_b128 v111, v[68:71] offset:18432
	s_waitcnt lgkmcnt(3)
	v_mfma_f32_32x32x16_bf16 v[48:63], v[104:107], v[196:199], v[48:63]
	ds_read_b128 v[208:211], v109 offset:4640
	s_waitcnt lgkmcnt(3)
	v_mfma_f32_32x32x16_bf16 v[16:31], v[200:203], v[114:117], v[16:31]
	s_waitcnt vmcnt(6)
	ds_write_b128 v111, v[84:87] offset:23040
	v_mfma_f32_32x32x16_bf16 v[0:15], v[200:203], v[196:199], v[0:15]
	ds_read_b128 v[212:215], v109 offset:64
	ds_read_b128 v[216:219], v110 offset:36928
	v_mfma_f32_32x32x16_bf16 v[32:47], v[118:121], v[192:195], v[32:47]
	ds_read_b128 v[220:223], v110 offset:41536
	s_waitcnt vmcnt(5)
	ds_write_b128 v111, v[88:91] offset:27648
	s_waitcnt lgkmcnt(7)
	v_mfma_f32_32x32x16_bf16 v[48:63], v[118:121], v[204:207], v[48:63]
	ds_read_b128 v[224:227], v109 offset:4672
	s_waitcnt lgkmcnt(6)
	v_mfma_f32_32x32x16_bf16 v[16:31], v[208:211], v[192:195], v[16:31]
	s_waitcnt vmcnt(4)
	ds_write_b128 v111, v[92:95] offset:32256
	v_mfma_f32_32x32x16_bf16 v[0:15], v[208:211], v[204:207], v[0:15]
	ds_read_b128 v[228:231], v109 offset:96
	ds_read_b128 v[104:107], v110 offset:36960
	s_waitcnt lgkmcnt(6)
	v_mfma_f32_32x32x16_bf16 v[32:47], v[212:215], v[216:219], v[32:47]
	ds_read_b128 v[114:117], v109 offset:4704
	s_waitcnt vmcnt(3)
	ds_write_b128 v111, v[64:67] offset:55296
	s_waitcnt lgkmcnt(7)
	v_mfma_f32_32x32x16_bf16 v[48:63], v[212:215], v[220:223], v[48:63]
	ds_read_b128 v[196:199], v110 offset:41568
	s_waitcnt lgkmcnt(6)
	v_mfma_f32_32x32x16_bf16 v[16:31], v[224:227], v[216:219], v[16:31]
	s_waitcnt vmcnt(2)
	ds_write_b128 v111, v[72:75] offset:59904
	v_mfma_f32_32x32x16_bf16 v[0:15], v[224:227], v[220:223], v[0:15]
	s_waitcnt lgkmcnt(4)
	v_mfma_f32_32x32x16_bf16 v[32:47], v[228:231], v[104:107], v[32:47]
	s_waitcnt vmcnt(1)
	ds_write_b128 v111, v[76:79] offset:64512
	s_waitcnt lgkmcnt(4)
	v_mfma_f32_32x32x16_bf16 v[16:31], v[114:117], v[104:107], v[16:31]
	s_waitcnt lgkmcnt(2)
	v_mfma_f32_32x32x16_bf16 v[0:15], v[114:117], v[196:199], v[0:15]
	s_waitcnt vmcnt(0)
	ds_write_b128 v112, v[80:83] offset:13824
	v_mfma_f32_32x32x16_bf16 v[48:63], v[228:231], v[196:199], v[48:63]
	s_setprio 0
	s_waitcnt lgkmcnt(0)
	s_barrier
	s_setprio 1
	ds_read_b128 v[64:67], v109 offset:18432
	ds_read_b128 v[68:71], v110 offset:55296
	ds_read_b128 v[72:75], v109 offset:18464
	ds_read_b128 v[192:195], v110 offset:55328
	ds_read_b128 v[196:199], v110 offset:59904
	ds_read_b128 v[200:203], v109 offset:23040
	s_waitcnt lgkmcnt(4)
	v_mfma_f32_32x32x16_bf16 v[32:47], v[64:67], v[68:71], v[32:47]
	ds_read_b128 v[204:207], v110 offset:59936
	s_waitcnt lgkmcnt(2)
	v_mfma_f32_32x32x16_bf16 v[48:63], v[64:67], v[196:199], v[48:63]
	ds_read_b128 v[208:211], v109 offset:23072
	s_waitcnt lgkmcnt(2)
	v_mfma_f32_32x32x16_bf16 v[16:31], v[200:203], v[68:71], v[16:31]
	v_mfma_f32_32x32x16_bf16 v[0:15], v[200:203], v[196:199], v[0:15]
	ds_read_b128 v[212:215], v109 offset:18496
	ds_read_b128 v[216:219], v110 offset:55360
	v_mfma_f32_32x32x16_bf16 v[32:47], v[72:75], v[192:195], v[32:47]
	ds_read_b128 v[220:223], v110 offset:59968
	s_waitcnt lgkmcnt(4)
	v_mfma_f32_32x32x16_bf16 v[48:63], v[72:75], v[204:207], v[48:63]
	ds_read_b128 v[224:227], v109 offset:23104
	s_waitcnt lgkmcnt(4)
	v_mfma_f32_32x32x16_bf16 v[16:31], v[208:211], v[192:195], v[16:31]
	v_mfma_f32_32x32x16_bf16 v[0:15], v[208:211], v[204:207], v[0:15]
	ds_read_b128 v[228:231], v109 offset:18528
	ds_read_b128 v[64:67], v110 offset:55392
	s_waitcnt lgkmcnt(4)
	v_mfma_f32_32x32x16_bf16 v[32:47], v[212:215], v[216:219], v[32:47]
	ds_read_b128 v[68:71], v109 offset:23136
	s_waitcnt lgkmcnt(4)
	v_mfma_f32_32x32x16_bf16 v[48:63], v[212:215], v[220:223], v[48:63]
	ds_read_b128 v[196:199], v110 offset:60000
	s_waitcnt lgkmcnt(4)
	v_mfma_f32_32x32x16_bf16 v[16:31], v[224:227], v[216:219], v[16:31]
	v_mfma_f32_32x32x16_bf16 v[0:15], v[224:227], v[220:223], v[0:15]
	s_waitcnt lgkmcnt(2)
	v_mfma_f32_32x32x16_bf16 v[32:47], v[228:231], v[64:67], v[32:47]
	s_waitcnt lgkmcnt(1)
	v_mfma_f32_32x32x16_bf16 v[16:31], v[68:71], v[64:67], v[16:31]
	s_waitcnt lgkmcnt(0)
	v_mfma_f32_32x32x16_bf16 v[0:15], v[68:71], v[196:199], v[0:15]
	v_mfma_f32_32x32x16_bf16 v[48:63], v[228:231], v[196:199], v[48:63]
	s_setprio 0
	s_addk_i32 s0, 0xf000
	s_lshr_b32 s8, s0, 10
	s_mulk_i32 s8, 0x1800
	s_addk_i32 s8, 0x1800
	s_and_b64 s[58:59], s[4:5], exec
	s_cselect_b32 s8, 0, s8
	v_mov_b32_e32 v68, v234
	s_barrier
	s_lshl_b64 s[58:59], s[8:9], 2
	s_add_u32 s58, s30, s58
	v_and_b32_e32 v69, 0x5f, v68
	v_or_b32_e32 v64, s23, v69
	s_addc_u32 s59, s31, s59
	v_ashrrev_i32_e32 v65, 31, v64
	v_lshl_add_u64 v[64:65], v[64:65], 2, s[58:59]
	v_lshl_add_u64 v[66:67], v[64:65], 0, s[12:13]
	v_add_co_u32_e32 v64, vcc, s51, v64
	global_load_dword v66, v[66:67], off offset:128
	s_nop 0
	v_addc_co_u32_e32 v65, vcc, 0, v65, vcc
	global_load_dword v64, v[64:65], off
	v_lshrrev_b32_e32 v67, 3, v68
	v_lshrrev_b32_e32 v65, 1, v68
	v_and_b32_e32 v67, 4, v67
	v_and_or_b32 v65, v65, s45, v67
	v_lshlrev_b32_e32 v69, 2, v69
	v_mul_lo_u32 v65, v65, s52
	v_add3_u32 v65, 32, v69, v65
	v_add_u32_e32 v67, 0x400, v65
	v_add_u32_e32 v69, 0x1000, v65
	v_add_u32_e32 v70, 0x1400, v65
	v_add_u32_e32 v71, 0x2000, v65
	v_add_u32_e32 v72, 0x2400, v65
	v_add_u32_e32 v73, 0x3000, v65
	v_add_u32_e32 v74, 0x3200, v65
	v_add_u32_e32 v75, 0x3400, v65
	v_add_u32_e32 v76, 0x3600, v65
	v_add_u32_e32 v77, 0x4000, v65
	v_readlane_b32 s80, v250, 6
	v_readlane_b32 s81, v250, 7
	v_readlane_b32 s82, v250, 8
	v_readlane_b32 s83, v250, 9
	s_lshl_b32 s1, s1, 19
	s_add_u32 s8, s15, s1
	s_mov_b32 s1, s9
	v_readlane_b32 s84, v250, 10
	v_readlane_b32 s85, v250, 11
	v_readlane_b32 s86, v250, 12
	v_readlane_b32 s87, v250, 13
	v_readlane_b32 s88, v250, 14
	v_readlane_b32 s89, v250, 15
	v_readlane_b32 s90, v250, 16
	v_readlane_b32 s91, v250, 17
	v_readlane_b32 s92, v250, 18
	v_readlane_b32 s93, v250, 19
	v_readlane_b32 s94, v250, 20
	v_readlane_b32 s95, v250, 21
	s_waitcnt vmcnt(1)
	v_mul_f32_e32 v48, v48, v66
	v_mul_f32_e32 v0, v0, v66
	v_mul_f32_e32 v49, v49, v66
	s_waitcnt vmcnt(0)
	v_mul_f32_e32 v32, v32, v64
	v_mul_f32_e32 v50, v50, v66
	v_mul_f32_e32 v51, v51, v66
	v_mul_f32_e32 v52, v52, v66
	v_mul_f32_e32 v53, v53, v66
	v_mul_f32_e32 v54, v54, v66
	v_mul_f32_e32 v55, v55, v66
	v_mul_f32_e32 v56, v56, v66
	v_mul_f32_e32 v57, v57, v66
	v_mul_f32_e32 v58, v58, v66
	v_mul_f32_e32 v59, v59, v66
	v_mul_f32_e32 v60, v60, v66
	v_mul_f32_e32 v61, v61, v66
	v_mul_f32_e32 v62, v62, v66
	v_mul_f32_e32 v63, v63, v66
	v_mul_f32_e32 v33, v33, v64
	v_mul_f32_e32 v34, v34, v64
	v_mul_f32_e32 v35, v35, v64
	v_mul_f32_e32 v36, v36, v64
	v_mul_f32_e32 v37, v37, v64
	v_mul_f32_e32 v38, v38, v64
	v_mul_f32_e32 v39, v39, v64
	v_mul_f32_e32 v40, v40, v64
	v_mul_f32_e32 v41, v41, v64
	v_mul_f32_e32 v42, v42, v64
	v_mul_f32_e32 v43, v43, v64
	v_mul_f32_e32 v44, v44, v64
	v_mul_f32_e32 v45, v45, v64
	v_mul_f32_e32 v46, v46, v64
	v_mul_f32_e32 v47, v47, v64
	v_mul_f32_e32 v16, v16, v64
	v_mul_f32_e32 v17, v17, v64
	ds_write2_b32 v65, v32, v48 offset1:32
	ds_write2_b32 v65, v33, v49 offset0:132 offset1:164
	ds_write2_b32 v67, v34, v50 offset0:8 offset1:40
	ds_write2_b32 v67, v35, v51 offset0:140 offset1:172
	ds_write2_b32 v69, v36, v52 offset0:32 offset1:64
	ds_write2_b32 v69, v37, v53 offset0:164 offset1:196
	ds_write2_b32 v70, v38, v54 offset0:40 offset1:72
	ds_write2_b32 v70, v39, v55 offset0:172 offset1:204
	ds_write2_b32 v71, v40, v56 offset0:64 offset1:96
	ds_write2_b32 v71, v41, v57 offset0:196 offset1:228
	ds_write2_b32 v72, v42, v58 offset0:72 offset1:104
	ds_write2_b32 v72, v43, v59 offset0:204 offset1:236
	ds_write2_b32 v73, v44, v60 offset0:96 offset1:128
	ds_write2_b32 v74, v45, v61 offset0:100 offset1:132
	ds_write2_b32 v75, v46, v62 offset0:104 offset1:136
	ds_write2_b32 v76, v47, v63 offset0:108 offset1:140
	ds_write2_b32 v77, v16, v0 offset0:128 offset1:160
	v_mul_f32_e32 v0, v1, v66
	v_add_u32_e32 v1, 0x4400, v65
	ds_write2_b32 v1, v17, v0 offset0:4 offset1:36
	v_mul_f32_e32 v0, v18, v64
	v_mul_f32_e32 v2, v2, v66
	ds_write2_b32 v1, v0, v2 offset0:136 offset1:168
	v_mul_f32_e32 v0, v19, v64
	v_mul_f32_e32 v1, v3, v66
	v_add_u32_e32 v2, 0x4800, v65
	ds_write2_b32 v2, v0, v1 offset0:12 offset1:44
	v_mul_f32_e32 v0, v20, v64
	v_mul_f32_e32 v1, v4, v66
	v_add_u32_e32 v2, 0x5000, v65
	ds_write2_b32 v2, v0, v1 offset0:160 offset1:192
	v_mul_f32_e32 v0, v21, v64
	v_mul_f32_e32 v1, v5, v66
	v_add_u32_e32 v2, 0x5400, v65
	ds_write2_b32 v2, v0, v1 offset0:36 offset1:68
	v_mul_f32_e32 v0, v22, v64
	v_mul_f32_e32 v1, v6, v66
	ds_write2_b32 v2, v0, v1 offset0:168 offset1:200
	v_mul_f32_e32 v0, v23, v64
	v_mul_f32_e32 v1, v7, v66
	v_add_u32_e32 v2, 0x5800, v65
	ds_write2_b32 v2, v0, v1 offset0:44 offset1:76
	v_mul_f32_e32 v0, v24, v64
	v_mul_f32_e32 v1, v8, v66
	v_add_u32_e32 v2, 0x6000, v65
	ds_write2_b32 v2, v0, v1 offset0:192 offset1:224
	v_mul_f32_e32 v0, v25, v64
	v_mul_f32_e32 v1, v9, v66
	v_add_u32_e32 v2, 0x6400, v65
	ds_write2_b32 v2, v0, v1 offset0:68 offset1:100
	v_mul_f32_e32 v0, v26, v64
	v_mul_f32_e32 v1, v10, v66
	ds_write2_b32 v2, v0, v1 offset0:200 offset1:232
	v_mul_f32_e32 v0, v27, v64
	v_mul_f32_e32 v1, v11, v66
	v_add_u32_e32 v2, 0x6800, v65
	ds_write2_b32 v2, v0, v1 offset0:76 offset1:108
	v_mul_f32_e32 v0, v28, v64
	v_mul_f32_e32 v1, v12, v66
	v_add_u32_e32 v2, 0x7200, v65
	ds_write2_b32 v2, v0, v1 offset0:96 offset1:128
	v_mul_f32_e32 v0, v29, v64
	v_mul_f32_e32 v1, v13, v66
	v_add_u32_e32 v2, 0x7400, v65
	ds_write2_b32 v2, v0, v1 offset0:100 offset1:132
	v_mul_f32_e32 v0, v30, v64
	v_mul_f32_e32 v1, v14, v66
	v_add_u32_e32 v2, 0x7600, v65
	v_and_b32_e32 v12, 31, v68
	ds_write2_b32 v2, v0, v1 offset0:104 offset1:136
	v_mul_f32_e32 v0, v31, v64
	v_mul_f32_e32 v1, v15, v66
	v_add_u32_e32 v2, 0x7800, v65
	v_lshlrev_b32_e32 v8, 2, v12
	ds_write2_b32 v2, v0, v1 offset0:108 offset1:140
	v_or_b32_e32 v0, s23, v8
	v_ashrrev_i32_e32 v1, 31, v0
	v_lshlrev_b64 v[0:1], 2, v[0:1]
	v_lshl_add_u64 v[2:3], s[80:81], 0, v[0:1]
	v_lshl_add_u64 v[4:5], s[82:83], 0, v[0:1]
	s_waitcnt lgkmcnt(0)
	s_barrier
	global_load_dwordx4 v[0:3], v[2:3], off
	s_nop 0
	global_load_dwordx4 v[4:7], v[4:5], off
	v_and_b32_e32 v9, 64, v108
	v_add_u32_e32 v9, 64, v9
	v_xor_b32_e32 v10, 1, v108
	v_cmp_lt_i32_e32 vcc, v10, v9
	s_addc_u32 s23, s17, 0
	s_lshl_b64 s[0:1], s[0:1], 12
	v_cndmask_b32_e32 v10, v108, v10, vcc
	v_lshlrev_b32_e32 v32, 2, v10
	v_xor_b32_e32 v10, 2, v108
	v_cmp_lt_i32_e32 vcc, v10, v9
	s_add_u32 s58, s24, s0
	s_addc_u32 s59, s25, s1
	v_cndmask_b32_e32 v10, v108, v10, vcc
	v_lshlrev_b32_e32 v33, 2, v10
	v_xor_b32_e32 v10, 4, v108
	v_cmp_lt_i32_e32 vcc, v10, v9
	s_and_b64 s[0:1], s[4:5], exec
	v_ashrrev_i32_e32 v22, 5, v68
	v_cndmask_b32_e32 v10, v108, v10, vcc
	v_lshlrev_b32_e32 v34, 2, v10
	v_xor_b32_e32 v10, 8, v108
	s_cselect_b32 s59, s23, s59
	s_cselect_b32 s58, s8, s58
	v_cmp_lt_i32_e32 vcc, v10, v9
	s_add_i32 s8, s22, s35
	v_add_u32_e32 v16, s8, v22
	v_cndmask_b32_e32 v10, v108, v10, vcc
	s_add_i32 s8, s22, s36
	s_add_i32 s22, s22, s37
	v_lshlrev_b32_e32 v35, 2, v10
	v_xor_b32_e32 v10, 16, v108
	v_add_u32_e32 v20, s8, v22
	v_add_u32_e32 v24, s22, v22
	v_cmp_eq_u32_e64 s[0:1], 0, v12
	v_cmp_lt_i32_e32 vcc, v10, v9
	v_ashrrev_i32_e32 v23, 31, v22
	v_mul_lo_u32 v13, v22, s52
	v_lshlrev_b32_e32 v12, 4, v12
	v_add_u32_e32 v26, s21, v22
	v_ashrrev_i32_e32 v17, 31, v16
	v_ashrrev_i32_e32 v21, 31, v20
	v_ashrrev_i32_e32 v25, 31, v24
	v_cndmask_b32_e32 v9, v108, v10, vcc
	v_add_u32_e32 v8, s20, v8
	v_lshlrev_b64 v[10:11], 12, v[22:23]
	v_add3_u32 v37, v13, v12, 32
	v_lshlrev_b32_e32 v12, 1, v26
	v_lshlrev_b64 v[14:15], 12, v[16:17]
	v_lshlrev_b32_e32 v16, 1, v16
	v_lshlrev_b64 v[18:19], 12, v[20:21]
	v_lshlrev_b32_e32 v20, 1, v20
	v_lshlrev_b64 v[22:23], 12, v[24:25]
	v_lshlrev_b32_e32 v24, 1, v24
	v_ashrrev_i32_e32 v27, 31, v26
	v_lshlrev_b32_e32 v36, 2, v9
	v_ashrrev_i32_e32 v9, 31, v8
	v_ashrrev_i32_e32 v13, 31, v12
	v_ashrrev_i32_e32 v17, 31, v16
	v_ashrrev_i32_e32 v21, 31, v20
	v_ashrrev_i32_e32 v25, 31, v24
	v_lshlrev_b64 v[26:27], 12, v[26:27]
	v_lshlrev_b64 v[8:9], 2, v[8:9]
	v_lshl_add_u64 v[10:11], s[58:59], 0, v[10:11]
	v_lshl_add_u64 v[12:13], v[12:13], 2, s[30:31]
	v_lshl_add_u64 v[14:15], s[28:29], 0, v[14:15]
	v_lshl_add_u64 v[16:17], v[16:17], 2, s[30:31]
	v_lshl_add_u64 v[18:19], s[28:29], 0, v[18:19]
	v_lshl_add_u64 v[20:21], v[20:21], 2, s[30:31]
	v_lshl_add_u64 v[22:23], s[28:29], 0, v[22:23]
	v_lshl_add_u64 v[24:25], v[24:25], 2, s[30:31]
	v_lshl_add_u64 v[26:27], s[6:7], 0, v[26:27]
	s_mov_b64 s[20:21], 0
	s_branch .LBB0_2065

.LBB0_2186:
	s_setprio 1
	ds_read_b128 v[140:143], v103
	ds_read_b128 v[144:147], v104 offset:36864
	ds_read_b128 v[148:151], v103 offset:32
	ds_read_b128 v[192:195], v104 offset:36896
	ds_read_b128 v[196:199], v104 offset:41472
	ds_read_b128 v[200:203], v103 offset:4608
	s_waitcnt lgkmcnt(4)
	v_mfma_f32_32x32x16_bf16 v[48:63], v[140:143], v[144:147], v[48:63]
	ds_read_b128 v[204:207], v104 offset:41504
	global_load_dwordx4 v[108:111], v168, s[98:99] offset:3840
	global_load_dwordx4 v[112:115], v170, s[98:99] offset:3840
	s_waitcnt vmcnt(9)
	ds_write_b128 v105, v[68:71] offset:18432
	s_waitcnt lgkmcnt(3)
	v_mfma_f32_32x32x16_bf16 v[32:47], v[140:143], v[196:199], v[32:47]
	ds_read_b128 v[208:211], v103 offset:4640
	global_load_dwordx4 v[116:119], v172, s[98:99] offset:3840
	global_load_dwordx4 v[120:123], v174, s[98:99] offset:3840
	s_waitcnt lgkmcnt(3)
	v_mfma_f32_32x32x16_bf16 v[16:31], v[200:203], v[144:147], v[16:31]
	global_load_dwordx4 v[124:127], v176, s[98:99] offset:3840
	global_load_dwordx4 v[128:131], v178, s[98:99] offset:3840
	s_waitcnt vmcnt(11)
	ds_write_b128 v105, v[84:87] offset:23040
	v_mfma_f32_32x32x16_bf16 v[0:15], v[200:203], v[196:199], v[0:15]
	ds_read_b128 v[212:215], v103 offset:64
	ds_read_b128 v[216:219], v104 offset:36928
	global_load_dwordx4 v[132:135], v180, s[98:99] offset:3840
	global_load_dwordx4 v[136:139], v182, s[98:99] offset:3840
	v_mfma_f32_32x32x16_bf16 v[48:63], v[148:151], v[192:195], v[48:63]
	ds_read_b128 v[220:223], v104 offset:41536
	s_waitcnt vmcnt(12)
	ds_write_b128 v105, v[88:91] offset:27648
	s_waitcnt lgkmcnt(7)
	v_mfma_f32_32x32x16_bf16 v[32:47], v[148:151], v[204:207], v[32:47]
	ds_read_b128 v[224:227], v103 offset:4672
	s_waitcnt lgkmcnt(6)
	v_mfma_f32_32x32x16_bf16 v[16:31], v[208:211], v[192:195], v[16:31]
	s_waitcnt vmcnt(11)
	ds_write_b128 v105, v[92:95] offset:32256
	v_mfma_f32_32x32x16_bf16 v[0:15], v[208:211], v[204:207], v[0:15]
	ds_read_b128 v[228:231], v103 offset:96
	ds_read_b128 v[140:143], v104 offset:36960
	s_waitcnt lgkmcnt(6)
	v_mfma_f32_32x32x16_bf16 v[48:63], v[212:215], v[216:219], v[48:63]
	ds_read_b128 v[144:147], v104 offset:41568
	ds_write_b128 v105, v[64:67] offset:55296
	s_waitcnt lgkmcnt(7)
	v_mfma_f32_32x32x16_bf16 v[32:47], v[212:215], v[220:223], v[32:47]
	ds_read_b128 v[196:199], v103 offset:4704
	s_waitcnt lgkmcnt(6)
	v_mfma_f32_32x32x16_bf16 v[16:31], v[224:227], v[216:219], v[16:31]
	s_waitcnt vmcnt(10)
	ds_write_b128 v105, v[72:75] offset:59904
	v_mfma_f32_32x32x16_bf16 v[0:15], v[224:227], v[220:223], v[0:15]
	s_waitcnt lgkmcnt(4)
	v_mfma_f32_32x32x16_bf16 v[48:63], v[228:231], v[140:143], v[48:63]
	s_waitcnt vmcnt(9)
	ds_write_b128 v105, v[76:79] offset:64512
	s_waitcnt lgkmcnt(4)
	v_mfma_f32_32x32x16_bf16 v[32:47], v[228:231], v[144:147], v[32:47]
	s_waitcnt lgkmcnt(2)
	v_mfma_f32_32x32x16_bf16 v[16:31], v[196:199], v[140:143], v[16:31]
	s_waitcnt vmcnt(8)
	ds_write_b128 v106, v[80:83] offset:13824
	v_mfma_f32_32x32x16_bf16 v[0:15], v[196:199], v[144:147], v[0:15]
	s_setprio 0
	s_waitcnt lgkmcnt(0)
	s_barrier
	s_setprio 1
	ds_read_b128 v[140:143], v103 offset:18432
	ds_read_b128 v[144:147], v104 offset:55296
	ds_read_b128 v[148:151], v103 offset:18464
	ds_read_b128 v[192:195], v104 offset:55328
	ds_read_b128 v[196:199], v104 offset:59904
	ds_read_b128 v[200:203], v103 offset:23040
	s_waitcnt lgkmcnt(4)
	v_mfma_f32_32x32x16_bf16 v[48:63], v[140:143], v[144:147], v[48:63]
	ds_read_b128 v[204:207], v104 offset:59936
	global_load_dwordx4 v[68:71], v168, s[98:99] offset:3968
	global_load_dwordx4 v[84:87], v170, s[98:99] offset:3968
	s_waitcnt vmcnt(9)
	ds_write_b128 v105, v[108:111]
	s_waitcnt lgkmcnt(3)
	v_mfma_f32_32x32x16_bf16 v[32:47], v[140:143], v[196:199], v[32:47]
	ds_read_b128 v[208:211], v103 offset:23072
	global_load_dwordx4 v[88:91], v172, s[98:99] offset:3968
	global_load_dwordx4 v[92:95], v174, s[98:99] offset:3968
	s_waitcnt lgkmcnt(3)
	v_mfma_f32_32x32x16_bf16 v[16:31], v[200:203], v[144:147], v[16:31]
	global_load_dwordx4 v[64:67], v176, s[98:99] offset:3968
	global_load_dwordx4 v[72:75], v178, s[98:99] offset:3968
	s_waitcnt vmcnt(12)
	ds_write_b128 v105, v[112:115] offset:4608
	v_mfma_f32_32x32x16_bf16 v[0:15], v[200:203], v[196:199], v[0:15]
	ds_read_b128 v[212:215], v103 offset:18496
	ds_read_b128 v[216:219], v104 offset:55360
	global_load_dwordx4 v[76:79], v180, s[98:99] offset:3968
	global_load_dwordx4 v[80:83], v182, s[98:99] offset:3968
	v_mfma_f32_32x32x16_bf16 v[48:63], v[148:151], v[192:195], v[48:63]
	ds_read_b128 v[220:223], v104 offset:59968
	s_add_u32 s98, s98, 0x100
	s_addc_u32 s99, s99, 0
	s_add_i32 s4, s4, 2
	s_cmp_lt_u32 s4, 11
	s_waitcnt vmcnt(13)
	ds_write_b128 v105, v[116:119] offset:9216
	s_waitcnt lgkmcnt(7)
	v_mfma_f32_32x32x16_bf16 v[32:47], v[148:151], v[204:207], v[32:47]
	ds_read_b128 v[224:227], v103 offset:23104
	s_waitcnt lgkmcnt(6)
	v_mfma_f32_32x32x16_bf16 v[16:31], v[208:211], v[192:195], v[16:31]
	s_waitcnt vmcnt(12)
	ds_write_b128 v105, v[120:123] offset:13824
	v_mfma_f32_32x32x16_bf16 v[0:15], v[208:211], v[204:207], v[0:15]
	ds_read_b128 v[228:231], v103 offset:18528
	ds_read_b128 v[140:143], v104 offset:55392
	s_waitcnt lgkmcnt(6)
	v_mfma_f32_32x32x16_bf16 v[48:63], v[212:215], v[216:219], v[48:63]
	ds_read_b128 v[144:147], v104 offset:60000
	s_waitcnt vmcnt(11)
	ds_write_b128 v105, v[124:127] offset:36864
	s_waitcnt lgkmcnt(7)
	v_mfma_f32_32x32x16_bf16 v[32:47], v[212:215], v[220:223], v[32:47]
	ds_read_b128 v[196:199], v103 offset:23136
	s_waitcnt lgkmcnt(6)
	v_mfma_f32_32x32x16_bf16 v[16:31], v[224:227], v[216:219], v[16:31]
	s_waitcnt vmcnt(10)
	ds_write_b128 v105, v[128:131] offset:41472
	v_mfma_f32_32x32x16_bf16 v[0:15], v[224:227], v[220:223], v[0:15]
	s_waitcnt lgkmcnt(4)
	v_mfma_f32_32x32x16_bf16 v[48:63], v[228:231], v[140:143], v[48:63]
	s_waitcnt vmcnt(9)
	ds_write_b128 v105, v[132:135] offset:46080
	s_waitcnt lgkmcnt(4)
	v_mfma_f32_32x32x16_bf16 v[32:47], v[228:231], v[144:147], v[32:47]
	s_waitcnt lgkmcnt(2)
	v_mfma_f32_32x32x16_bf16 v[16:31], v[196:199], v[140:143], v[16:31]
	s_waitcnt vmcnt(8)
	ds_write_b128 v105, v[136:139] offset:50688
	v_mfma_f32_32x32x16_bf16 v[0:15], v[196:199], v[144:147], v[0:15]
	s_setprio 0
	s_waitcnt lgkmcnt(0)
	s_barrier
	s_cbranch_scc1 .LBB0_2186
	s_setprio 1
	ds_read_b128 v[98:101], v103
	ds_read_b128 v[108:111], v104 offset:36864
	ds_read_b128 v[112:115], v103 offset:32
	ds_read_b128 v[192:195], v104 offset:36896
	ds_read_b128 v[196:199], v104 offset:41472
	ds_read_b128 v[200:203], v103 offset:4608
	s_waitcnt lgkmcnt(4)
	v_mfma_f32_32x32x16_bf16 v[48:63], v[98:101], v[108:111], v[48:63]
	ds_read_b128 v[204:207], v104 offset:41504
	s_waitcnt vmcnt(7)
	ds_write_b128 v105, v[68:71] offset:18432
	s_waitcnt lgkmcnt(3)
	v_mfma_f32_32x32x16_bf16 v[32:47], v[98:101], v[196:199], v[32:47]
	ds_read_b128 v[208:211], v103 offset:4640
	s_waitcnt lgkmcnt(3)
	v_mfma_f32_32x32x16_bf16 v[16:31], v[200:203], v[108:111], v[16:31]
	s_waitcnt vmcnt(6)
	ds_write_b128 v105, v[84:87] offset:23040
	v_mfma_f32_32x32x16_bf16 v[0:15], v[200:203], v[196:199], v[0:15]
	ds_read_b128 v[212:215], v103 offset:64
	ds_read_b128 v[216:219], v104 offset:36928
	v_mfma_f32_32x32x16_bf16 v[48:63], v[112:115], v[192:195], v[48:63]
	ds_read_b128 v[220:223], v104 offset:41536
	s_waitcnt vmcnt(5)
	ds_write_b128 v105, v[88:91] offset:27648
	s_waitcnt lgkmcnt(7)
	v_mfma_f32_32x32x16_bf16 v[32:47], v[112:115], v[204:207], v[32:47]
	ds_read_b128 v[224:227], v103 offset:4672
	s_waitcnt lgkmcnt(6)
	v_mfma_f32_32x32x16_bf16 v[16:31], v[208:211], v[192:195], v[16:31]
	s_waitcnt vmcnt(4)
	ds_write_b128 v105, v[92:95] offset:32256
	v_mfma_f32_32x32x16_bf16 v[0:15], v[208:211], v[204:207], v[0:15]
	ds_read_b128 v[228:231], v103 offset:96
	ds_read_b128 v[98:101], v104 offset:36960
	s_waitcnt lgkmcnt(6)
	v_mfma_f32_32x32x16_bf16 v[48:63], v[212:215], v[216:219], v[48:63]
	ds_read_b128 v[108:111], v104 offset:41568
	s_waitcnt vmcnt(3)
	ds_write_b128 v105, v[64:67] offset:55296
	s_waitcnt lgkmcnt(7)
	v_mfma_f32_32x32x16_bf16 v[32:47], v[212:215], v[220:223], v[32:47]
	ds_read_b128 v[196:199], v103 offset:4704
	s_waitcnt lgkmcnt(6)
	v_mfma_f32_32x32x16_bf16 v[16:31], v[224:227], v[216:219], v[16:31]
	s_waitcnt vmcnt(2)
	ds_write_b128 v105, v[72:75] offset:59904
	v_mfma_f32_32x32x16_bf16 v[0:15], v[224:227], v[220:223], v[0:15]
	s_waitcnt lgkmcnt(4)
	v_mfma_f32_32x32x16_bf16 v[48:63], v[228:231], v[98:101], v[48:63]
	s_waitcnt vmcnt(1)
	ds_write_b128 v105, v[76:79] offset:64512
	s_waitcnt lgkmcnt(4)
	v_mfma_f32_32x32x16_bf16 v[32:47], v[228:231], v[108:111], v[32:47]
	s_waitcnt lgkmcnt(2)
	v_mfma_f32_32x32x16_bf16 v[16:31], v[196:199], v[98:101], v[16:31]
	s_waitcnt vmcnt(0)
	ds_write_b128 v106, v[80:83] offset:13824
	v_mfma_f32_32x32x16_bf16 v[0:15], v[196:199], v[108:111], v[0:15]
	s_setprio 0
	s_waitcnt lgkmcnt(0)
	s_barrier
	s_setprio 1
	ds_read_b128 v[64:67], v103 offset:18432
	ds_read_b128 v[68:71], v104 offset:55296
	ds_read_b128 v[72:75], v103 offset:18464
	ds_read_b128 v[192:195], v104 offset:55328
	ds_read_b128 v[196:199], v104 offset:59904
	ds_read_b128 v[200:203], v103 offset:23040
	s_waitcnt lgkmcnt(4)
	v_mfma_f32_32x32x16_bf16 v[48:63], v[64:67], v[68:71], v[48:63]
	ds_read_b128 v[204:207], v104 offset:59936
	s_waitcnt lgkmcnt(2)
	v_mfma_f32_32x32x16_bf16 v[32:47], v[64:67], v[196:199], v[32:47]
	ds_read_b128 v[208:211], v103 offset:23072
	s_waitcnt lgkmcnt(2)
	v_mfma_f32_32x32x16_bf16 v[16:31], v[200:203], v[68:71], v[16:31]
	v_mfma_f32_32x32x16_bf16 v[0:15], v[200:203], v[196:199], v[0:15]
	ds_read_b128 v[212:215], v103 offset:18496
	ds_read_b128 v[216:219], v104 offset:55360
	v_mfma_f32_32x32x16_bf16 v[48:63], v[72:75], v[192:195], v[48:63]
	ds_read_b128 v[220:223], v104 offset:59968
	s_waitcnt lgkmcnt(4)
	v_mfma_f32_32x32x16_bf16 v[32:47], v[72:75], v[204:207], v[32:47]
	ds_read_b128 v[224:227], v103 offset:23104
	s_waitcnt lgkmcnt(4)
	v_mfma_f32_32x32x16_bf16 v[16:31], v[208:211], v[192:195], v[16:31]
	v_mfma_f32_32x32x16_bf16 v[0:15], v[208:211], v[204:207], v[0:15]
	ds_read_b128 v[228:231], v103 offset:18528
	ds_read_b128 v[64:67], v104 offset:55392
	s_waitcnt lgkmcnt(4)
	v_mfma_f32_32x32x16_bf16 v[48:63], v[212:215], v[216:219], v[48:63]
	ds_read_b128 v[68:71], v104 offset:60000
	s_waitcnt lgkmcnt(4)
	v_mfma_f32_32x32x16_bf16 v[32:47], v[212:215], v[220:223], v[32:47]
	ds_read_b128 v[196:199], v103 offset:23136
	s_waitcnt lgkmcnt(4)
	v_mfma_f32_32x32x16_bf16 v[16:31], v[224:227], v[216:219], v[16:31]
	v_mfma_f32_32x32x16_bf16 v[0:15], v[224:227], v[220:223], v[0:15]
	s_waitcnt lgkmcnt(2)
	v_mfma_f32_32x32x16_bf16 v[48:63], v[228:231], v[64:67], v[48:63]
	s_waitcnt lgkmcnt(1)
	v_mfma_f32_32x32x16_bf16 v[32:47], v[228:231], v[68:71], v[32:47]
	s_waitcnt lgkmcnt(0)
	v_mfma_f32_32x32x16_bf16 v[16:31], v[196:199], v[64:67], v[16:31]
	v_mfma_f32_32x32x16_bf16 v[0:15], v[196:199], v[68:71], v[0:15]
	s_setprio 0
	s_cmpk_gt_u32 s22, 0xfff
	s_cselect_b64 s[10:11], -1, 0
	s_cmpk_lt_u32 s22, 0x1000
	s_cselect_b64 s[40:41], -1, 0
	s_ashr_i32 s61, s2, 2
	s_cmp_lt_i32 s61, 7
	s_barrier
	s_cbranch_scc1 .LBB0_2189
	s_cmp_lg_u32 s61, 7
	s_cselect_b64 s[4:5], -1, 0
	s_cbranch_execz .LBB0_2190
	s_branch .LBB0_2191

.LBB0_3734:
	s_setprio 1
	ds_read_b128 v[148:151], v112
	ds_read_b128 v[152:155], v113 offset:36864
	ds_read_b128 v[156:159], v112 offset:32
	ds_read_b128 v[192:195], v113 offset:36896
	ds_read_b128 v[196:199], v113 offset:41472
	ds_read_b128 v[200:203], v112 offset:4608
	s_waitcnt lgkmcnt(4)
	v_mfma_f32_32x32x16_bf16 v[48:63], v[148:151], v[152:155], v[48:63]
	ds_read_b128 v[204:207], v113 offset:41504
	global_load_dwordx4 v[116:119], v176, s[98:99] offset:256
	global_load_dwordx4 v[120:123], v180, s[98:99] offset:256
	s_waitcnt vmcnt(9)
	ds_write_b128 v114, v[64:67] offset:18432
	s_waitcnt lgkmcnt(3)
	v_mfma_f32_32x32x16_bf16 v[32:47], v[148:151], v[196:199], v[32:47]
	ds_read_b128 v[208:211], v112 offset:4640
	global_load_dwordx4 v[124:127], v182, s[98:99] offset:256
	global_load_dwordx4 v[128:131], v184, s[98:99] offset:256
	s_waitcnt lgkmcnt(3)
	v_mfma_f32_32x32x16_bf16 v[16:31], v[200:203], v[152:155], v[16:31]
	global_load_dwordx4 v[132:135], v178, s[98:99]
	global_load_dwordx4 v[136:139], v98, s[98:99]
	s_waitcnt vmcnt(12)
	ds_write_b128 v114, v[68:71] offset:23040
	v_mfma_f32_32x32x16_bf16 v[0:15], v[200:203], v[196:199], v[0:15]
	ds_read_b128 v[212:215], v112 offset:64
	ds_read_b128 v[216:219], v113 offset:36928
	global_load_dwordx4 v[140:143], v186, s[98:99]
	global_load_dwordx4 v[144:147], v188, s[98:99] offset:-128
	v_mfma_f32_32x32x16_bf16 v[48:63], v[156:159], v[192:195], v[48:63]
	ds_read_b128 v[220:223], v113 offset:41536
	s_waitcnt vmcnt(13)
	ds_write_b128 v114, v[72:75] offset:27648
	s_waitcnt lgkmcnt(7)
	v_mfma_f32_32x32x16_bf16 v[32:47], v[156:159], v[204:207], v[32:47]
	ds_read_b128 v[224:227], v112 offset:4672
	s_waitcnt lgkmcnt(6)
	v_mfma_f32_32x32x16_bf16 v[16:31], v[208:211], v[192:195], v[16:31]
	s_waitcnt vmcnt(12)
	ds_write_b128 v114, v[76:79] offset:32256
	v_mfma_f32_32x32x16_bf16 v[0:15], v[208:211], v[204:207], v[0:15]
	ds_read_b128 v[228:231], v112 offset:96
	ds_read_b128 v[148:151], v113 offset:36960
	s_waitcnt lgkmcnt(6)
	v_mfma_f32_32x32x16_bf16 v[48:63], v[212:215], v[216:219], v[48:63]
	ds_read_b128 v[152:155], v113 offset:41568
	s_waitcnt vmcnt(11)
	ds_write_b128 v114, v[80:83] offset:55296
	s_waitcnt lgkmcnt(7)
	v_mfma_f32_32x32x16_bf16 v[32:47], v[212:215], v[220:223], v[32:47]
	ds_read_b128 v[196:199], v112 offset:4704
	s_waitcnt lgkmcnt(6)
	v_mfma_f32_32x32x16_bf16 v[16:31], v[224:227], v[216:219], v[16:31]
	s_waitcnt vmcnt(10)
	ds_write_b128 v114, v[84:87] offset:59904
	v_mfma_f32_32x32x16_bf16 v[0:15], v[224:227], v[220:223], v[0:15]
	s_waitcnt lgkmcnt(4)
	v_mfma_f32_32x32x16_bf16 v[48:63], v[228:231], v[148:151], v[48:63]
	s_waitcnt vmcnt(9)
	ds_write_b128 v114, v[88:91] offset:64512
	s_waitcnt lgkmcnt(4)
	v_mfma_f32_32x32x16_bf16 v[32:47], v[228:231], v[152:155], v[32:47]
	s_waitcnt lgkmcnt(2)
	v_mfma_f32_32x32x16_bf16 v[16:31], v[196:199], v[148:151], v[16:31]
	s_waitcnt vmcnt(8)
	ds_write_b128 v115, v[92:95] offset:13824
	v_mfma_f32_32x32x16_bf16 v[0:15], v[196:199], v[152:155], v[0:15]
	s_setprio 0
	s_waitcnt lgkmcnt(0)
	s_barrier
	s_setprio 1
	ds_read_b128 v[148:151], v112 offset:18432
	ds_read_b128 v[152:155], v113 offset:55296
	ds_read_b128 v[156:159], v112 offset:18464
	ds_read_b128 v[192:195], v113 offset:55328
	ds_read_b128 v[196:199], v113 offset:59904
	ds_read_b128 v[200:203], v112 offset:23040
	s_waitcnt lgkmcnt(4)
	v_mfma_f32_32x32x16_bf16 v[48:63], v[148:151], v[152:155], v[48:63]
	ds_read_b128 v[204:207], v113 offset:59936
	global_load_dwordx4 v[64:67], v176, s[98:99] offset:384
	global_load_dwordx4 v[68:71], v180, s[98:99] offset:384
	s_waitcnt vmcnt(9)
	ds_write_b128 v114, v[116:119]
	s_waitcnt lgkmcnt(3)
	v_mfma_f32_32x32x16_bf16 v[32:47], v[148:151], v[196:199], v[32:47]
	ds_read_b128 v[208:211], v112 offset:23072
	global_load_dwordx4 v[72:75], v182, s[98:99] offset:384
	global_load_dwordx4 v[76:79], v184, s[98:99] offset:384
	s_waitcnt lgkmcnt(3)
	v_mfma_f32_32x32x16_bf16 v[16:31], v[200:203], v[152:155], v[16:31]
	global_load_dwordx4 v[80:83], v178, s[98:99] offset:128
	global_load_dwordx4 v[84:87], v99, s[98:99]
	s_waitcnt vmcnt(12)
	ds_write_b128 v114, v[120:123] offset:4608
	v_mfma_f32_32x32x16_bf16 v[0:15], v[200:203], v[196:199], v[0:15]
	ds_read_b128 v[212:215], v112 offset:18496
	ds_read_b128 v[216:219], v113 offset:55360
	global_load_dwordx4 v[88:91], v186, s[98:99] offset:128
	global_load_dwordx4 v[92:95], v188, s[98:99]
	v_mfma_f32_32x32x16_bf16 v[48:63], v[156:159], v[192:195], v[48:63]
	ds_read_b128 v[220:223], v113 offset:59968
	s_add_u32 s98, s98, 0x100
	s_addc_u32 s99, s99, 0
	s_add_i32 s0, s0, 2
	s_cmp_lt_u32 s0, 3
	s_waitcnt vmcnt(13)
	ds_write_b128 v114, v[124:127] offset:9216
	s_waitcnt lgkmcnt(7)
	v_mfma_f32_32x32x16_bf16 v[32:47], v[156:159], v[204:207], v[32:47]
	ds_read_b128 v[224:227], v112 offset:23104
	s_waitcnt lgkmcnt(6)
	v_mfma_f32_32x32x16_bf16 v[16:31], v[208:211], v[192:195], v[16:31]
	s_waitcnt vmcnt(12)
	ds_write_b128 v114, v[128:131] offset:13824
	v_mfma_f32_32x32x16_bf16 v[0:15], v[208:211], v[204:207], v[0:15]
	ds_read_b128 v[228:231], v112 offset:18528
	ds_read_b128 v[148:151], v113 offset:55392
	s_waitcnt lgkmcnt(6)
	v_mfma_f32_32x32x16_bf16 v[48:63], v[212:215], v[216:219], v[48:63]
	ds_read_b128 v[152:155], v113 offset:60000
	s_waitcnt vmcnt(11)
	ds_write_b128 v114, v[132:135] offset:36864
	s_waitcnt lgkmcnt(7)
	v_mfma_f32_32x32x16_bf16 v[32:47], v[212:215], v[220:223], v[32:47]
	ds_read_b128 v[196:199], v112 offset:23136
	s_waitcnt lgkmcnt(6)
	v_mfma_f32_32x32x16_bf16 v[16:31], v[224:227], v[216:219], v[16:31]
	s_waitcnt vmcnt(10)
	ds_write_b128 v114, v[136:139] offset:41472
	v_mfma_f32_32x32x16_bf16 v[0:15], v[224:227], v[220:223], v[0:15]
	s_waitcnt lgkmcnt(4)
	v_mfma_f32_32x32x16_bf16 v[48:63], v[228:231], v[148:151], v[48:63]
	s_waitcnt vmcnt(9)
	ds_write_b128 v114, v[140:143] offset:46080
	s_waitcnt lgkmcnt(4)
	v_mfma_f32_32x32x16_bf16 v[32:47], v[228:231], v[152:155], v[32:47]
	s_waitcnt lgkmcnt(2)
	v_mfma_f32_32x32x16_bf16 v[16:31], v[196:199], v[148:151], v[16:31]
	s_waitcnt vmcnt(8)
	ds_write_b128 v114, v[144:147] offset:50688
	v_mfma_f32_32x32x16_bf16 v[0:15], v[196:199], v[152:155], v[0:15]
	s_setprio 0
	s_waitcnt lgkmcnt(0)
	s_barrier
	s_cbranch_scc1 .LBB0_3734
	s_setprio 1
	ds_read_b128 v[98:101], v112
	ds_read_b128 v[102:105], v113 offset:36864
	ds_read_b128 v[106:109], v112 offset:32
	ds_read_b128 v[192:195], v113 offset:36896
	ds_read_b128 v[196:199], v113 offset:41472
	ds_read_b128 v[200:203], v112 offset:4608
	s_waitcnt lgkmcnt(4)
	v_mfma_f32_32x32x16_bf16 v[48:63], v[98:101], v[102:105], v[48:63]
	ds_read_b128 v[204:207], v113 offset:41504
	s_waitcnt vmcnt(7)
	ds_write_b128 v114, v[64:67] offset:18432
	s_waitcnt lgkmcnt(3)
	v_mfma_f32_32x32x16_bf16 v[32:47], v[98:101], v[196:199], v[32:47]
	ds_read_b128 v[208:211], v112 offset:4640
	s_waitcnt lgkmcnt(3)
	v_mfma_f32_32x32x16_bf16 v[16:31], v[200:203], v[102:105], v[16:31]
	s_waitcnt vmcnt(6)
	ds_write_b128 v114, v[68:71] offset:23040
	v_mfma_f32_32x32x16_bf16 v[0:15], v[200:203], v[196:199], v[0:15]
	ds_read_b128 v[212:215], v112 offset:64
	ds_read_b128 v[216:219], v113 offset:36928
	v_mfma_f32_32x32x16_bf16 v[48:63], v[106:109], v[192:195], v[48:63]
	ds_read_b128 v[220:223], v113 offset:41536
	s_waitcnt vmcnt(5)
	ds_write_b128 v114, v[72:75] offset:27648
	s_waitcnt lgkmcnt(7)
	v_mfma_f32_32x32x16_bf16 v[32:47], v[106:109], v[204:207], v[32:47]
	ds_read_b128 v[224:227], v112 offset:4672
	s_waitcnt lgkmcnt(6)
	v_mfma_f32_32x32x16_bf16 v[16:31], v[208:211], v[192:195], v[16:31]
	s_waitcnt vmcnt(4)
	ds_write_b128 v114, v[76:79] offset:32256
	v_mfma_f32_32x32x16_bf16 v[0:15], v[208:211], v[204:207], v[0:15]
	ds_read_b128 v[228:231], v113 offset:36960
	ds_read_b128 v[98:101], v112 offset:4704
	s_waitcnt lgkmcnt(6)
	v_mfma_f32_32x32x16_bf16 v[48:63], v[212:215], v[216:219], v[48:63]
	ds_read_b128 v[102:105], v113 offset:41568
	s_waitcnt vmcnt(3)
	ds_write_b128 v114, v[80:83] offset:55296
	s_waitcnt lgkmcnt(7)
	v_mfma_f32_32x32x16_bf16 v[32:47], v[212:215], v[220:223], v[32:47]
	ds_read_b128 v[196:199], v112 offset:96
	s_waitcnt lgkmcnt(6)
	v_mfma_f32_32x32x16_bf16 v[16:31], v[224:227], v[216:219], v[16:31]
	s_waitcnt vmcnt(2)
	ds_write_b128 v114, v[84:87] offset:59904
	v_mfma_f32_32x32x16_bf16 v[0:15], v[224:227], v[220:223], v[0:15]
	s_waitcnt lgkmcnt(4)
	v_mfma_f32_32x32x16_bf16 v[16:31], v[98:101], v[228:231], v[16:31]
	s_waitcnt vmcnt(1)
	ds_write_b128 v114, v[88:91] offset:64512
	s_waitcnt lgkmcnt(4)
	v_mfma_f32_32x32x16_bf16 v[0:15], v[98:101], v[102:105], v[0:15]
	s_waitcnt lgkmcnt(2)
	v_mfma_f32_32x32x16_bf16 v[48:63], v[196:199], v[228:231], v[48:63]
	s_waitcnt vmcnt(0)
	ds_write_b128 v115, v[92:95] offset:13824
	v_mfma_f32_32x32x16_bf16 v[32:47], v[196:199], v[102:105], v[32:47]
	s_setprio 0
	s_waitcnt lgkmcnt(0)
	s_barrier
	s_setprio 1
	ds_read_b128 v[64:67], v112 offset:18432
	ds_read_b128 v[68:71], v113 offset:55296
	ds_read_b128 v[72:75], v112 offset:18464
	ds_read_b128 v[192:195], v113 offset:55328
	ds_read_b128 v[196:199], v113 offset:59904
	ds_read_b128 v[200:203], v112 offset:23040
	s_waitcnt lgkmcnt(4)
	v_mfma_f32_32x32x16_bf16 v[48:63], v[64:67], v[68:71], v[48:63]
	ds_read_b128 v[204:207], v113 offset:59936
	s_waitcnt lgkmcnt(2)
	v_mfma_f32_32x32x16_bf16 v[32:47], v[64:67], v[196:199], v[32:47]
	ds_read_b128 v[208:211], v112 offset:23072
	s_waitcnt lgkmcnt(2)
	v_mfma_f32_32x32x16_bf16 v[16:31], v[200:203], v[68:71], v[16:31]
	v_mfma_f32_32x32x16_bf16 v[0:15], v[200:203], v[196:199], v[0:15]
	ds_read_b128 v[212:215], v112 offset:18496
	ds_read_b128 v[216:219], v113 offset:55360
	v_mfma_f32_32x32x16_bf16 v[48:63], v[72:75], v[192:195], v[48:63]
	ds_read_b128 v[220:223], v113 offset:59968
	s_waitcnt lgkmcnt(4)
	v_mfma_f32_32x32x16_bf16 v[32:47], v[72:75], v[204:207], v[32:47]
	ds_read_b128 v[224:227], v112 offset:23104
	s_waitcnt lgkmcnt(4)
	v_mfma_f32_32x32x16_bf16 v[16:31], v[208:211], v[192:195], v[16:31]
	v_mfma_f32_32x32x16_bf16 v[0:15], v[208:211], v[204:207], v[0:15]
	ds_read_b128 v[228:231], v113 offset:55392
	ds_read_b128 v[64:67], v112 offset:23136
	s_waitcnt lgkmcnt(4)
	v_mfma_f32_32x32x16_bf16 v[48:63], v[212:215], v[216:219], v[48:63]
	ds_read_b128 v[68:71], v113 offset:60000
	s_waitcnt lgkmcnt(4)
	v_mfma_f32_32x32x16_bf16 v[32:47], v[212:215], v[220:223], v[32:47]
	ds_read_b128 v[196:199], v112 offset:18528
	s_waitcnt lgkmcnt(4)
	v_mfma_f32_32x32x16_bf16 v[16:31], v[224:227], v[216:219], v[16:31]
	v_mfma_f32_32x32x16_bf16 v[0:15], v[224:227], v[220:223], v[0:15]
	s_waitcnt lgkmcnt(2)
	v_mfma_f32_32x32x16_bf16 v[16:31], v[64:67], v[228:231], v[16:31]
	s_waitcnt lgkmcnt(1)
	v_mfma_f32_32x32x16_bf16 v[0:15], v[64:67], v[68:71], v[0:15]
	s_waitcnt lgkmcnt(0)
	v_mfma_f32_32x32x16_bf16 v[48:63], v[196:199], v[228:231], v[48:63]
	v_mfma_f32_32x32x16_bf16 v[32:47], v[196:199], v[68:71], v[32:47]
	s_setprio 0
	s_nop 10
	v_cvt_pk_bf16_f32 v32, v32, s0
	v_cvt_pk_bf16_f32 v0, v0, s0
	s_barrier
	ds_write_b16 v111, v32 offset:64
	v_cvt_pk_bf16_f32 v32, v49, s0
	ds_write_b16 v111, v0 offset:8768
	v_cvt_pk_bf16_f32 v0, v17, s0
	ds_write_b16 v111, v32 offset:272
	v_cvt_pk_bf16_f32 v32, v33, s0
	ds_write_b16 v111, v0 offset:8976
	v_cvt_pk_bf16_f32 v0, v1, s0
	ds_write_b16 v111, v32 offset:336
	v_cvt_pk_bf16_f32 v32, v50, s0
	ds_write_b16 v111, v0 offset:9040
	v_cvt_pk_bf16_f32 v0, v18, s0
	ds_write_b16 v111, v32 offset:544
	v_cvt_pk_bf16_f32 v32, v34, s0
	ds_write_b16 v111, v0 offset:9248
	v_cvt_pk_bf16_f32 v0, v2, s0
	ds_write_b16 v111, v32 offset:608
	v_cvt_pk_bf16_f32 v32, v51, s0
	ds_write_b16 v111, v0 offset:9312
	v_cvt_pk_bf16_f32 v0, v19, s0
	ds_write_b16 v111, v32 offset:816
	v_cvt_pk_bf16_f32 v32, v35, s0
	ds_write_b16 v111, v0 offset:9520
	v_cvt_pk_bf16_f32 v0, v3, s0
	ds_write_b16 v111, v32 offset:880
	v_cvt_pk_bf16_f32 v32, v52, s0
	ds_write_b16 v111, v0 offset:9584
	v_cvt_pk_bf16_f32 v0, v20, s0
	ds_write_b16 v111, v32 offset:2176
	v_cvt_pk_bf16_f32 v32, v36, s0
	ds_write_b16 v111, v0 offset:10880
	v_cvt_pk_bf16_f32 v0, v4, s0
	ds_write_b16 v111, v32 offset:2240
	v_cvt_pk_bf16_f32 v32, v53, s0
	ds_write_b16 v111, v0 offset:10944
	v_cvt_pk_bf16_f32 v0, v21, s0
	ds_write_b16 v111, v32 offset:2448
	v_cvt_pk_bf16_f32 v32, v37, s0
	ds_write_b16 v111, v0 offset:11152
	v_cvt_pk_bf16_f32 v0, v5, s0
	ds_write_b16 v111, v32 offset:2512
	v_cvt_pk_bf16_f32 v32, v54, s0
	ds_write_b16 v111, v0 offset:11216
	v_cvt_pk_bf16_f32 v0, v22, s0
	ds_write_b16 v111, v32 offset:2720
	v_cvt_pk_bf16_f32 v32, v38, s0
	ds_write_b16 v111, v0 offset:11424
	v_cvt_pk_bf16_f32 v0, v6, s0
	ds_write_b16 v111, v32 offset:2784
	v_cvt_pk_bf16_f32 v32, v55, s0
	ds_write_b16 v111, v0 offset:11488
	v_cvt_pk_bf16_f32 v0, v23, s0
	ds_write_b16 v111, v32 offset:2992
	v_cvt_pk_bf16_f32 v32, v39, s0
	ds_write_b16 v111, v0 offset:11696
	v_cvt_pk_bf16_f32 v0, v7, s0
	ds_write_b16 v111, v32 offset:3056
	v_cvt_pk_bf16_f32 v32, v56, s0
	ds_write_b16 v111, v0 offset:11760
	v_cvt_pk_bf16_f32 v0, v24, s0
	ds_write_b16 v111, v32 offset:4352
	v_cvt_pk_bf16_f32 v32, v40, s0
	ds_write_b16 v111, v0 offset:13056
	v_cvt_pk_bf16_f32 v0, v8, s0
	ds_write_b16 v111, v32 offset:4416
	v_cvt_pk_bf16_f32 v32, v57, s0
	ds_write_b16 v111, v0 offset:13120
	v_cvt_pk_bf16_f32 v0, v25, s0
	ds_write_b16 v111, v32 offset:4624
	v_cvt_pk_bf16_f32 v32, v41, s0
	ds_write_b16 v111, v0 offset:13328
	v_cvt_pk_bf16_f32 v0, v9, s0
	ds_write_b16 v111, v32 offset:4688
	v_cvt_pk_bf16_f32 v32, v58, s0
	ds_write_b16 v111, v0 offset:13392
	v_cvt_pk_bf16_f32 v0, v26, s0
	ds_write_b16 v111, v32 offset:4896
	v_cvt_pk_bf16_f32 v32, v42, s0
	ds_write_b16 v111, v0 offset:13600
	v_cvt_pk_bf16_f32 v0, v10, s0
	ds_write_b16 v111, v32 offset:4960
	v_cvt_pk_bf16_f32 v32, v59, s0
	ds_write_b16 v111, v0 offset:13664
	v_cvt_pk_bf16_f32 v0, v27, s0
	ds_write_b16 v111, v32 offset:5168
	v_cvt_pk_bf16_f32 v32, v43, s0
	ds_write_b16 v111, v0 offset:13872
	v_cvt_pk_bf16_f32 v0, v11, s0
	ds_write_b16 v111, v32 offset:5232
	v_cvt_pk_bf16_f32 v32, v60, s0
	ds_write_b16 v111, v0 offset:13936
	v_cvt_pk_bf16_f32 v0, v28, s0
	ds_write_b16 v111, v32 offset:6528
	v_cvt_pk_bf16_f32 v32, v44, s0
	ds_write_b16 v111, v0 offset:15232
	v_cvt_pk_bf16_f32 v0, v12, s0
	ds_write_b16 v111, v32 offset:6592
	v_cvt_pk_bf16_f32 v32, v61, s0
	ds_write_b16 v111, v0 offset:15296
	v_cvt_pk_bf16_f32 v0, v29, s0
	ds_write_b16 v111, v32 offset:6800
	v_cvt_pk_bf16_f32 v32, v45, s0
	ds_write_b16 v111, v0 offset:15504
	v_cvt_pk_bf16_f32 v0, v13, s0
	ds_write_b16 v111, v32 offset:6864
	v_cvt_pk_bf16_f32 v32, v62, s0
	ds_write_b16 v111, v0 offset:15568
	v_cvt_pk_bf16_f32 v0, v30, s0
	ds_write_b16 v111, v32 offset:7072
	v_cvt_pk_bf16_f32 v32, v46, s0
	ds_write_b16 v111, v0 offset:15776
	v_cvt_pk_bf16_f32 v0, v14, s0
	ds_write_b16 v111, v32 offset:7136
	v_cvt_pk_bf16_f32 v32, v63, s0
	ds_write_b16 v111, v0 offset:15840
	v_cvt_pk_bf16_f32 v0, v31, s0
	v_cvt_pk_bf16_f32 v48, v48, s0
	ds_write_b16 v111, v32 offset:7344
	v_cvt_pk_bf16_f32 v32, v47, s0
	v_cvt_pk_bf16_f32 v16, v16, s0
	ds_write_b16 v111, v0 offset:16048
	v_cvt_pk_bf16_f32 v0, v15, s0
	v_mov_b32_e32 v15, v110
	ds_write_b16 v111, v48
	ds_write_b16 v111, v32 offset:7408
	ds_write_b16 v111, v16 offset:8704
	ds_write_b16 v111, v0 offset:16112
	s_waitcnt lgkmcnt(0)
	s_barrier
	v_mov_b64_e32 v[2:3], s[4:5]
	v_lshlrev_b32_e32 v0, 3, v15
	v_and_b32_e32 v0, 0x78, v0
	v_ashrrev_i32_e32 v1, 4, v15
	v_lshlrev_b32_e32 v96, 1, v0
	v_add_u32_e32 v0, s63, v1
	s_lshl_b32 s16, s26, 10
	v_mad_i64_i32 v[2:3], s[0:1], v0, s60, v[2:3]
	v_lshl_add_u64 v[2:3], s[16:17], 1, v[2:3]
	v_lshl_add_u64 v[2:3], s[22:23], 1, v[2:3]
	v_lshl_add_u64 v[2:3], v[2:3], 0, v[96:97]
	global_load_dwordx4 v[6:9], v[2:3], off
	v_add_co_u32_e32 v80, vcc, 0x18000, v2
	s_nop 1
	v_addc_co_u32_e32 v81, vcc, 0, v3, vcc
	global_load_dwordx4 v[24:27], v[80:81], off
	v_add_co_u32_e32 v80, vcc, 0x30000, v2
	s_nop 1
	v_addc_co_u32_e32 v81, vcc, 0, v3, vcc
	global_load_dwordx4 v[28:31], v[80:81], off
	v_add_co_u32_e32 v80, vcc, 0x48000, v2
	s_nop 1
	v_addc_co_u32_e32 v81, vcc, 0, v3, vcc
	global_load_dwordx4 v[32:35], v[80:81], off
	v_add_co_u32_e32 v80, vcc, 0x60000, v2
	s_nop 1
	v_addc_co_u32_e32 v81, vcc, 0, v3, vcc
	global_load_dwordx4 v[36:39], v[80:81], off
	v_add_co_u32_e32 v80, vcc, 0x78000, v2
	s_nop 1
	v_addc_co_u32_e32 v81, vcc, 0, v3, vcc
	global_load_dwordx4 v[40:43], v[80:81], off
	v_add_co_u32_e32 v80, vcc, 0x90000, v2
	s_nop 1
	v_addc_co_u32_e32 v81, vcc, 0, v3, vcc
	global_load_dwordx4 v[44:47], v[80:81], off
	v_add_co_u32_e32 v80, vcc, 0xa8000, v2
	s_nop 1
	v_addc_co_u32_e32 v81, vcc, 0, v3, vcc
	global_load_dwordx4 v[48:51], v[80:81], off
	v_add_u32_e32 v14, 32, v96
	v_mad_u64_u32 v[2:3], s[0:1], v1, s54, v[14:15]
	ds_read_b128 v[2:5], v2
	v_ashrrev_i32_e32 v1, 31, v0
	v_lshlrev_b64 v[0:1], 11, v[0:1]
	v_lshl_add_u64 v[0:1], s[24:25], 0, v[0:1]
	v_lshl_add_u64 v[16:17], v[0:1], 0, v[96:97]
	v_cndmask_b32_e64 v1, 0, 1, s[44:45]
	v_mov_b32_e32 v0, 0
	v_cmp_ne_u32_e64 s[0:1], 1, v1
	s_andn2_b64 vcc, exec, s[44:45]
	v_mov_b32_e32 v10, 0
	v_mov_b32_e32 v11, 0
	v_mov_b32_e32 v12, 0
	v_mov_b32_e32 v13, 0
	s_cbranch_vccnz .LBB0_3737
	global_load_dwordx4 v[10:13], v[16:17], off
	v_add_co_u32_e32 v80, vcc, 0x8000, v16
	s_nop 1
	v_addc_co_u32_e32 v81, vcc, 0, v17, vcc
	global_load_dwordx4 v[52:55], v[80:81], off
	v_add_co_u32_e32 v80, vcc, 0x10000, v16
	s_nop 1
	v_addc_co_u32_e32 v81, vcc, 0, v17, vcc
	global_load_dwordx4 v[56:59], v[80:81], off
	v_add_co_u32_e32 v80, vcc, 0x18000, v16
	s_nop 1
	v_addc_co_u32_e32 v81, vcc, 0, v17, vcc
	global_load_dwordx4 v[60:63], v[80:81], off
	v_add_co_u32_e32 v80, vcc, 0x20000, v16
	s_nop 1
	v_addc_co_u32_e32 v81, vcc, 0, v17, vcc
	global_load_dwordx4 v[64:67], v[80:81], off
	v_add_co_u32_e32 v80, vcc, 0x28000, v16
	s_nop 1
	v_addc_co_u32_e32 v81, vcc, 0, v17, vcc
	global_load_dwordx4 v[68:71], v[80:81], off
	v_add_co_u32_e32 v80, vcc, 0x30000, v16
	s_nop 1
	v_addc_co_u32_e32 v81, vcc, 0, v17, vcc
	global_load_dwordx4 v[72:75], v[80:81], off
	v_add_co_u32_e32 v80, vcc, 0x38000, v16
	s_nop 1
	v_addc_co_u32_e32 v81, vcc, 0, v17, vcc
	global_load_dwordx4 v[76:79], v[80:81], off

.LBB0_3806:
	s_setprio 1
	ds_read_b128 v[140:143], v103
	ds_read_b128 v[144:147], v104 offset:36864
	ds_read_b128 v[148:151], v103 offset:32
	ds_read_b128 v[192:195], v104 offset:36896
	ds_read_b128 v[196:199], v104 offset:41472
	ds_read_b128 v[200:203], v103 offset:4608
	s_waitcnt lgkmcnt(4)
	v_mfma_f32_32x32x16_bf16 v[48:63], v[140:143], v[144:147], v[48:63]
	ds_read_b128 v[204:207], v104 offset:41504
	global_load_dwordx4 v[108:111], v168, s[98:99] offset:3840
	global_load_dwordx4 v[112:115], v170, s[98:99] offset:3840
	s_waitcnt vmcnt(9)
	ds_write_b128 v105, v[68:71] offset:18432
	s_waitcnt lgkmcnt(3)
	v_mfma_f32_32x32x16_bf16 v[32:47], v[140:143], v[196:199], v[32:47]
	ds_read_b128 v[208:211], v103 offset:4640
	global_load_dwordx4 v[116:119], v172, s[98:99] offset:3840
	global_load_dwordx4 v[120:123], v174, s[98:99] offset:3840
	s_waitcnt lgkmcnt(3)
	v_mfma_f32_32x32x16_bf16 v[16:31], v[200:203], v[144:147], v[16:31]
	global_load_dwordx4 v[124:127], v176, s[98:99] offset:3840
	global_load_dwordx4 v[128:131], v178, s[98:99] offset:3840
	s_waitcnt vmcnt(11)
	ds_write_b128 v105, v[84:87] offset:23040
	v_mfma_f32_32x32x16_bf16 v[0:15], v[200:203], v[196:199], v[0:15]
	ds_read_b128 v[212:215], v103 offset:64
	ds_read_b128 v[216:219], v104 offset:36928
	global_load_dwordx4 v[132:135], v180, s[98:99] offset:3840
	global_load_dwordx4 v[136:139], v182, s[98:99] offset:3840
	v_mfma_f32_32x32x16_bf16 v[48:63], v[148:151], v[192:195], v[48:63]
	ds_read_b128 v[220:223], v104 offset:41536
	s_waitcnt vmcnt(12)
	ds_write_b128 v105, v[88:91] offset:27648
	s_waitcnt lgkmcnt(7)
	v_mfma_f32_32x32x16_bf16 v[32:47], v[148:151], v[204:207], v[32:47]
	ds_read_b128 v[224:227], v103 offset:4672
	s_waitcnt lgkmcnt(6)
	v_mfma_f32_32x32x16_bf16 v[16:31], v[208:211], v[192:195], v[16:31]
	s_waitcnt vmcnt(11)
	ds_write_b128 v105, v[92:95] offset:32256
	v_mfma_f32_32x32x16_bf16 v[0:15], v[208:211], v[204:207], v[0:15]
	ds_read_b128 v[228:231], v103 offset:96
	ds_read_b128 v[140:143], v104 offset:36960
	s_waitcnt lgkmcnt(6)
	v_mfma_f32_32x32x16_bf16 v[48:63], v[212:215], v[216:219], v[48:63]
	ds_read_b128 v[144:147], v104 offset:41568
	ds_write_b128 v105, v[64:67] offset:55296
	s_waitcnt lgkmcnt(7)
	v_mfma_f32_32x32x16_bf16 v[32:47], v[212:215], v[220:223], v[32:47]
	ds_read_b128 v[196:199], v103 offset:4704
	s_waitcnt lgkmcnt(6)
	v_mfma_f32_32x32x16_bf16 v[16:31], v[224:227], v[216:219], v[16:31]
	s_waitcnt vmcnt(10)
	ds_write_b128 v105, v[72:75] offset:59904
	v_mfma_f32_32x32x16_bf16 v[0:15], v[224:227], v[220:223], v[0:15]
	s_waitcnt lgkmcnt(4)
	v_mfma_f32_32x32x16_bf16 v[48:63], v[228:231], v[140:143], v[48:63]
	s_waitcnt vmcnt(9)
	ds_write_b128 v105, v[76:79] offset:64512
	s_waitcnt lgkmcnt(4)
	v_mfma_f32_32x32x16_bf16 v[32:47], v[228:231], v[144:147], v[32:47]
	s_waitcnt lgkmcnt(2)
	v_mfma_f32_32x32x16_bf16 v[16:31], v[196:199], v[140:143], v[16:31]
	s_waitcnt vmcnt(8)
	ds_write_b128 v106, v[80:83] offset:13824
	v_mfma_f32_32x32x16_bf16 v[0:15], v[196:199], v[144:147], v[0:15]
	s_setprio 0
	s_waitcnt lgkmcnt(0)
	s_barrier
	s_setprio 1
	ds_read_b128 v[140:143], v103 offset:18432
	ds_read_b128 v[144:147], v104 offset:55296
	ds_read_b128 v[148:151], v103 offset:18464
	ds_read_b128 v[192:195], v104 offset:55328
	ds_read_b128 v[196:199], v104 offset:59904
	ds_read_b128 v[200:203], v103 offset:23040
	s_waitcnt lgkmcnt(4)
	v_mfma_f32_32x32x16_bf16 v[48:63], v[140:143], v[144:147], v[48:63]
	ds_read_b128 v[204:207], v104 offset:59936
	global_load_dwordx4 v[68:71], v168, s[98:99] offset:3968
	global_load_dwordx4 v[84:87], v170, s[98:99] offset:3968
	s_waitcnt vmcnt(9)
	ds_write_b128 v105, v[108:111]
	s_waitcnt lgkmcnt(3)
	v_mfma_f32_32x32x16_bf16 v[32:47], v[140:143], v[196:199], v[32:47]
	ds_read_b128 v[208:211], v103 offset:23072
	global_load_dwordx4 v[88:91], v172, s[98:99] offset:3968
	global_load_dwordx4 v[92:95], v174, s[98:99] offset:3968
	s_waitcnt lgkmcnt(3)
	v_mfma_f32_32x32x16_bf16 v[16:31], v[200:203], v[144:147], v[16:31]
	global_load_dwordx4 v[64:67], v176, s[98:99] offset:3968
	global_load_dwordx4 v[72:75], v178, s[98:99] offset:3968
	s_waitcnt vmcnt(12)
	ds_write_b128 v105, v[112:115] offset:4608
	v_mfma_f32_32x32x16_bf16 v[0:15], v[200:203], v[196:199], v[0:15]
	ds_read_b128 v[212:215], v103 offset:18496
	ds_read_b128 v[216:219], v104 offset:55360
	global_load_dwordx4 v[76:79], v180, s[98:99] offset:3968
	global_load_dwordx4 v[80:83], v182, s[98:99] offset:3968
	v_mfma_f32_32x32x16_bf16 v[48:63], v[148:151], v[192:195], v[48:63]
	ds_read_b128 v[220:223], v104 offset:59968
	s_add_u32 s98, s98, 0x100
	s_addc_u32 s99, s99, 0
	s_add_i32 s10, s10, 2
	s_cmp_lt_u32 s10, 11
	s_waitcnt vmcnt(13)
	ds_write_b128 v105, v[116:119] offset:9216
	s_waitcnt lgkmcnt(7)
	v_mfma_f32_32x32x16_bf16 v[32:47], v[148:151], v[204:207], v[32:47]
	ds_read_b128 v[224:227], v103 offset:23104
	s_waitcnt lgkmcnt(6)
	v_mfma_f32_32x32x16_bf16 v[16:31], v[208:211], v[192:195], v[16:31]
	s_waitcnt vmcnt(12)
	ds_write_b128 v105, v[120:123] offset:13824
	v_mfma_f32_32x32x16_bf16 v[0:15], v[208:211], v[204:207], v[0:15]
	ds_read_b128 v[228:231], v103 offset:18528
	ds_read_b128 v[140:143], v104 offset:55392
	s_waitcnt lgkmcnt(6)
	v_mfma_f32_32x32x16_bf16 v[48:63], v[212:215], v[216:219], v[48:63]
	ds_read_b128 v[144:147], v104 offset:60000
	s_waitcnt vmcnt(11)
	ds_write_b128 v105, v[124:127] offset:36864
	s_waitcnt lgkmcnt(7)
	v_mfma_f32_32x32x16_bf16 v[32:47], v[212:215], v[220:223], v[32:47]
	ds_read_b128 v[196:199], v103 offset:23136
	s_waitcnt lgkmcnt(6)
	v_mfma_f32_32x32x16_bf16 v[16:31], v[224:227], v[216:219], v[16:31]
	s_waitcnt vmcnt(10)
	ds_write_b128 v105, v[128:131] offset:41472
	v_mfma_f32_32x32x16_bf16 v[0:15], v[224:227], v[220:223], v[0:15]
	s_waitcnt lgkmcnt(4)
	v_mfma_f32_32x32x16_bf16 v[48:63], v[228:231], v[140:143], v[48:63]
	s_waitcnt vmcnt(9)
	ds_write_b128 v105, v[132:135] offset:46080
	s_waitcnt lgkmcnt(4)
	v_mfma_f32_32x32x16_bf16 v[32:47], v[228:231], v[144:147], v[32:47]
	s_waitcnt lgkmcnt(2)
	v_mfma_f32_32x32x16_bf16 v[16:31], v[196:199], v[140:143], v[16:31]
	s_waitcnt vmcnt(8)
	ds_write_b128 v105, v[136:139] offset:50688
	v_mfma_f32_32x32x16_bf16 v[0:15], v[196:199], v[144:147], v[0:15]
	s_setprio 0
	s_waitcnt lgkmcnt(0)
	s_barrier
	s_cbranch_scc1 .LBB0_3806
	s_setprio 1
	ds_read_b128 v[98:101], v103
	ds_read_b128 v[108:111], v104 offset:36864
	ds_read_b128 v[112:115], v103 offset:32
	ds_read_b128 v[192:195], v104 offset:36896
	ds_read_b128 v[196:199], v104 offset:41472
	ds_read_b128 v[200:203], v103 offset:4608
	s_waitcnt lgkmcnt(4)
	v_mfma_f32_32x32x16_bf16 v[48:63], v[98:101], v[108:111], v[48:63]
	ds_read_b128 v[204:207], v104 offset:41504
	s_waitcnt vmcnt(7)
	ds_write_b128 v105, v[68:71] offset:18432
	s_waitcnt lgkmcnt(3)
	v_mfma_f32_32x32x16_bf16 v[32:47], v[98:101], v[196:199], v[32:47]
	ds_read_b128 v[208:211], v103 offset:4640
	s_waitcnt lgkmcnt(3)
	v_mfma_f32_32x32x16_bf16 v[16:31], v[200:203], v[108:111], v[16:31]
	s_waitcnt vmcnt(6)
	ds_write_b128 v105, v[84:87] offset:23040
	v_mfma_f32_32x32x16_bf16 v[0:15], v[200:203], v[196:199], v[0:15]
	ds_read_b128 v[212:215], v103 offset:64
	ds_read_b128 v[216:219], v104 offset:36928
	v_mfma_f32_32x32x16_bf16 v[48:63], v[112:115], v[192:195], v[48:63]
	ds_read_b128 v[220:223], v104 offset:41536
	s_waitcnt vmcnt(5)
	ds_write_b128 v105, v[88:91] offset:27648
	s_waitcnt lgkmcnt(7)
	v_mfma_f32_32x32x16_bf16 v[32:47], v[112:115], v[204:207], v[32:47]
	ds_read_b128 v[224:227], v103 offset:4672
	s_waitcnt lgkmcnt(6)
	v_mfma_f32_32x32x16_bf16 v[16:31], v[208:211], v[192:195], v[16:31]
	s_waitcnt vmcnt(4)
	ds_write_b128 v105, v[92:95] offset:32256
	v_mfma_f32_32x32x16_bf16 v[0:15], v[208:211], v[204:207], v[0:15]
	ds_read_b128 v[228:231], v103 offset:96
	ds_read_b128 v[98:101], v104 offset:41568
	s_waitcnt lgkmcnt(6)
	v_mfma_f32_32x32x16_bf16 v[48:63], v[212:215], v[216:219], v[48:63]
	ds_read_b128 v[108:111], v104 offset:36960
	ds_read_b128 v[196:199], v103 offset:4704
	s_waitcnt vmcnt(3)
	ds_write_b128 v105, v[64:67] offset:55296
	s_waitcnt lgkmcnt(8)
	v_mfma_f32_32x32x16_bf16 v[32:47], v[212:215], v[220:223], v[32:47]
	s_waitcnt lgkmcnt(6)
	v_mfma_f32_32x32x16_bf16 v[16:31], v[224:227], v[216:219], v[16:31]
	s_waitcnt vmcnt(2)
	ds_write_b128 v105, v[72:75] offset:59904
	v_mfma_f32_32x32x16_bf16 v[0:15], v[224:227], v[220:223], v[0:15]
	s_waitcnt lgkmcnt(4)
	v_mfma_f32_32x32x16_bf16 v[32:47], v[228:231], v[98:101], v[32:47]
	s_waitcnt vmcnt(1)
	ds_write_b128 v105, v[76:79] offset:64512
	s_waitcnt lgkmcnt(3)
	v_mfma_f32_32x32x16_bf16 v[16:31], v[196:199], v[108:111], v[16:31]
	v_mfma_f32_32x32x16_bf16 v[0:15], v[196:199], v[98:101], v[0:15]
	s_waitcnt vmcnt(0)
	ds_write_b128 v106, v[80:83] offset:13824
	v_mfma_f32_32x32x16_bf16 v[48:63], v[228:231], v[108:111], v[48:63]
	s_setprio 0
	s_waitcnt lgkmcnt(0)
	s_barrier
	s_setprio 1
	ds_read_b128 v[64:67], v103 offset:18432
	ds_read_b128 v[68:71], v104 offset:55296
	ds_read_b128 v[72:75], v103 offset:18464
	ds_read_b128 v[192:195], v104 offset:55328
	ds_read_b128 v[196:199], v104 offset:59904
	ds_read_b128 v[200:203], v103 offset:23040
	s_waitcnt lgkmcnt(4)
	v_mfma_f32_32x32x16_bf16 v[48:63], v[64:67], v[68:71], v[48:63]
	ds_read_b128 v[204:207], v104 offset:59936
	s_waitcnt lgkmcnt(2)
	v_mfma_f32_32x32x16_bf16 v[32:47], v[64:67], v[196:199], v[32:47]
	ds_read_b128 v[208:211], v103 offset:23072
	s_waitcnt lgkmcnt(2)
	v_mfma_f32_32x32x16_bf16 v[16:31], v[200:203], v[68:71], v[16:31]
	v_mfma_f32_32x32x16_bf16 v[0:15], v[200:203], v[196:199], v[0:15]
	ds_read_b128 v[212:215], v103 offset:18496
	ds_read_b128 v[216:219], v104 offset:55360
	v_mfma_f32_32x32x16_bf16 v[48:63], v[72:75], v[192:195], v[48:63]
	ds_read_b128 v[220:223], v104 offset:59968
	s_waitcnt lgkmcnt(4)
	v_mfma_f32_32x32x16_bf16 v[32:47], v[72:75], v[204:207], v[32:47]
	ds_read_b128 v[224:227], v103 offset:23104
	s_waitcnt lgkmcnt(4)
	v_mfma_f32_32x32x16_bf16 v[16:31], v[208:211], v[192:195], v[16:31]
	v_mfma_f32_32x32x16_bf16 v[0:15], v[208:211], v[204:207], v[0:15]
	ds_read_b128 v[228:231], v103 offset:18528
	ds_read_b128 v[64:67], v104 offset:60000
	s_waitcnt lgkmcnt(4)
	v_mfma_f32_32x32x16_bf16 v[48:63], v[212:215], v[216:219], v[48:63]
	ds_read_b128 v[68:71], v104 offset:55392
	ds_read_b128 v[196:199], v103 offset:23136
	s_waitcnt lgkmcnt(5)
	v_mfma_f32_32x32x16_bf16 v[32:47], v[212:215], v[220:223], v[32:47]
	s_waitcnt lgkmcnt(4)
	v_mfma_f32_32x32x16_bf16 v[16:31], v[224:227], v[216:219], v[16:31]
	v_mfma_f32_32x32x16_bf16 v[0:15], v[224:227], v[220:223], v[0:15]
	s_waitcnt lgkmcnt(2)
	v_mfma_f32_32x32x16_bf16 v[32:47], v[228:231], v[64:67], v[32:47]
	s_waitcnt lgkmcnt(0)
	v_mfma_f32_32x32x16_bf16 v[16:31], v[196:199], v[68:71], v[16:31]
	v_mfma_f32_32x32x16_bf16 v[0:15], v[196:199], v[64:67], v[0:15]
	v_mfma_f32_32x32x16_bf16 v[48:63], v[228:231], v[68:71], v[48:63]
	s_setprio 0
	s_addk_i32 s0, 0xf000
	s_lshr_b32 s10, s0, 10
	s_mulk_i32 s10, 0x1800
	s_add_i32 s10, s10, 0x9000
	s_and_b64 s[58:59], s[8:9], exec
	s_cselect_b32 s10, 0x7800, s10
	v_mov_b32_e32 v68, v234
	s_barrier
	s_lshl_b64 s[58:59], s[10:11], 2
	s_add_u32 s58, s30, s58
	v_and_b32_e32 v69, 0x5f, v68
	v_or_b32_e32 v64, s25, v69
	s_addc_u32 s59, s31, s59
	v_ashrrev_i32_e32 v65, 31, v64
	v_lshl_add_u64 v[64:65], v[64:65], 2, s[58:59]
	v_lshl_add_u64 v[66:67], v[64:65], 0, s[14:15]
	v_add_co_u32_e32 v64, vcc, s51, v64
	v_lshlrev_b32_e32 v69, 2, v69
	s_nop 0
	v_addc_co_u32_e32 v65, vcc, 0, v65, vcc
	global_load_dword v64, v[64:65], off
	s_nop 0
	global_load_dword v65, v[66:67], off offset:128
	v_lshrrev_b32_e32 v67, 3, v68
	v_lshrrev_b32_e32 v66, 1, v68
	v_and_b32_e32 v67, 4, v67
	v_and_or_b32 v66, v66, s42, v67
	v_mul_lo_u32 v66, v66, s52
	v_add3_u32 v66, 32, v69, v66
	v_add_u32_e32 v67, 0x400, v66
	v_add_u32_e32 v69, 0x1000, v66
	v_add_u32_e32 v70, 0x1400, v66
	v_add_u32_e32 v71, 0x2000, v66
	v_add_u32_e32 v72, 0x2400, v66
	v_add_u32_e32 v73, 0x3000, v66
	v_add_u32_e32 v74, 0x3200, v66
	v_add_u32_e32 v75, 0x3400, v66
	v_add_u32_e32 v76, 0x3600, v66
	v_add_u32_e32 v77, 0x4000, v66
	v_readlane_b32 s80, v250, 6
	v_readlane_b32 s81, v250, 7
	v_readlane_b32 s82, v250, 8
	v_readlane_b32 s83, v250, 9
	v_readlane_b32 s92, v250, 18
	v_readlane_b32 s93, v250, 19
	v_readlane_b32 s94, v250, 20
	v_readlane_b32 s95, v250, 21
	s_mov_b64 s[80:81], s[92:93]
	s_mov_b64 s[82:83], s[94:95]
	s_lshl_b32 s1, s1, 19
	s_add_u32 s10, s28, s1
	s_mov_b32 s1, s11
	v_readlane_b32 s84, v250, 10
	v_readlane_b32 s85, v250, 11
	v_readlane_b32 s86, v250, 12
	v_readlane_b32 s87, v250, 13
	v_readlane_b32 s88, v250, 14
	v_readlane_b32 s89, v250, 15
	v_readlane_b32 s90, v250, 16
	v_readlane_b32 s91, v250, 17
	s_waitcnt vmcnt(1)
	v_mul_f32_e32 v48, v48, v64
	s_waitcnt vmcnt(0)
	v_mul_f32_e32 v32, v32, v65
	v_mul_f32_e32 v16, v16, v64
	v_mul_f32_e32 v0, v0, v65
	v_mul_f32_e32 v49, v49, v64
	v_mul_f32_e32 v33, v33, v65
	v_mul_f32_e32 v50, v50, v64
	v_mul_f32_e32 v34, v34, v65
	v_mul_f32_e32 v51, v51, v64
	v_mul_f32_e32 v35, v35, v65
	v_mul_f32_e32 v52, v52, v64
	v_mul_f32_e32 v36, v36, v65
	v_mul_f32_e32 v53, v53, v64
	v_mul_f32_e32 v37, v37, v65
	v_mul_f32_e32 v54, v54, v64
	v_mul_f32_e32 v38, v38, v65
	v_mul_f32_e32 v55, v55, v64
	v_mul_f32_e32 v39, v39, v65
	v_mul_f32_e32 v56, v56, v64
	v_mul_f32_e32 v40, v40, v65
	v_mul_f32_e32 v57, v57, v64
	v_mul_f32_e32 v41, v41, v65
	v_mul_f32_e32 v58, v58, v64
	v_mul_f32_e32 v42, v42, v65
	v_mul_f32_e32 v59, v59, v64
	v_mul_f32_e32 v43, v43, v65
	v_mul_f32_e32 v60, v60, v64
	v_mul_f32_e32 v44, v44, v65
	v_mul_f32_e32 v61, v61, v64
	v_mul_f32_e32 v45, v45, v65
	v_mul_f32_e32 v62, v62, v64
	v_mul_f32_e32 v46, v46, v65
	v_mul_f32_e32 v63, v63, v64
	v_mul_f32_e32 v47, v47, v65
	ds_write2_b32 v66, v48, v32 offset1:32
	ds_write2_b32 v66, v49, v33 offset0:132 offset1:164
	ds_write2_b32 v67, v50, v34 offset0:8 offset1:40
	ds_write2_b32 v67, v51, v35 offset0:140 offset1:172
	ds_write2_b32 v69, v52, v36 offset0:32 offset1:64
	ds_write2_b32 v69, v53, v37 offset0:164 offset1:196
	ds_write2_b32 v70, v54, v38 offset0:40 offset1:72
	ds_write2_b32 v70, v55, v39 offset0:172 offset1:204
	ds_write2_b32 v71, v56, v40 offset0:64 offset1:96
	ds_write2_b32 v71, v57, v41 offset0:196 offset1:228
	ds_write2_b32 v72, v58, v42 offset0:72 offset1:104
	ds_write2_b32 v72, v59, v43 offset0:204 offset1:236
	ds_write2_b32 v73, v60, v44 offset0:96 offset1:128
	ds_write2_b32 v74, v61, v45 offset0:100 offset1:132
	ds_write2_b32 v75, v62, v46 offset0:104 offset1:136
	ds_write2_b32 v76, v63, v47 offset0:108 offset1:140
	ds_write2_b32 v77, v16, v0 offset0:128 offset1:160
	v_mul_f32_e32 v0, v17, v64
	v_mul_f32_e32 v1, v1, v65
	v_add_u32_e32 v16, 0x4400, v66
	ds_write2_b32 v16, v0, v1 offset0:4 offset1:36
	v_mul_f32_e32 v0, v18, v64
	v_mul_f32_e32 v1, v2, v65
	ds_write2_b32 v16, v0, v1 offset0:136 offset1:168
	v_mul_f32_e32 v0, v19, v64
	v_mul_f32_e32 v1, v3, v65
	v_add_u32_e32 v2, 0x4800, v66
	ds_write2_b32 v2, v0, v1 offset0:12 offset1:44
	v_mul_f32_e32 v0, v20, v64
	v_mul_f32_e32 v1, v4, v65
	v_add_u32_e32 v2, 0x5000, v66
	ds_write2_b32 v2, v0, v1 offset0:160 offset1:192
	v_mul_f32_e32 v0, v21, v64
	v_mul_f32_e32 v1, v5, v65
	v_add_u32_e32 v2, 0x5400, v66
	ds_write2_b32 v2, v0, v1 offset0:36 offset1:68
	v_mul_f32_e32 v0, v22, v64
	v_mul_f32_e32 v1, v6, v65
	ds_write2_b32 v2, v0, v1 offset0:168 offset1:200
	v_mul_f32_e32 v0, v23, v64
	v_mul_f32_e32 v1, v7, v65
	v_add_u32_e32 v2, 0x5800, v66
	ds_write2_b32 v2, v0, v1 offset0:44 offset1:76
	v_mul_f32_e32 v0, v24, v64
	v_mul_f32_e32 v1, v8, v65
	v_add_u32_e32 v2, 0x6000, v66
	ds_write2_b32 v2, v0, v1 offset0:192 offset1:224
	v_mul_f32_e32 v0, v25, v64
	v_mul_f32_e32 v1, v9, v65
	v_add_u32_e32 v2, 0x6400, v66
	ds_write2_b32 v2, v0, v1 offset0:68 offset1:100
	v_mul_f32_e32 v0, v26, v64
	v_mul_f32_e32 v1, v10, v65
	ds_write2_b32 v2, v0, v1 offset0:200 offset1:232
	v_mul_f32_e32 v0, v27, v64
	v_mul_f32_e32 v1, v11, v65
	v_add_u32_e32 v2, 0x6800, v66
	ds_write2_b32 v2, v0, v1 offset0:76 offset1:108
	v_mul_f32_e32 v0, v28, v64
	v_mul_f32_e32 v1, v12, v65
	v_add_u32_e32 v2, 0x7200, v66
	ds_write2_b32 v2, v0, v1 offset0:96 offset1:128
	v_mul_f32_e32 v0, v29, v64
	v_mul_f32_e32 v1, v13, v65
	v_add_u32_e32 v2, 0x7400, v66
	ds_write2_b32 v2, v0, v1 offset0:100 offset1:132
	v_mul_f32_e32 v0, v30, v64
	v_mul_f32_e32 v1, v14, v65
	v_add_u32_e32 v2, 0x7600, v66
	v_and_b32_e32 v12, 31, v68
	ds_write2_b32 v2, v0, v1 offset0:104 offset1:136
	v_mul_f32_e32 v0, v31, v64
	v_mul_f32_e32 v1, v15, v65
	v_add_u32_e32 v2, 0x7800, v66
	v_lshlrev_b32_e32 v10, 2, v12
	ds_write2_b32 v2, v0, v1 offset0:108 offset1:140
	v_or_b32_e32 v0, s25, v10
	v_ashrrev_i32_e32 v1, 31, v0
	v_lshlrev_b64 v[0:1], 2, v[0:1]
	v_lshl_add_u64 v[2:3], s[80:81], 0, v[0:1]
	v_lshl_add_u64 v[4:5], s[82:83], 0, v[0:1]
	s_waitcnt lgkmcnt(0)
	s_barrier
	global_load_dwordx4 v[0:3], v[2:3], off
	s_nop 0
	global_load_dwordx4 v[4:7], v[4:5], off
	v_and_b32_e32 v8, 64, v102
	v_add_u32_e32 v8, 64, v8
	v_xor_b32_e32 v9, 1, v102
	v_cmp_lt_i32_e32 vcc, v9, v8
	s_addc_u32 s25, s29, 0
	s_lshl_b64 s[0:1], s[0:1], 12
	v_cndmask_b32_e32 v9, v102, v9, vcc
	v_lshlrev_b32_e32 v30, 2, v9
	v_xor_b32_e32 v9, 2, v102
	v_cmp_lt_i32_e32 vcc, v9, v8
	s_add_u32 s58, s17, s0
	s_addc_u32 s59, s19, s1
	v_cndmask_b32_e32 v9, v102, v9, vcc
	v_lshlrev_b32_e32 v31, 2, v9
	v_xor_b32_e32 v9, 4, v102
	v_cmp_lt_i32_e32 vcc, v9, v8
	s_and_b64 s[0:1], s[8:9], exec
	v_add_u32_e32 v10, s22, v10
	v_cndmask_b32_e32 v9, v102, v9, vcc
	v_lshlrev_b32_e32 v32, 2, v9
	v_xor_b32_e32 v9, 8, v102
	v_cmp_lt_i32_e32 vcc, v9, v8
	v_ashrrev_i32_e32 v22, 5, v68
	s_cselect_b32 s59, s25, s59
	s_cselect_b32 s58, s10, s58
	v_cndmask_b32_e32 v9, v102, v9, vcc
	v_ashrrev_i32_e32 v11, 31, v10
	s_add_i32 s10, s24, s35
	v_cmp_eq_u32_e64 s[0:1], 0, v12
	v_lshlrev_b32_e32 v33, 2, v9
	v_xor_b32_e32 v9, 16, v102
	v_lshlrev_b64 v[24:25], 2, v[10:11]
	v_lshlrev_b32_e32 v11, 4, v12
	v_add_u32_e32 v12, s10, v22
	s_add_i32 s10, s24, s36
	s_add_i32 s24, s24, s37
	v_cmp_lt_i32_e32 vcc, v9, v8
	v_add_u32_e32 v16, s10, v22
	v_add_u32_e32 v20, s24, v22
	v_cndmask_b32_e32 v8, v102, v9, vcc
	v_ashrrev_i32_e32 v23, 31, v22
	v_mul_lo_u32 v10, v22, s52
	v_ashrrev_i32_e32 v13, 31, v12
	v_ashrrev_i32_e32 v17, 31, v16
	v_ashrrev_i32_e32 v21, 31, v20
	v_add_u32_e32 v26, s23, v22
	v_lshlrev_b32_e32 v34, 2, v8
	v_lshlrev_b64 v[8:9], 12, v[22:23]
	v_add3_u32 v35, v10, v11, 32
	v_lshlrev_b64 v[10:11], 12, v[12:13]
	v_lshlrev_b32_e32 v12, 1, v12
	v_lshlrev_b64 v[14:15], 12, v[16:17]
	v_lshlrev_b32_e32 v16, 1, v16
	v_lshlrev_b64 v[18:19], 12, v[20:21]
	v_lshlrev_b32_e32 v20, 1, v20
	v_lshlrev_b32_e32 v22, 1, v26
	v_ashrrev_i32_e32 v27, 31, v26
	v_lshl_add_u64 v[8:9], v[8:9], 0, v[24:25]
	v_ashrrev_i32_e32 v13, 31, v12
	v_ashrrev_i32_e32 v17, 31, v16
	v_ashrrev_i32_e32 v21, 31, v20
	v_ashrrev_i32_e32 v23, 31, v22
	v_lshlrev_b64 v[26:27], 12, v[26:27]
	v_lshl_add_u64 v[8:9], s[58:59], 0, v[8:9]
	v_lshl_add_u64 v[10:11], v[10:11], 0, v[24:25]
	v_lshlrev_b64 v[12:13], 2, v[12:13]
	v_lshl_add_u64 v[14:15], v[14:15], 0, v[24:25]
	v_lshlrev_b64 v[16:17], 2, v[16:17]
	v_lshl_add_u64 v[18:19], v[18:19], 0, v[24:25]
	v_lshlrev_b64 v[20:21], 2, v[20:21]
	v_lshlrev_b64 v[22:23], 2, v[22:23]
	v_lshl_add_u64 v[24:25], v[26:27], 0, v[24:25]
	s_mov_b64 s[22:23], 0
	s_branch .LBB0_3809

.LBB0_3929:
	s_setprio 1
	ds_read_b128 v[140:143], v103
	ds_read_b128 v[144:147], v104 offset:36864
	ds_read_b128 v[148:151], v103 offset:32
	ds_read_b128 v[192:195], v104 offset:36896
	ds_read_b128 v[196:199], v104 offset:41472
	ds_read_b128 v[200:203], v103 offset:4608
	s_waitcnt lgkmcnt(4)
	v_mfma_f32_32x32x16_bf16 v[48:63], v[140:143], v[144:147], v[48:63]
	ds_read_b128 v[204:207], v104 offset:41504
	global_load_dwordx4 v[108:111], v168, s[98:99] offset:3840
	global_load_dwordx4 v[112:115], v170, s[98:99] offset:3840
	s_waitcnt vmcnt(9)
	ds_write_b128 v105, v[68:71] offset:18432
	s_waitcnt lgkmcnt(3)
	v_mfma_f32_32x32x16_bf16 v[32:47], v[140:143], v[196:199], v[32:47]
	ds_read_b128 v[208:211], v103 offset:4640
	global_load_dwordx4 v[116:119], v172, s[98:99] offset:3840
	global_load_dwordx4 v[120:123], v174, s[98:99] offset:3840
	s_waitcnt lgkmcnt(3)
	v_mfma_f32_32x32x16_bf16 v[16:31], v[200:203], v[144:147], v[16:31]
	global_load_dwordx4 v[124:127], v176, s[98:99] offset:3840
	global_load_dwordx4 v[128:131], v178, s[98:99] offset:3840
	s_waitcnt vmcnt(11)
	ds_write_b128 v105, v[84:87] offset:23040
	v_mfma_f32_32x32x16_bf16 v[0:15], v[200:203], v[196:199], v[0:15]
	ds_read_b128 v[212:215], v103 offset:64
	ds_read_b128 v[216:219], v104 offset:36928
	global_load_dwordx4 v[132:135], v180, s[98:99] offset:3840
	global_load_dwordx4 v[136:139], v182, s[98:99] offset:3840
	v_mfma_f32_32x32x16_bf16 v[48:63], v[148:151], v[192:195], v[48:63]
	ds_read_b128 v[220:223], v104 offset:41536
	s_waitcnt vmcnt(12)
	ds_write_b128 v105, v[88:91] offset:27648
	s_waitcnt lgkmcnt(7)
	v_mfma_f32_32x32x16_bf16 v[32:47], v[148:151], v[204:207], v[32:47]
	ds_read_b128 v[224:227], v103 offset:4672
	s_waitcnt lgkmcnt(6)
	v_mfma_f32_32x32x16_bf16 v[16:31], v[208:211], v[192:195], v[16:31]
	s_waitcnt vmcnt(11)
	ds_write_b128 v105, v[92:95] offset:32256
	v_mfma_f32_32x32x16_bf16 v[0:15], v[208:211], v[204:207], v[0:15]
	ds_read_b128 v[228:231], v103 offset:96
	ds_read_b128 v[140:143], v104 offset:36960
	s_waitcnt lgkmcnt(6)
	v_mfma_f32_32x32x16_bf16 v[48:63], v[212:215], v[216:219], v[48:63]
	ds_read_b128 v[144:147], v104 offset:41568
	ds_write_b128 v105, v[64:67] offset:55296
	s_waitcnt lgkmcnt(7)
	v_mfma_f32_32x32x16_bf16 v[32:47], v[212:215], v[220:223], v[32:47]
	ds_read_b128 v[196:199], v103 offset:4704
	s_waitcnt lgkmcnt(6)
	v_mfma_f32_32x32x16_bf16 v[16:31], v[224:227], v[216:219], v[16:31]
	s_waitcnt vmcnt(10)
	ds_write_b128 v105, v[72:75] offset:59904
	v_mfma_f32_32x32x16_bf16 v[0:15], v[224:227], v[220:223], v[0:15]
	s_waitcnt lgkmcnt(4)
	v_mfma_f32_32x32x16_bf16 v[48:63], v[228:231], v[140:143], v[48:63]
	s_waitcnt vmcnt(9)
	ds_write_b128 v105, v[76:79] offset:64512
	s_waitcnt lgkmcnt(4)
	v_mfma_f32_32x32x16_bf16 v[32:47], v[228:231], v[144:147], v[32:47]
	s_waitcnt lgkmcnt(2)
	v_mfma_f32_32x32x16_bf16 v[16:31], v[196:199], v[140:143], v[16:31]
	s_waitcnt vmcnt(8)
	ds_write_b128 v106, v[80:83] offset:13824
	v_mfma_f32_32x32x16_bf16 v[0:15], v[196:199], v[144:147], v[0:15]
	s_setprio 0
	s_waitcnt lgkmcnt(0)
	s_barrier
	s_setprio 1
	ds_read_b128 v[140:143], v103 offset:18432
	ds_read_b128 v[144:147], v104 offset:55296
	ds_read_b128 v[148:151], v103 offset:18464
	ds_read_b128 v[192:195], v104 offset:55328
	ds_read_b128 v[196:199], v104 offset:59904
	ds_read_b128 v[200:203], v103 offset:23040
	s_waitcnt lgkmcnt(4)
	v_mfma_f32_32x32x16_bf16 v[48:63], v[140:143], v[144:147], v[48:63]
	ds_read_b128 v[204:207], v104 offset:59936
	global_load_dwordx4 v[68:71], v168, s[98:99] offset:3968
	global_load_dwordx4 v[84:87], v170, s[98:99] offset:3968
	s_waitcnt vmcnt(9)
	ds_write_b128 v105, v[108:111]
	s_waitcnt lgkmcnt(3)
	v_mfma_f32_32x32x16_bf16 v[32:47], v[140:143], v[196:199], v[32:47]
	ds_read_b128 v[208:211], v103 offset:23072
	global_load_dwordx4 v[88:91], v172, s[98:99] offset:3968
	global_load_dwordx4 v[92:95], v174, s[98:99] offset:3968
	s_waitcnt lgkmcnt(3)
	v_mfma_f32_32x32x16_bf16 v[16:31], v[200:203], v[144:147], v[16:31]
	global_load_dwordx4 v[64:67], v176, s[98:99] offset:3968
	global_load_dwordx4 v[72:75], v178, s[98:99] offset:3968
	s_waitcnt vmcnt(12)
	ds_write_b128 v105, v[112:115] offset:4608
	v_mfma_f32_32x32x16_bf16 v[0:15], v[200:203], v[196:199], v[0:15]
	ds_read_b128 v[212:215], v103 offset:18496
	ds_read_b128 v[216:219], v104 offset:55360
	global_load_dwordx4 v[76:79], v180, s[98:99] offset:3968
	global_load_dwordx4 v[80:83], v182, s[98:99] offset:3968
	v_mfma_f32_32x32x16_bf16 v[48:63], v[148:151], v[192:195], v[48:63]
	ds_read_b128 v[220:223], v104 offset:59968
	s_add_u32 s98, s98, 0x100
	s_addc_u32 s99, s99, 0
	s_add_i32 s41, s41, 2
	s_cmp_lt_u32 s41, 11
	s_waitcnt vmcnt(13)
	ds_write_b128 v105, v[116:119] offset:9216
	s_waitcnt lgkmcnt(7)
	v_mfma_f32_32x32x16_bf16 v[32:47], v[148:151], v[204:207], v[32:47]
	ds_read_b128 v[224:227], v103 offset:23104
	s_waitcnt lgkmcnt(6)
	v_mfma_f32_32x32x16_bf16 v[16:31], v[208:211], v[192:195], v[16:31]
	s_waitcnt vmcnt(12)
	ds_write_b128 v105, v[120:123] offset:13824
	v_mfma_f32_32x32x16_bf16 v[0:15], v[208:211], v[204:207], v[0:15]
	ds_read_b128 v[228:231], v103 offset:18528
	ds_read_b128 v[140:143], v104 offset:55392
	s_waitcnt lgkmcnt(6)
	v_mfma_f32_32x32x16_bf16 v[48:63], v[212:215], v[216:219], v[48:63]
	ds_read_b128 v[144:147], v104 offset:60000
	s_waitcnt vmcnt(11)
	ds_write_b128 v105, v[124:127] offset:36864
	s_waitcnt lgkmcnt(7)
	v_mfma_f32_32x32x16_bf16 v[32:47], v[212:215], v[220:223], v[32:47]
	ds_read_b128 v[196:199], v103 offset:23136
	s_waitcnt lgkmcnt(6)
	v_mfma_f32_32x32x16_bf16 v[16:31], v[224:227], v[216:219], v[16:31]
	s_waitcnt vmcnt(10)
	ds_write_b128 v105, v[128:131] offset:41472
	v_mfma_f32_32x32x16_bf16 v[0:15], v[224:227], v[220:223], v[0:15]
	s_waitcnt lgkmcnt(4)
	v_mfma_f32_32x32x16_bf16 v[48:63], v[228:231], v[140:143], v[48:63]
	s_waitcnt vmcnt(9)
	ds_write_b128 v105, v[132:135] offset:46080
	s_waitcnt lgkmcnt(4)
	v_mfma_f32_32x32x16_bf16 v[32:47], v[228:231], v[144:147], v[32:47]
	s_waitcnt lgkmcnt(2)
	v_mfma_f32_32x32x16_bf16 v[16:31], v[196:199], v[140:143], v[16:31]
	s_waitcnt vmcnt(8)
	ds_write_b128 v105, v[136:139] offset:50688
	v_mfma_f32_32x32x16_bf16 v[0:15], v[196:199], v[144:147], v[0:15]
	s_setprio 0
	s_waitcnt lgkmcnt(0)
	s_barrier
	s_cbranch_scc1 .LBB0_3929
	s_setprio 1
	ds_read_b128 v[98:101], v103
	ds_read_b128 v[108:111], v104 offset:36864
	ds_read_b128 v[112:115], v103 offset:32
	ds_read_b128 v[192:195], v104 offset:36896
	ds_read_b128 v[196:199], v104 offset:41472
	ds_read_b128 v[200:203], v103 offset:4608
	s_waitcnt lgkmcnt(4)
	v_mfma_f32_32x32x16_bf16 v[48:63], v[98:101], v[108:111], v[48:63]
	ds_read_b128 v[204:207], v104 offset:41504
	s_waitcnt vmcnt(7)
	ds_write_b128 v105, v[68:71] offset:18432
	s_waitcnt lgkmcnt(3)
	v_mfma_f32_32x32x16_bf16 v[32:47], v[98:101], v[196:199], v[32:47]
	ds_read_b128 v[208:211], v103 offset:4640
	s_waitcnt lgkmcnt(3)
	v_mfma_f32_32x32x16_bf16 v[16:31], v[200:203], v[108:111], v[16:31]
	s_waitcnt vmcnt(6)
	ds_write_b128 v105, v[84:87] offset:23040
	v_mfma_f32_32x32x16_bf16 v[0:15], v[200:203], v[196:199], v[0:15]
	ds_read_b128 v[212:215], v103 offset:64
	ds_read_b128 v[216:219], v104 offset:36928
	v_mfma_f32_32x32x16_bf16 v[48:63], v[112:115], v[192:195], v[48:63]
	ds_read_b128 v[220:223], v104 offset:41536
	s_waitcnt vmcnt(5)
	ds_write_b128 v105, v[88:91] offset:27648
	s_waitcnt lgkmcnt(7)
	v_mfma_f32_32x32x16_bf16 v[32:47], v[112:115], v[204:207], v[32:47]
	ds_read_b128 v[224:227], v103 offset:4672
	s_waitcnt lgkmcnt(6)
	v_mfma_f32_32x32x16_bf16 v[16:31], v[208:211], v[192:195], v[16:31]
	s_waitcnt vmcnt(4)
	ds_write_b128 v105, v[92:95] offset:32256
	v_mfma_f32_32x32x16_bf16 v[0:15], v[208:211], v[204:207], v[0:15]
	ds_read_b128 v[228:231], v103 offset:96
	ds_read_b128 v[98:101], v104 offset:36960
	s_waitcnt lgkmcnt(6)
	v_mfma_f32_32x32x16_bf16 v[48:63], v[212:215], v[216:219], v[48:63]
	ds_read_b128 v[108:111], v104 offset:41568
	s_waitcnt vmcnt(3)
	ds_write_b128 v105, v[64:67] offset:55296
	s_waitcnt lgkmcnt(7)
	v_mfma_f32_32x32x16_bf16 v[32:47], v[212:215], v[220:223], v[32:47]
	ds_read_b128 v[196:199], v103 offset:4704
	s_waitcnt lgkmcnt(6)
	v_mfma_f32_32x32x16_bf16 v[16:31], v[224:227], v[216:219], v[16:31]
	s_waitcnt vmcnt(2)
	ds_write_b128 v105, v[72:75] offset:59904
	v_mfma_f32_32x32x16_bf16 v[0:15], v[224:227], v[220:223], v[0:15]
	s_waitcnt lgkmcnt(4)
	v_mfma_f32_32x32x16_bf16 v[48:63], v[228:231], v[98:101], v[48:63]
	s_waitcnt vmcnt(1)
	ds_write_b128 v105, v[76:79] offset:64512
	s_waitcnt lgkmcnt(4)
	v_mfma_f32_32x32x16_bf16 v[32:47], v[228:231], v[108:111], v[32:47]
	s_waitcnt lgkmcnt(2)
	v_mfma_f32_32x32x16_bf16 v[16:31], v[196:199], v[98:101], v[16:31]
	s_waitcnt vmcnt(0)
	ds_write_b128 v106, v[80:83] offset:13824
	v_mfma_f32_32x32x16_bf16 v[0:15], v[196:199], v[108:111], v[0:15]
	s_setprio 0
	s_waitcnt lgkmcnt(0)
	s_barrier
	s_setprio 1
	ds_read_b128 v[64:67], v103 offset:18432
	ds_read_b128 v[68:71], v104 offset:55296
	ds_read_b128 v[72:75], v103 offset:18464
	ds_read_b128 v[192:195], v104 offset:55328
	ds_read_b128 v[196:199], v104 offset:59904
	ds_read_b128 v[200:203], v103 offset:23040
	s_waitcnt lgkmcnt(4)
	v_mfma_f32_32x32x16_bf16 v[48:63], v[64:67], v[68:71], v[48:63]
	ds_read_b128 v[204:207], v104 offset:59936
	s_waitcnt lgkmcnt(2)
	v_mfma_f32_32x32x16_bf16 v[32:47], v[64:67], v[196:199], v[32:47]
	ds_read_b128 v[208:211], v103 offset:23072
	s_waitcnt lgkmcnt(2)
	v_mfma_f32_32x32x16_bf16 v[16:31], v[200:203], v[68:71], v[16:31]
	v_mfma_f32_32x32x16_bf16 v[0:15], v[200:203], v[196:199], v[0:15]
	ds_read_b128 v[212:215], v103 offset:18496
	ds_read_b128 v[216:219], v104 offset:55360
	v_mfma_f32_32x32x16_bf16 v[48:63], v[72:75], v[192:195], v[48:63]
	ds_read_b128 v[220:223], v104 offset:59968
	s_waitcnt lgkmcnt(4)
	v_mfma_f32_32x32x16_bf16 v[32:47], v[72:75], v[204:207], v[32:47]
	ds_read_b128 v[224:227], v103 offset:23104
	s_waitcnt lgkmcnt(4)
	v_mfma_f32_32x32x16_bf16 v[16:31], v[208:211], v[192:195], v[16:31]
	v_mfma_f32_32x32x16_bf16 v[0:15], v[208:211], v[204:207], v[0:15]
	ds_read_b128 v[228:231], v103 offset:18528
	ds_read_b128 v[64:67], v104 offset:55392
	s_waitcnt lgkmcnt(4)
	v_mfma_f32_32x32x16_bf16 v[48:63], v[212:215], v[216:219], v[48:63]
	ds_read_b128 v[68:71], v104 offset:60000
	s_waitcnt lgkmcnt(4)
	v_mfma_f32_32x32x16_bf16 v[32:47], v[212:215], v[220:223], v[32:47]
	ds_read_b128 v[196:199], v103 offset:23136
	s_waitcnt lgkmcnt(4)
	v_mfma_f32_32x32x16_bf16 v[16:31], v[224:227], v[216:219], v[16:31]
	v_mfma_f32_32x32x16_bf16 v[0:15], v[224:227], v[220:223], v[0:15]
	s_waitcnt lgkmcnt(2)
	v_mfma_f32_32x32x16_bf16 v[48:63], v[228:231], v[64:67], v[48:63]
	s_waitcnt lgkmcnt(1)
	v_mfma_f32_32x32x16_bf16 v[32:47], v[228:231], v[68:71], v[32:47]
	s_waitcnt lgkmcnt(0)
	v_mfma_f32_32x32x16_bf16 v[16:31], v[196:199], v[64:67], v[16:31]
	v_mfma_f32_32x32x16_bf16 v[0:15], v[196:199], v[68:71], v[0:15]
	s_setprio 0
	v_lshrrev_b32_e32 v65, 3, v102
	v_lshrrev_b32_e32 v64, 1, v102
	v_and_b32_e32 v65, 4, v65
	v_and_or_b32 v64, v64, s22, v65
	v_and_b32_e32 v65, 0x5f, v102
	v_lshlrev_b32_e32 v65, 1, v65
	v_mul_lo_u32 v64, v64, s36
	v_add3_u32 v64, 32, v65, v64
	s_nop 2
	v_cvt_pk_bf16_f32 v0, v0, s0
	s_barrier
	ds_write_b16 v64, v0 offset:8768
	v_cvt_pk_bf16_f32 v0, v17, s0
	ds_write_b16 v64, v0 offset:8976
	v_cvt_pk_bf16_f32 v0, v1, s0
	ds_write_b16 v64, v0 offset:9040
	v_cvt_pk_bf16_f32 v0, v18, s0
	v_cvt_pk_bf16_f32 v32, v32, s0
	ds_write_b16 v64, v0 offset:9248
	v_cvt_pk_bf16_f32 v0, v2, s0
	ds_write_b16 v64, v32 offset:64
	v_cvt_pk_bf16_f32 v32, v49, s0
	ds_write_b16 v64, v0 offset:9312
	v_cvt_pk_bf16_f32 v0, v19, s0
	ds_write_b16 v64, v32 offset:272
	v_cvt_pk_bf16_f32 v32, v33, s0
	ds_write_b16 v64, v0 offset:9520
	v_cvt_pk_bf16_f32 v0, v3, s0
	ds_write_b16 v64, v32 offset:336
	v_cvt_pk_bf16_f32 v32, v50, s0
	ds_write_b16 v64, v0 offset:9584
	v_cvt_pk_bf16_f32 v0, v20, s0
	ds_write_b16 v64, v32 offset:544
	v_cvt_pk_bf16_f32 v32, v34, s0
	ds_write_b16 v64, v0 offset:10880
	v_cvt_pk_bf16_f32 v0, v4, s0
	ds_write_b16 v64, v32 offset:608
	v_cvt_pk_bf16_f32 v32, v51, s0
	ds_write_b16 v64, v0 offset:10944
	v_cvt_pk_bf16_f32 v0, v21, s0
	ds_write_b16 v64, v32 offset:816
	v_cvt_pk_bf16_f32 v32, v35, s0
	ds_write_b16 v64, v0 offset:11152
	v_cvt_pk_bf16_f32 v0, v5, s0
	ds_write_b16 v64, v32 offset:880
	v_cvt_pk_bf16_f32 v32, v52, s0
	ds_write_b16 v64, v0 offset:11216
	v_cvt_pk_bf16_f32 v0, v22, s0
	ds_write_b16 v64, v32 offset:2176
	v_cvt_pk_bf16_f32 v32, v36, s0
	ds_write_b16 v64, v0 offset:11424
	v_cvt_pk_bf16_f32 v0, v6, s0
	ds_write_b16 v64, v32 offset:2240
	v_cvt_pk_bf16_f32 v32, v53, s0
	ds_write_b16 v64, v0 offset:11488
	v_cvt_pk_bf16_f32 v0, v23, s0
	ds_write_b16 v64, v32 offset:2448
	v_cvt_pk_bf16_f32 v32, v37, s0
	ds_write_b16 v64, v0 offset:11696
	v_cvt_pk_bf16_f32 v0, v7, s0
	ds_write_b16 v64, v32 offset:2512
	v_cvt_pk_bf16_f32 v32, v54, s0
	ds_write_b16 v64, v0 offset:11760
	v_cvt_pk_bf16_f32 v0, v24, s0
	ds_write_b16 v64, v32 offset:2720
	v_cvt_pk_bf16_f32 v32, v38, s0
	ds_write_b16 v64, v0 offset:13056
	v_cvt_pk_bf16_f32 v0, v8, s0
	ds_write_b16 v64, v32 offset:2784
	v_cvt_pk_bf16_f32 v32, v55, s0
	ds_write_b16 v64, v0 offset:13120
	v_cvt_pk_bf16_f32 v0, v25, s0
	ds_write_b16 v64, v32 offset:2992
	v_cvt_pk_bf16_f32 v32, v39, s0
	ds_write_b16 v64, v0 offset:13328
	v_cvt_pk_bf16_f32 v0, v9, s0
	ds_write_b16 v64, v32 offset:3056
	v_cvt_pk_bf16_f32 v32, v56, s0
	ds_write_b16 v64, v0 offset:13392
	v_cvt_pk_bf16_f32 v0, v26, s0
	ds_write_b16 v64, v32 offset:4352
	v_cvt_pk_bf16_f32 v32, v40, s0
	ds_write_b16 v64, v0 offset:13600
	v_cvt_pk_bf16_f32 v0, v10, s0
	ds_write_b16 v64, v32 offset:4416
	v_cvt_pk_bf16_f32 v32, v57, s0
	ds_write_b16 v64, v0 offset:13664
	v_cvt_pk_bf16_f32 v0, v27, s0
	ds_write_b16 v64, v32 offset:4624
	v_cvt_pk_bf16_f32 v32, v41, s0
	ds_write_b16 v64, v0 offset:13872
	v_cvt_pk_bf16_f32 v0, v11, s0
	ds_write_b16 v64, v32 offset:4688
	v_cvt_pk_bf16_f32 v32, v58, s0
	ds_write_b16 v64, v0 offset:13936
	v_cvt_pk_bf16_f32 v0, v28, s0
	ds_write_b16 v64, v32 offset:4896
	v_cvt_pk_bf16_f32 v32, v42, s0
	ds_write_b16 v64, v0 offset:15232
	v_cvt_pk_bf16_f32 v0, v12, s0
	ds_write_b16 v64, v32 offset:4960
	v_cvt_pk_bf16_f32 v32, v59, s0
	ds_write_b16 v64, v0 offset:15296
	v_cvt_pk_bf16_f32 v0, v29, s0
	ds_write_b16 v64, v32 offset:5168
	v_cvt_pk_bf16_f32 v32, v43, s0
	ds_write_b16 v64, v0 offset:15504
	v_cvt_pk_bf16_f32 v0, v13, s0
	ds_write_b16 v64, v32 offset:5232
	v_cvt_pk_bf16_f32 v32, v60, s0
	ds_write_b16 v64, v0 offset:15568
	v_cvt_pk_bf16_f32 v0, v30, s0
	ds_write_b16 v64, v32 offset:6528
	v_cvt_pk_bf16_f32 v32, v44, s0
	ds_write_b16 v64, v0 offset:15776
	v_cvt_pk_bf16_f32 v0, v14, s0
	s_mul_i32 s11, s11, 0x160000
	ds_write_b16 v64, v32 offset:6592
	v_cvt_pk_bf16_f32 v32, v61, s0
	ds_write_b16 v64, v0 offset:15840
	v_cvt_pk_bf16_f32 v0, v31, s0
	s_add_u32 s41, s13, s11
	ds_write_b16 v64, v32 offset:6800
	v_cvt_pk_bf16_f32 v32, v45, s0
	ds_write_b16 v64, v0 offset:16048
	v_cvt_pk_bf16_f32 v0, v15, s0
	s_addc_u32 s42, s14, 0
	s_ashr_i32 s11, s10, 31
	ds_write_b16 v64, v32 offset:6864
	v_cvt_pk_bf16_f32 v32, v62, s0
	ds_write_b16 v64, v0 offset:16112
	s_lshl_b64 s[10:11], s[10:11], 1
	v_lshlrev_b32_e32 v0, 4, v102
	ds_write_b16 v64, v32 offset:7072
	v_cvt_pk_bf16_f32 v32, v46, s0
	s_add_u32 s10, s41, s10
	v_and_b32_e32 v96, 0xf0, v0
	ds_write_b16 v64, v32 offset:7136
	v_cvt_pk_bf16_f32 v32, v63, s0
	s_addc_u32 s11, s42, s11
	v_add_u32_e32 v8, 32, v96
	v_ashrrev_i32_e32 v9, 4, v102
	v_add_u32_e32 v4, 0x100, v102
	v_cvt_pk_bf16_f32 v48, v48, s0
	ds_write_b16 v64, v32 offset:7344
	v_cvt_pk_bf16_f32 v32, v47, s0
	v_cvt_pk_bf16_f32 v16, v16, s0
	v_lshl_add_u64 v[10:11], s[10:11], 0, v[96:97]
	v_mad_u64_u32 v[0:1], s[10:11], v9, s36, v[8:9]
	v_ashrrev_i32_e32 v14, 4, v4
	ds_write_b16 v64, v48
	ds_write_b16 v64, v32 offset:7408
	ds_write_b16 v64, v16 offset:8704
	s_waitcnt lgkmcnt(0)
	s_barrier
	ds_read_b128 v[0:3], v0
	v_mad_u64_u32 v[4:5], s[10:11], v14, s36, v[8:9]
	ds_read_b128 v[4:7], v4
	v_mad_i64_i32 v[12:13], s[10:11], v9, s37, v[10:11]
	s_waitcnt lgkmcnt(1)
	global_store_dwordx4 v[12:13], v[0:3], off
	s_nop 1
	v_mad_i64_i32 v[0:1], s[10:11], v14, s37, v[10:11]
	s_waitcnt lgkmcnt(0)
	global_store_dwordx4 v[0:1], v[4:7], off
	v_add_u32_e32 v0, 0x200, v102
	v_ashrrev_i32_e32 v9, 4, v0
	v_add_u32_e32 v4, 0x300, v102
	v_mad_u64_u32 v[0:1], s[10:11], v9, s36, v[8:9]
	v_ashrrev_i32_e32 v14, 4, v4
	ds_read_b128 v[0:3], v0
	v_mad_u64_u32 v[4:5], s[10:11], v14, s36, v[8:9]
	ds_read_b128 v[4:7], v4
	v_mad_i64_i32 v[12:13], s[10:11], v9, s37, v[10:11]
	s_waitcnt lgkmcnt(1)
	global_store_dwordx4 v[12:13], v[0:3], off
	s_nop 1
	v_mad_i64_i32 v[0:1], s[10:11], v14, s37, v[10:11]
	s_waitcnt lgkmcnt(0)
	global_store_dwordx4 v[0:1], v[4:7], off
	v_add_u32_e32 v0, 0x400, v102
	v_ashrrev_i32_e32 v9, 4, v0
	v_add_u32_e32 v4, 0x500, v102
	v_mad_u64_u32 v[0:1], s[10:11], v9, s36, v[8:9]
	v_ashrrev_i32_e32 v14, 4, v4
	ds_read_b128 v[0:3], v0
	v_mad_u64_u32 v[4:5], s[10:11], v14, s36, v[8:9]
	ds_read_b128 v[4:7], v4
	v_mad_i64_i32 v[12:13], s[10:11], v9, s37, v[10:11]
	s_waitcnt lgkmcnt(1)
	global_store_dwordx4 v[12:13], v[0:3], off
	s_nop 1
	v_mad_i64_i32 v[0:1], s[10:11], v14, s37, v[10:11]
	s_waitcnt lgkmcnt(0)
	global_store_dwordx4 v[0:1], v[4:7], off
	v_add_u32_e32 v0, 0x600, v102
	v_ashrrev_i32_e32 v9, 4, v0
	v_add_u32_e32 v4, 0x700, v102
	v_mad_u64_u32 v[0:1], s[10:11], v9, s36, v[8:9]
	v_ashrrev_i32_e32 v12, 4, v4
	ds_read_b128 v[0:3], v0
	v_mad_u64_u32 v[4:5], s[10:11], v12, s36, v[8:9]
	ds_read_b128 v[4:7], v4
	v_mad_i64_i32 v[8:9], s[10:11], v9, s37, v[10:11]
	s_waitcnt lgkmcnt(1)
	global_store_dwordx4 v[8:9], v[0:3], off
	s_nop 1
	v_mad_i64_i32 v[0:1], s[10:11], v12, s37, v[10:11]
	s_waitcnt lgkmcnt(0)
	global_store_dwordx4 v[0:1], v[4:7], off
	s_branch .LBB0_3926

.LBB0_4051:
	s_setprio 1
	ds_read_b128 v[146:149], v109
	ds_read_b128 v[150:153], v110 offset:36864
	ds_read_b128 v[154:157], v109 offset:32
	ds_read_b128 v[192:195], v110 offset:36896
	ds_read_b128 v[196:199], v110 offset:41472
	ds_read_b128 v[200:203], v109 offset:4608
	s_waitcnt lgkmcnt(4)
	v_mfma_f32_32x32x16_bf16 v[48:63], v[146:149], v[150:153], v[48:63]
	ds_read_b128 v[204:207], v110 offset:41504
	global_load_dwordx4 v[114:117], v174, s[98:99] offset:3840
	global_load_dwordx4 v[118:121], v176, s[98:99] offset:3840
	s_waitcnt vmcnt(9)
	ds_write_b128 v111, v[68:71] offset:18432
	s_waitcnt lgkmcnt(3)
	v_mfma_f32_32x32x16_bf16 v[32:47], v[146:149], v[196:199], v[32:47]
	ds_read_b128 v[208:211], v109 offset:4640
	global_load_dwordx4 v[122:125], v178, s[98:99] offset:3840
	global_load_dwordx4 v[126:129], v180, s[98:99] offset:3840
	s_waitcnt lgkmcnt(3)
	v_mfma_f32_32x32x16_bf16 v[16:31], v[200:203], v[150:153], v[16:31]
	global_load_dwordx4 v[130:133], v182, s[98:99] offset:3840
	global_load_dwordx4 v[134:137], v184, s[98:99] offset:3840
	s_waitcnt vmcnt(11)
	ds_write_b128 v111, v[84:87] offset:23040
	v_mfma_f32_32x32x16_bf16 v[0:15], v[200:203], v[196:199], v[0:15]
	ds_read_b128 v[212:215], v109 offset:64
	ds_read_b128 v[216:219], v110 offset:36928
	global_load_dwordx4 v[138:141], v186, s[98:99] offset:3840
	global_load_dwordx4 v[142:145], v188, s[98:99] offset:3840
	v_mfma_f32_32x32x16_bf16 v[48:63], v[154:157], v[192:195], v[48:63]
	ds_read_b128 v[220:223], v110 offset:41536
	s_waitcnt vmcnt(12)
	ds_write_b128 v111, v[88:91] offset:27648
	s_waitcnt lgkmcnt(7)
	v_mfma_f32_32x32x16_bf16 v[32:47], v[154:157], v[204:207], v[32:47]
	ds_read_b128 v[224:227], v109 offset:4672
	s_waitcnt lgkmcnt(6)
	v_mfma_f32_32x32x16_bf16 v[16:31], v[208:211], v[192:195], v[16:31]
	s_waitcnt vmcnt(11)
	ds_write_b128 v111, v[92:95] offset:32256
	v_mfma_f32_32x32x16_bf16 v[0:15], v[208:211], v[204:207], v[0:15]
	ds_read_b128 v[228:231], v109 offset:96
	ds_read_b128 v[146:149], v110 offset:36960
	s_waitcnt lgkmcnt(6)
	v_mfma_f32_32x32x16_bf16 v[48:63], v[212:215], v[216:219], v[48:63]
	ds_read_b128 v[150:153], v110 offset:41568
	ds_write_b128 v111, v[64:67] offset:55296
	s_waitcnt lgkmcnt(7)
	v_mfma_f32_32x32x16_bf16 v[32:47], v[212:215], v[220:223], v[32:47]
	ds_read_b128 v[196:199], v109 offset:4704
	s_waitcnt lgkmcnt(6)
	v_mfma_f32_32x32x16_bf16 v[16:31], v[224:227], v[216:219], v[16:31]
	s_waitcnt vmcnt(10)
	ds_write_b128 v111, v[72:75] offset:59904
	v_mfma_f32_32x32x16_bf16 v[0:15], v[224:227], v[220:223], v[0:15]
	s_waitcnt lgkmcnt(4)
	v_mfma_f32_32x32x16_bf16 v[48:63], v[228:231], v[146:149], v[48:63]
	s_waitcnt vmcnt(9)
	ds_write_b128 v111, v[76:79] offset:64512
	s_waitcnt lgkmcnt(4)
	v_mfma_f32_32x32x16_bf16 v[32:47], v[228:231], v[150:153], v[32:47]
	s_waitcnt lgkmcnt(2)
	v_mfma_f32_32x32x16_bf16 v[16:31], v[196:199], v[146:149], v[16:31]
	s_waitcnt vmcnt(8)
	ds_write_b128 v112, v[80:83] offset:13824
	v_mfma_f32_32x32x16_bf16 v[0:15], v[196:199], v[150:153], v[0:15]
	s_setprio 0
	s_waitcnt lgkmcnt(0)
	s_barrier
	s_setprio 1
	ds_read_b128 v[146:149], v109 offset:18432
	ds_read_b128 v[150:153], v110 offset:55296
	ds_read_b128 v[154:157], v109 offset:18464
	ds_read_b128 v[192:195], v110 offset:55328
	ds_read_b128 v[196:199], v110 offset:59904
	ds_read_b128 v[200:203], v109 offset:23040
	s_waitcnt lgkmcnt(4)
	v_mfma_f32_32x32x16_bf16 v[48:63], v[146:149], v[150:153], v[48:63]
	ds_read_b128 v[204:207], v110 offset:59936
	global_load_dwordx4 v[68:71], v174, s[98:99] offset:3968
	global_load_dwordx4 v[84:87], v176, s[98:99] offset:3968
	s_waitcnt vmcnt(9)
	ds_write_b128 v111, v[114:117]
	s_waitcnt lgkmcnt(3)
	v_mfma_f32_32x32x16_bf16 v[32:47], v[146:149], v[196:199], v[32:47]
	ds_read_b128 v[208:211], v109 offset:23072
	global_load_dwordx4 v[88:91], v178, s[98:99] offset:3968
	global_load_dwordx4 v[92:95], v180, s[98:99] offset:3968
	s_waitcnt lgkmcnt(3)
	v_mfma_f32_32x32x16_bf16 v[16:31], v[200:203], v[150:153], v[16:31]
	global_load_dwordx4 v[64:67], v182, s[98:99] offset:3968
	global_load_dwordx4 v[72:75], v184, s[98:99] offset:3968
	s_waitcnt vmcnt(12)
	ds_write_b128 v111, v[118:121] offset:4608
	v_mfma_f32_32x32x16_bf16 v[0:15], v[200:203], v[196:199], v[0:15]
	ds_read_b128 v[212:215], v109 offset:18496
	ds_read_b128 v[216:219], v110 offset:55360
	global_load_dwordx4 v[76:79], v186, s[98:99] offset:3968
	global_load_dwordx4 v[80:83], v188, s[98:99] offset:3968
	v_mfma_f32_32x32x16_bf16 v[48:63], v[154:157], v[192:195], v[48:63]
	ds_read_b128 v[220:223], v110 offset:59968
	s_add_u32 s98, s98, 0x100
	s_addc_u32 s99, s99, 0
	s_add_i32 s12, s12, 2
	s_cmp_lt_u32 s12, 39
	s_waitcnt vmcnt(13)
	ds_write_b128 v111, v[122:125] offset:9216
	s_waitcnt lgkmcnt(7)
	v_mfma_f32_32x32x16_bf16 v[32:47], v[154:157], v[204:207], v[32:47]
	ds_read_b128 v[224:227], v109 offset:23104
	s_waitcnt lgkmcnt(6)
	v_mfma_f32_32x32x16_bf16 v[16:31], v[208:211], v[192:195], v[16:31]
	s_waitcnt vmcnt(12)
	ds_write_b128 v111, v[126:129] offset:13824
	v_mfma_f32_32x32x16_bf16 v[0:15], v[208:211], v[204:207], v[0:15]
	ds_read_b128 v[228:231], v109 offset:18528
	ds_read_b128 v[146:149], v110 offset:55392
	s_waitcnt lgkmcnt(6)
	v_mfma_f32_32x32x16_bf16 v[48:63], v[212:215], v[216:219], v[48:63]
	ds_read_b128 v[150:153], v110 offset:60000
	s_waitcnt vmcnt(11)
	ds_write_b128 v111, v[130:133] offset:36864
	s_waitcnt lgkmcnt(7)
	v_mfma_f32_32x32x16_bf16 v[32:47], v[212:215], v[220:223], v[32:47]
	ds_read_b128 v[196:199], v109 offset:23136
	s_waitcnt lgkmcnt(6)
	v_mfma_f32_32x32x16_bf16 v[16:31], v[224:227], v[216:219], v[16:31]
	s_waitcnt vmcnt(10)
	ds_write_b128 v111, v[134:137] offset:41472
	v_mfma_f32_32x32x16_bf16 v[0:15], v[224:227], v[220:223], v[0:15]
	s_waitcnt lgkmcnt(4)
	v_mfma_f32_32x32x16_bf16 v[48:63], v[228:231], v[146:149], v[48:63]
	s_waitcnt vmcnt(9)
	ds_write_b128 v111, v[138:141] offset:46080
	s_waitcnt lgkmcnt(4)
	v_mfma_f32_32x32x16_bf16 v[32:47], v[228:231], v[150:153], v[32:47]
	s_waitcnt lgkmcnt(2)
	v_mfma_f32_32x32x16_bf16 v[16:31], v[196:199], v[146:149], v[16:31]
	s_waitcnt vmcnt(8)
	ds_write_b128 v111, v[142:145] offset:50688
	v_mfma_f32_32x32x16_bf16 v[0:15], v[196:199], v[150:153], v[0:15]
	s_setprio 0
	s_waitcnt lgkmcnt(0)
	s_barrier
	s_cbranch_scc1 .LBB0_4051
	s_setprio 1
	ds_read_b128 v[104:107], v109
	ds_read_b128 v[114:117], v110 offset:36864
	ds_read_b128 v[118:121], v109 offset:32
	ds_read_b128 v[192:195], v110 offset:36896
	ds_read_b128 v[196:199], v110 offset:41472
	ds_read_b128 v[200:203], v109 offset:4608
	s_waitcnt lgkmcnt(4)
	v_mfma_f32_32x32x16_bf16 v[48:63], v[104:107], v[114:117], v[48:63]
	ds_read_b128 v[204:207], v110 offset:41504
	s_waitcnt vmcnt(7)
	ds_write_b128 v111, v[68:71] offset:18432
	s_waitcnt lgkmcnt(3)
	v_mfma_f32_32x32x16_bf16 v[32:47], v[104:107], v[196:199], v[32:47]
	ds_read_b128 v[208:211], v109 offset:4640
	s_waitcnt lgkmcnt(3)
	v_mfma_f32_32x32x16_bf16 v[16:31], v[200:203], v[114:117], v[16:31]
	s_waitcnt vmcnt(6)
	ds_write_b128 v111, v[84:87] offset:23040
	v_mfma_f32_32x32x16_bf16 v[0:15], v[200:203], v[196:199], v[0:15]
	ds_read_b128 v[212:215], v109 offset:64
	ds_read_b128 v[216:219], v110 offset:36928
	v_mfma_f32_32x32x16_bf16 v[48:63], v[118:121], v[192:195], v[48:63]
	ds_read_b128 v[220:223], v110 offset:41536
	s_waitcnt vmcnt(5)
	ds_write_b128 v111, v[88:91] offset:27648
	s_waitcnt lgkmcnt(7)
	v_mfma_f32_32x32x16_bf16 v[32:47], v[118:121], v[204:207], v[32:47]
	ds_read_b128 v[224:227], v109 offset:4672
	s_waitcnt lgkmcnt(6)
	v_mfma_f32_32x32x16_bf16 v[16:31], v[208:211], v[192:195], v[16:31]
	s_waitcnt vmcnt(4)
	ds_write_b128 v111, v[92:95] offset:32256
	v_mfma_f32_32x32x16_bf16 v[0:15], v[208:211], v[204:207], v[0:15]
	ds_read_b128 v[228:231], v109 offset:96
	ds_read_b128 v[104:107], v110 offset:41568
	s_waitcnt lgkmcnt(6)
	v_mfma_f32_32x32x16_bf16 v[48:63], v[212:215], v[216:219], v[48:63]
	ds_read_b128 v[114:117], v110 offset:36960
	ds_read_b128 v[196:199], v109 offset:4704
	s_waitcnt vmcnt(3)
	ds_write_b128 v111, v[64:67] offset:55296
	s_waitcnt lgkmcnt(8)
	v_mfma_f32_32x32x16_bf16 v[32:47], v[212:215], v[220:223], v[32:47]
	s_waitcnt lgkmcnt(6)
	v_mfma_f32_32x32x16_bf16 v[16:31], v[224:227], v[216:219], v[16:31]
	s_waitcnt vmcnt(2)
	ds_write_b128 v111, v[72:75] offset:59904
	v_mfma_f32_32x32x16_bf16 v[0:15], v[224:227], v[220:223], v[0:15]
	s_waitcnt lgkmcnt(4)
	v_mfma_f32_32x32x16_bf16 v[32:47], v[228:231], v[104:107], v[32:47]
	s_waitcnt vmcnt(1)
	ds_write_b128 v111, v[76:79] offset:64512
	s_waitcnt lgkmcnt(3)
	v_mfma_f32_32x32x16_bf16 v[16:31], v[196:199], v[114:117], v[16:31]
	v_mfma_f32_32x32x16_bf16 v[0:15], v[196:199], v[104:107], v[0:15]
	s_waitcnt vmcnt(0)
	ds_write_b128 v112, v[80:83] offset:13824
	v_mfma_f32_32x32x16_bf16 v[48:63], v[228:231], v[114:117], v[48:63]
	s_setprio 0
	s_waitcnt lgkmcnt(0)
	s_barrier
	s_setprio 1
	ds_read_b128 v[64:67], v109 offset:18432
	ds_read_b128 v[68:71], v110 offset:55296
	ds_read_b128 v[72:75], v109 offset:18464
	ds_read_b128 v[192:195], v110 offset:55328
	ds_read_b128 v[196:199], v110 offset:59904
	ds_read_b128 v[200:203], v109 offset:23040
	s_waitcnt lgkmcnt(4)
	v_mfma_f32_32x32x16_bf16 v[48:63], v[64:67], v[68:71], v[48:63]
	ds_read_b128 v[204:207], v110 offset:59936
	s_waitcnt lgkmcnt(2)
	v_mfma_f32_32x32x16_bf16 v[32:47], v[64:67], v[196:199], v[32:47]
	ds_read_b128 v[208:211], v109 offset:23072
	s_waitcnt lgkmcnt(2)
	v_mfma_f32_32x32x16_bf16 v[16:31], v[200:203], v[68:71], v[16:31]
	v_mfma_f32_32x32x16_bf16 v[0:15], v[200:203], v[196:199], v[0:15]
	ds_read_b128 v[212:215], v109 offset:18496
	ds_read_b128 v[216:219], v110 offset:55360
	v_mfma_f32_32x32x16_bf16 v[48:63], v[72:75], v[192:195], v[48:63]
	ds_read_b128 v[220:223], v110 offset:59968
	s_waitcnt lgkmcnt(4)
	v_mfma_f32_32x32x16_bf16 v[32:47], v[72:75], v[204:207], v[32:47]
	ds_read_b128 v[224:227], v109 offset:23104
	s_waitcnt lgkmcnt(4)
	v_mfma_f32_32x32x16_bf16 v[16:31], v[208:211], v[192:195], v[16:31]
	v_mfma_f32_32x32x16_bf16 v[0:15], v[208:211], v[204:207], v[0:15]
	ds_read_b128 v[228:231], v109 offset:18528
	ds_read_b128 v[64:67], v110 offset:60000
	s_waitcnt lgkmcnt(4)
	v_mfma_f32_32x32x16_bf16 v[48:63], v[212:215], v[216:219], v[48:63]
	ds_read_b128 v[68:71], v110 offset:55392
	ds_read_b128 v[196:199], v109 offset:23136
	s_waitcnt lgkmcnt(5)
	v_mfma_f32_32x32x16_bf16 v[32:47], v[212:215], v[220:223], v[32:47]
	s_waitcnt lgkmcnt(4)
	v_mfma_f32_32x32x16_bf16 v[16:31], v[224:227], v[216:219], v[16:31]
	v_mfma_f32_32x32x16_bf16 v[0:15], v[224:227], v[220:223], v[0:15]
	s_waitcnt lgkmcnt(2)
	v_mfma_f32_32x32x16_bf16 v[32:47], v[228:231], v[64:67], v[32:47]
	s_waitcnt lgkmcnt(0)
	v_mfma_f32_32x32x16_bf16 v[16:31], v[196:199], v[68:71], v[16:31]
	v_mfma_f32_32x32x16_bf16 v[0:15], v[196:199], v[64:67], v[0:15]
	v_mfma_f32_32x32x16_bf16 v[48:63], v[228:231], v[68:71], v[48:63]
	s_setprio 0
	s_addk_i32 s0, 0xf000
	s_lshr_b32 s12, s0, 10
	s_mulk_i32 s12, 0x1800
	s_add_i32 s12, s12, 0x9000
	s_and_b64 s[66:67], s[4:5], exec
	s_cselect_b32 s12, 0x7800, s12
	v_mov_b32_e32 v68, v234
	s_barrier
	s_lshl_b64 s[66:67], s[12:13], 2
	s_add_u32 s66, s30, s66
	v_and_b32_e32 v69, 0x5f, v68
	v_or_b32_e32 v64, s27, v69
	s_addc_u32 s67, s31, s67
	v_ashrrev_i32_e32 v65, 31, v64
	v_lshl_add_u64 v[64:65], v[64:65], 2, s[66:67]
	v_lshl_add_u64 v[66:67], v[64:65], 0, s[16:17]
	v_add_co_u32_e32 v64, vcc, s56, v64
	v_lshlrev_b32_e32 v69, 2, v69
	s_nop 0
	v_addc_co_u32_e32 v65, vcc, 0, v65, vcc
	global_load_dword v64, v[64:65], off
	s_nop 0
	global_load_dword v65, v[66:67], off offset:128
	v_lshrrev_b32_e32 v67, 3, v68
	v_lshrrev_b32_e32 v66, 1, v68
	v_and_b32_e32 v67, 4, v67
	v_and_or_b32 v66, v66, s47, v67
	v_mul_lo_u32 v66, v66, s57
	v_add3_u32 v66, 32, v69, v66
	v_add_u32_e32 v67, 0x400, v66
	v_add_u32_e32 v69, 0x1000, v66
	v_add_u32_e32 v70, 0x1400, v66
	v_add_u32_e32 v71, 0x2000, v66
	v_add_u32_e32 v72, 0x2400, v66
	v_add_u32_e32 v73, 0x3000, v66
	v_add_u32_e32 v74, 0x3200, v66
	v_add_u32_e32 v75, 0x3400, v66
	v_add_u32_e32 v76, 0x3600, v66
	v_add_u32_e32 v77, 0x4000, v66
	s_lshl_b32 s1, s1, 19
	s_add_u32 s12, s19, s1
	s_mov_b32 s1, s13
	s_waitcnt vmcnt(1)
	v_mul_f32_e32 v48, v48, v64
	s_waitcnt vmcnt(0)
	v_mul_f32_e32 v32, v32, v65
	v_mul_f32_e32 v16, v16, v64
	v_mul_f32_e32 v0, v0, v65
	v_mul_f32_e32 v49, v49, v64
	v_mul_f32_e32 v33, v33, v65
	v_mul_f32_e32 v50, v50, v64
	v_mul_f32_e32 v34, v34, v65
	v_mul_f32_e32 v51, v51, v64
	v_mul_f32_e32 v35, v35, v65
	v_mul_f32_e32 v52, v52, v64
	v_mul_f32_e32 v36, v36, v65
	v_mul_f32_e32 v53, v53, v64
	v_mul_f32_e32 v37, v37, v65
	v_mul_f32_e32 v54, v54, v64
	v_mul_f32_e32 v38, v38, v65
	v_mul_f32_e32 v55, v55, v64
	v_mul_f32_e32 v39, v39, v65
	v_mul_f32_e32 v56, v56, v64
	v_mul_f32_e32 v40, v40, v65
	v_mul_f32_e32 v57, v57, v64
	v_mul_f32_e32 v41, v41, v65
	v_mul_f32_e32 v58, v58, v64
	v_mul_f32_e32 v42, v42, v65
	v_mul_f32_e32 v59, v59, v64
	v_mul_f32_e32 v43, v43, v65
	v_mul_f32_e32 v60, v60, v64
	v_mul_f32_e32 v44, v44, v65
	v_mul_f32_e32 v61, v61, v64
	v_mul_f32_e32 v45, v45, v65
	v_mul_f32_e32 v62, v62, v64
	v_mul_f32_e32 v46, v46, v65
	v_mul_f32_e32 v63, v63, v64
	v_mul_f32_e32 v47, v47, v65
	ds_write2_b32 v66, v48, v32 offset1:32
	ds_write2_b32 v66, v49, v33 offset0:132 offset1:164
	ds_write2_b32 v67, v50, v34 offset0:8 offset1:40
	ds_write2_b32 v67, v51, v35 offset0:140 offset1:172
	ds_write2_b32 v69, v52, v36 offset0:32 offset1:64
	ds_write2_b32 v69, v53, v37 offset0:164 offset1:196
	ds_write2_b32 v70, v54, v38 offset0:40 offset1:72
	ds_write2_b32 v70, v55, v39 offset0:172 offset1:204
	ds_write2_b32 v71, v56, v40 offset0:64 offset1:96
	ds_write2_b32 v71, v57, v41 offset0:196 offset1:228
	ds_write2_b32 v72, v58, v42 offset0:72 offset1:104
	ds_write2_b32 v72, v59, v43 offset0:204 offset1:236
	ds_write2_b32 v73, v60, v44 offset0:96 offset1:128
	ds_write2_b32 v74, v61, v45 offset0:100 offset1:132
	ds_write2_b32 v75, v62, v46 offset0:104 offset1:136
	ds_write2_b32 v76, v63, v47 offset0:108 offset1:140
	ds_write2_b32 v77, v16, v0 offset0:128 offset1:160
	v_mul_f32_e32 v0, v17, v64
	v_mul_f32_e32 v1, v1, v65
	v_add_u32_e32 v16, 0x4400, v66
	ds_write2_b32 v16, v0, v1 offset0:4 offset1:36
	v_mul_f32_e32 v0, v18, v64
	v_mul_f32_e32 v1, v2, v65
	ds_write2_b32 v16, v0, v1 offset0:136 offset1:168
	v_mul_f32_e32 v0, v19, v64
	v_mul_f32_e32 v1, v3, v65
	v_add_u32_e32 v2, 0x4800, v66
	ds_write2_b32 v2, v0, v1 offset0:12 offset1:44
	v_mul_f32_e32 v0, v20, v64
	v_mul_f32_e32 v1, v4, v65
	v_add_u32_e32 v2, 0x5000, v66
	ds_write2_b32 v2, v0, v1 offset0:160 offset1:192
	v_mul_f32_e32 v0, v21, v64
	v_mul_f32_e32 v1, v5, v65
	v_add_u32_e32 v2, 0x5400, v66
	ds_write2_b32 v2, v0, v1 offset0:36 offset1:68
	v_mul_f32_e32 v0, v22, v64
	v_mul_f32_e32 v1, v6, v65
	ds_write2_b32 v2, v0, v1 offset0:168 offset1:200
	v_mul_f32_e32 v0, v23, v64
	v_mul_f32_e32 v1, v7, v65
	v_add_u32_e32 v2, 0x5800, v66
	ds_write2_b32 v2, v0, v1 offset0:44 offset1:76
	v_mul_f32_e32 v0, v24, v64
	v_mul_f32_e32 v1, v8, v65
	v_add_u32_e32 v2, 0x6000, v66
	ds_write2_b32 v2, v0, v1 offset0:192 offset1:224
	v_mul_f32_e32 v0, v25, v64
	v_mul_f32_e32 v1, v9, v65
	v_add_u32_e32 v2, 0x6400, v66
	ds_write2_b32 v2, v0, v1 offset0:68 offset1:100
	v_mul_f32_e32 v0, v26, v64
	v_mul_f32_e32 v1, v10, v65
	ds_write2_b32 v2, v0, v1 offset0:200 offset1:232
	v_mul_f32_e32 v0, v27, v64
	v_mul_f32_e32 v1, v11, v65
	v_add_u32_e32 v2, 0x6800, v66
	ds_write2_b32 v2, v0, v1 offset0:76 offset1:108
	v_mul_f32_e32 v0, v28, v64
	v_mul_f32_e32 v1, v12, v65
	v_add_u32_e32 v2, 0x7200, v66
	ds_write2_b32 v2, v0, v1 offset0:96 offset1:128
	v_mul_f32_e32 v0, v29, v64
	v_mul_f32_e32 v1, v13, v65
	v_add_u32_e32 v2, 0x7400, v66
	ds_write2_b32 v2, v0, v1 offset0:100 offset1:132
	v_mul_f32_e32 v0, v30, v64
	v_mul_f32_e32 v1, v14, v65
	v_add_u32_e32 v2, 0x7600, v66
	v_and_b32_e32 v12, 31, v68
	ds_write2_b32 v2, v0, v1 offset0:104 offset1:136
	v_mul_f32_e32 v0, v31, v64
	v_mul_f32_e32 v1, v15, v65
	v_add_u32_e32 v2, 0x7800, v66
	v_lshlrev_b32_e32 v8, 2, v12
	ds_write2_b32 v2, v0, v1 offset0:108 offset1:140
	v_or_b32_e32 v0, s27, v8
	v_ashrrev_i32_e32 v1, 31, v0
	v_lshlrev_b64 v[0:1], 2, v[0:1]
	v_lshl_add_u64 v[2:3], s[6:7], 0, v[0:1]
	v_lshl_add_u64 v[4:5], s[8:9], 0, v[0:1]
	s_waitcnt lgkmcnt(0)
	s_barrier
	global_load_dwordx4 v[0:3], v[2:3], off
	s_nop 0
	global_load_dwordx4 v[4:7], v[4:5], off
	v_and_b32_e32 v9, 64, v108
	v_add_u32_e32 v9, 64, v9
	v_xor_b32_e32 v10, 1, v108
	v_cmp_lt_i32_e32 vcc, v10, v9
	s_addc_u32 s27, s21, 0
	s_lshl_b64 s[0:1], s[0:1], 12
	v_cndmask_b32_e32 v10, v108, v10, vcc
	v_lshlrev_b32_e32 v32, 2, v10
	v_xor_b32_e32 v10, 2, v108
	v_cmp_lt_i32_e32 vcc, v10, v9
	s_add_u32 s63, s33, s0
	s_addc_u32 s65, s34, s1
	v_cndmask_b32_e32 v10, v108, v10, vcc
	v_lshlrev_b32_e32 v33, 2, v10
	v_xor_b32_e32 v10, 4, v108
	v_cmp_lt_i32_e32 vcc, v10, v9
	s_and_b64 s[0:1], s[4:5], exec
	v_ashrrev_i32_e32 v22, 5, v68
	v_cndmask_b32_e32 v10, v108, v10, vcc
	v_lshlrev_b32_e32 v34, 2, v10
	v_xor_b32_e32 v10, 8, v108
	s_cselect_b32 s67, s27, s65
	s_cselect_b32 s66, s12, s63
	v_cmp_lt_i32_e32 vcc, v10, v9
	s_add_i32 s12, s26, s39
	v_add_u32_e32 v16, s12, v22
	v_cndmask_b32_e32 v10, v108, v10, vcc
	s_add_i32 s12, s26, s40
	s_add_i32 s26, s26, s41
	v_lshlrev_b32_e32 v35, 2, v10
	v_xor_b32_e32 v10, 16, v108
	v_add_u32_e32 v20, s12, v22
	v_add_u32_e32 v24, s26, v22
	v_cmp_eq_u32_e64 s[0:1], 0, v12
	v_cmp_lt_i32_e32 vcc, v10, v9
	v_ashrrev_i32_e32 v23, 31, v22
	v_mul_lo_u32 v13, v22, s57
	v_lshlrev_b32_e32 v12, 4, v12
	v_add_u32_e32 v26, s25, v22
	v_ashrrev_i32_e32 v17, 31, v16
	v_ashrrev_i32_e32 v21, 31, v20
	v_ashrrev_i32_e32 v25, 31, v24
	v_cndmask_b32_e32 v9, v108, v10, vcc
	v_add_u32_e32 v8, s24, v8
	v_lshlrev_b64 v[10:11], 12, v[22:23]
	v_add3_u32 v37, v13, v12, 32
	v_lshlrev_b32_e32 v12, 1, v26
	v_lshlrev_b64 v[14:15], 12, v[16:17]
	v_lshlrev_b32_e32 v16, 1, v16
	v_lshlrev_b64 v[18:19], 12, v[20:21]
	v_lshlrev_b32_e32 v20, 1, v20
	v_lshlrev_b64 v[22:23], 12, v[24:25]
	v_lshlrev_b32_e32 v24, 1, v24
	v_ashrrev_i32_e32 v27, 31, v26
	v_lshlrev_b32_e32 v36, 2, v9
	v_ashrrev_i32_e32 v9, 31, v8
	v_ashrrev_i32_e32 v13, 31, v12
	v_ashrrev_i32_e32 v17, 31, v16
	v_ashrrev_i32_e32 v21, 31, v20
	v_ashrrev_i32_e32 v25, 31, v24
	v_lshlrev_b64 v[26:27], 12, v[26:27]
	v_lshlrev_b64 v[8:9], 2, v[8:9]
	v_lshl_add_u64 v[10:11], s[66:67], 0, v[10:11]
	v_lshl_add_u64 v[12:13], v[12:13], 2, s[30:31]
	v_lshl_add_u64 v[14:15], s[28:29], 0, v[14:15]
	v_lshl_add_u64 v[16:17], v[16:17], 2, s[30:31]
	v_lshl_add_u64 v[18:19], s[28:29], 0, v[18:19]
	v_lshl_add_u64 v[20:21], v[20:21], 2, s[30:31]
	v_lshl_add_u64 v[22:23], s[28:29], 0, v[22:23]
	v_lshl_add_u64 v[24:25], v[24:25], 2, s[30:31]
	v_lshl_add_u64 v[26:27], s[10:11], 0, v[26:27]
	s_mov_b64 s[24:25], 0
	s_branch .LBB0_4054
